# G1 qd/kd row stores widened: 4x4 in-quad transposes (DPP quad_perm, alignbit, bfi, select), 128 two-byte stores -> 32 eight-byte stores per unit; counted waits recomputed
# baseline (speedup 1.0000x reference)
.LBB0_284:
	s_mul_hi_i32 s4, s18, 0x2aaaaaab
	s_lshr_b32 s5, s4, 31
	s_load_dwordx4 s[8:11], s[14:15], 0x60
	s_add_i32 s31, s4, s5
	v_and_b32_e32 v54, 63, v108
	s_lshl_b32 s4, s31, 12
	s_add_i32 s4, s4, 0
	v_lshlrev_b32_e32 v70, 2, v54
	v_add_u32_e32 v55, s4, v70
	s_mul_i32 s4, s42, 0x6000
	s_waitcnt lgkmcnt(0)
	s_add_u32 s6, s8, s4
	s_addc_u32 s7, s9, 0
	s_mul_i32 s4, s42, 0x600
	s_add_u32 s4, s10, s4
	s_addc_u32 s5, s11, 0
	s_add_i32 s8, s31, s27
	s_mul_i32 s9, s31, -6
	s_add_i32 s30, s18, s9
	s_ashr_i32 s9, s8, 31
	s_mul_i32 s11, s8, 0xb0000
	s_mul_hi_i32 s10, s8, 0xb0000
	s_add_u32 s33, s16, s11
	s_addc_u32 s35, s17, s10
	s_mul_i32 s10, s31, 0xfffffe80
	s_add_i32 s10, s28, s10
	s_ashr_i32 s11, s10, 31
	s_lshl_b64 s[10:11], s[10:11], 1
	s_add_u32 s34, s33, s10
	v_lshlrev_b32_e32 v4, 1, v54
	s_addc_u32 s35, s35, s11
	v_lshl_add_u64 v[52:53], s[34:35], 0, v[4:5]
	s_lshl_b64 s[34:35], s[8:9], 6
	v_bfe_u32 v72, v108, 3, 3
	v_or_b32_e32 v6, s34, v72
	v_mov_b64_e32 v[2:3], s[16:17]
	s_mul_i32 s9, s31, 0xfffffd00
	v_mad_u64_u32 v[2:3], s[38:39], v6, s2, v[2:3]
	s_add_i32 s34, s29, s9
	v_mad_i32_i24 v3, s35, v243, v3
	s_ashr_i32 s35, s34, 31
	v_and_b32_e32 v6, 7, v108
	v_lshl_add_u64 v[2:3], s[34:35], 1, v[2:3]
	v_lshlrev_b32_e32 v6, 4, v6
	v_mov_b32_e32 v7, v5
	v_lshl_add_u64 v[30:31], v[2:3], 0, v[6:7]
	v_add_co_u32_e32 v6, vcc, s75, v30
	s_mulk_i32 s31, 0x180
	s_nop 0
	v_addc_co_u32_e32 v7, vcc, 0, v31, vcc
	v_add_co_u32_e32 v38, vcc, s64, v30
	v_subrev_u32_e32 v54, s31, v54
	s_nop 0
	v_addc_co_u32_e32 v39, vcc, 0, v31, vcc
	v_add_co_u32_e32 v40, vcc, s57, v30
	v_add_u32_e32 v54, s28, v54
	s_nop 0
	v_addc_co_u32_e32 v41, vcc, 0, v31, vcc
	v_add_co_u32_e32 v42, vcc, s58, v30
	v_add_u32_e32 v73, 0x20000, v55
	s_nop 0
	v_addc_co_u32_e32 v43, vcc, 0, v31, vcc
	v_add_co_u32_e32 v44, vcc, s59, v30
	v_ashrrev_i32_e32 v55, 31, v54
	s_nop 0
	v_addc_co_u32_e32 v45, vcc, 0, v31, vcc
	v_add_co_u32_e32 v46, vcc, s60, v30
	v_lshlrev_b64 v[74:75], 2, v[54:55]
	s_nop 0
	v_addc_co_u32_e32 v47, vcc, 0, v31, vcc
	v_add_co_u32_e32 v48, vcc, s97, v30
	v_lshl_add_u64 v[54:55], s[6:7], 0, v[74:75]
	s_nop 0
	v_addc_co_u32_e32 v49, vcc, 0, v31, vcc
	v_add_co_u32_e32 v50, vcc, s47, v30
	s_mov_b64 s[34:35], 0x2000
	s_nop 0
	v_addc_co_u32_e32 v51, vcc, 0, v31, vcc
	v_add_co_u32_e32 v56, vcc, s1, v54
	v_lshl_add_u64 v[2:3], v[30:31], 0, s[34:35]
	s_nop 0
	v_addc_co_u32_e32 v57, vcc, 0, v55, vcc
	global_load_dwordx4 v[34:37], v[6:7], off
	global_load_dwordx4 v[10:13], v[40:41], off
	global_load_dwordx4 v[14:17], v[42:43], off
	global_load_dwordx4 v[18:21], v[44:45], off
	global_load_dwordx4 v[22:25], v[46:47], off
	global_load_dwordx4 v[26:29], v[48:49], off
	global_load_dwordx4 v[30:33], v[50:51], off
	global_load_dwordx4 v[6:9], v[38:39], off
	global_load_dword v99, v[54:55], off
	ds_read2st64_b32 v[68:69], v73 offset1:1
	global_load_dword v130, v[54:55], off offset:1536
	global_load_dword v98, v[54:55], off offset:3072
	ds_read2st64_b32 v[66:67], v73 offset0:2 offset1:3
	global_load_dword v133, v[56:57], off offset:512
	global_load_dword v131, v[56:57], off offset:2048
	global_load_dword v132, v[56:57], off offset:3584
	v_add_co_u32_e32 v56, vcc, s75, v54
	v_lshl_add_u64 v[74:75], s[4:5], 0, v[74:75]
	s_nop 0
	v_addc_co_u32_e32 v57, vcc, 0, v55, vcc
	global_load_dword v134, v[56:57], off offset:1024
	global_load_dword v135, v[56:57], off offset:2560
	v_add_co_u32_e32 v56, vcc, s74, v54
	ds_read2st64_b32 v[64:65], v73 offset0:4 offset1:5
	ds_read2st64_b32 v[62:63], v73 offset0:6 offset1:7
	ds_read2st64_b32 v[60:61], v73 offset0:8 offset1:9
	v_addc_co_u32_e32 v57, vcc, 0, v55, vcc
	v_add_co_u32_e32 v76, vcc, s79, v54
	global_load_dword v137, v[56:57], off
	s_nop 0
	v_addc_co_u32_e32 v77, vcc, 0, v55, vcc
	global_load_dword v138, v[56:57], off offset:1536
	global_load_dword v136, v[56:57], off offset:3072
	ds_read2st64_b32 v[58:59], v73 offset0:10 offset1:11
	global_load_dword v141, v[76:77], off offset:512
	global_load_dword v139, v[76:77], off offset:2048
	global_load_dword v144, v[74:75], off
	global_load_dword v140, v[76:77], off offset:3584
	v_add_co_u32_e32 v76, vcc, s40, v54
	s_waitcnt lgkmcnt(5)
	v_readlane_b32 s4, v68, 0
	v_addc_co_u32_e32 v77, vcc, 0, v55, vcc
	global_load_dword v142, v[76:77], off offset:1024
	global_load_dword v143, v[76:77], off offset:2560
	ds_read2st64_b32 v[56:57], v73 offset0:12 offset1:13
	ds_read2st64_b32 v[54:55], v73 offset0:14 offset1:15
	s_mul_i32 s5, s8, 6
	v_and_b32_e32 v71, 15, v108
	v_lshlrev_b32_e32 v147, 1, v71
	s_waitcnt vmcnt(3)
	v_fma_f32 v73, s4, v99, v144
	v_readlane_b32 s4, v68, 1
	s_nop 1
	v_fmac_f32_e32 v73, s4, v130
	v_readlane_b32 s4, v68, 2
	s_nop 1
	v_fmac_f32_e32 v73, s4, v98
	v_readlane_b32 s4, v68, 3
	s_nop 1
	v_fmac_f32_e32 v73, s4, v133
	v_readlane_b32 s4, v68, 4
	s_nop 1
	v_fmac_f32_e32 v73, s4, v131
	v_readlane_b32 s4, v68, 5
	s_nop 1
	v_fmac_f32_e32 v73, s4, v132
	v_readlane_b32 s4, v68, 6
	s_nop 1
	v_fmac_f32_e32 v73, s4, v134
	v_readlane_b32 s4, v68, 7
	s_nop 1
	v_fmac_f32_e32 v73, s4, v135
	v_readlane_b32 s4, v68, 8
	s_nop 1
	v_fmac_f32_e32 v73, s4, v137
	v_readlane_b32 s4, v68, 9
	s_nop 1
	v_fmac_f32_e32 v73, s4, v138
	v_readlane_b32 s4, v68, 10
	s_nop 1
	v_fmac_f32_e32 v73, s4, v136
	v_readlane_b32 s4, v68, 11
	s_nop 1
	v_fmac_f32_e32 v73, s4, v141
	v_readlane_b32 s4, v68, 12
	s_nop 1
	v_fmac_f32_e32 v73, s4, v139
	v_readlane_b32 s4, v68, 13
	s_waitcnt vmcnt(2)
	s_nop 0
	v_fmac_f32_e32 v73, s4, v140
	v_readlane_b32 s4, v68, 14
	s_waitcnt vmcnt(1)
	s_nop 0
	v_fmac_f32_e32 v73, s4, v142
	v_readlane_b32 s4, v68, 15
	s_waitcnt vmcnt(0)
	s_nop 0
	v_fmac_f32_e32 v73, s4, v143
	v_min_f32_e32 v74, 0, v73
	v_mul_f32_e64 v73, |v73|, s0
	v_exp_f32_e32 v73, v73
	s_mov_b32 s4, 0x3d800000
	v_add_f32_e32 v73, 1.0, v73
	v_cmp_gt_f32_e32 vcc, s92, v73
	s_nop 1
	v_cndmask_b32_e64 v75, 0, 32, vcc
	v_ldexp_f32 v73, v73, v75
	v_log_f32_e32 v73, v73
	s_nop 0
	v_mul_f32_e32 v75, 0x3f317217, v73
	v_fma_f32 v75, v73, s3, -v75
	v_fmac_f32_e32 v75, 0x3377d1cf, v73
	v_fmac_f32_e32 v75, 0x3f317217, v73
	v_cmp_lt_f32_e64 s[6:7], |v73|, s96
	s_nop 1
	v_cndmask_b32_e64 v73, v73, v75, s[6:7]
	v_cndmask_b32_e32 v75, 0, v244, vcc
	v_sub_f32_e32 v73, v73, v75
	v_sub_f32_e32 v73, v74, v73
	v_fma_f32 v129, v73, s4, 0
	v_readlane_b32 s4, v68, 16
	s_nop 1
	v_fma_f32 v73, s4, v99, v144
	v_readlane_b32 s4, v68, 17
	s_nop 1
	v_fmac_f32_e32 v73, s4, v130
	v_readlane_b32 s4, v68, 18
	s_nop 1
	v_fmac_f32_e32 v73, s4, v98
	v_readlane_b32 s4, v68, 19
	s_nop 1
	v_fmac_f32_e32 v73, s4, v133
	v_readlane_b32 s4, v68, 20
	s_nop 1
	v_fmac_f32_e32 v73, s4, v131
	v_readlane_b32 s4, v68, 21
	s_nop 1
	v_fmac_f32_e32 v73, s4, v132
	v_readlane_b32 s4, v68, 22
	s_nop 1
	v_fmac_f32_e32 v73, s4, v134
	v_readlane_b32 s4, v68, 23
	s_nop 1
	v_fmac_f32_e32 v73, s4, v135
	v_readlane_b32 s4, v68, 24
	s_nop 1
	v_fmac_f32_e32 v73, s4, v137
	v_readlane_b32 s4, v68, 25
	s_nop 1
	v_fmac_f32_e32 v73, s4, v138
	v_readlane_b32 s4, v68, 26
	s_nop 1
	v_fmac_f32_e32 v73, s4, v136
	v_readlane_b32 s4, v68, 27
	s_nop 1
	v_fmac_f32_e32 v73, s4, v141
	v_readlane_b32 s4, v68, 28
	s_nop 1
	v_fmac_f32_e32 v73, s4, v139
	v_readlane_b32 s4, v68, 29
	s_nop 1
	v_fmac_f32_e32 v73, s4, v140
	v_readlane_b32 s4, v68, 30
	s_nop 1
	v_fmac_f32_e32 v73, s4, v142
	v_readlane_b32 s4, v68, 31
	s_nop 1
	v_fmac_f32_e32 v73, s4, v143
	v_min_f32_e32 v74, 0, v73
	v_mul_f32_e64 v73, |v73|, s0
	v_exp_f32_e32 v73, v73
	v_readlane_b32 s4, v68, 32
	v_add_f32_e32 v73, 1.0, v73
	v_cmp_gt_f32_e32 vcc, s92, v73
	s_nop 1
	v_cndmask_b32_e64 v75, 0, 32, vcc
	v_ldexp_f32 v73, v73, v75
	v_log_f32_e32 v73, v73
	s_nop 0
	v_mul_f32_e32 v75, 0x3f317217, v73
	v_fma_f32 v75, v73, s3, -v75
	v_fmac_f32_e32 v75, 0x3377d1cf, v73
	v_fmac_f32_e32 v75, 0x3f317217, v73
	v_cmp_lt_f32_e64 s[6:7], |v73|, s96
	s_nop 1
	v_cndmask_b32_e64 v73, v73, v75, s[6:7]
	v_cndmask_b32_e32 v75, 0, v244, vcc
	v_sub_f32_e32 v73, v73, v75
	v_sub_f32_e32 v73, v74, v73
	v_fmamk_f32 v113, v73, 0x3d800000, v129
	v_fma_f32 v73, s4, v99, v144
	v_readlane_b32 s4, v68, 33
	s_nop 1
	v_fmac_f32_e32 v73, s4, v130
	v_readlane_b32 s4, v68, 34
	s_nop 1
	v_fmac_f32_e32 v73, s4, v98
	v_readlane_b32 s4, v68, 35
	s_nop 1
	v_fmac_f32_e32 v73, s4, v133
	v_readlane_b32 s4, v68, 36
	s_nop 1
	v_fmac_f32_e32 v73, s4, v131
	v_readlane_b32 s4, v68, 37
	s_nop 1
	v_fmac_f32_e32 v73, s4, v132
	v_readlane_b32 s4, v68, 38
	s_nop 1
	v_fmac_f32_e32 v73, s4, v134
	v_readlane_b32 s4, v68, 39
	s_nop 1
	v_fmac_f32_e32 v73, s4, v135
	v_readlane_b32 s4, v68, 40
	s_nop 1
	v_fmac_f32_e32 v73, s4, v137
	v_readlane_b32 s4, v68, 41
	s_nop 1
	v_fmac_f32_e32 v73, s4, v138
	v_readlane_b32 s4, v68, 42
	s_nop 1
	v_fmac_f32_e32 v73, s4, v136
	v_readlane_b32 s4, v68, 43
	s_nop 1
	v_fmac_f32_e32 v73, s4, v141
	v_readlane_b32 s4, v68, 44
	s_nop 1
	v_fmac_f32_e32 v73, s4, v139
	v_readlane_b32 s4, v68, 45
	s_nop 1
	v_fmac_f32_e32 v73, s4, v140
	v_readlane_b32 s4, v68, 46
	s_nop 1
	v_fmac_f32_e32 v73, s4, v142
	v_readlane_b32 s4, v68, 47
	s_nop 1
	v_fmac_f32_e32 v73, s4, v143
	v_min_f32_e32 v74, 0, v73
	v_mul_f32_e64 v73, |v73|, s0
	v_exp_f32_e32 v73, v73
	v_readlane_b32 s4, v68, 48
	v_add_f32_e32 v73, 1.0, v73
	v_cmp_gt_f32_e32 vcc, s92, v73
	s_nop 1
	v_cndmask_b32_e64 v75, 0, 32, vcc
	v_ldexp_f32 v73, v73, v75
	v_log_f32_e32 v73, v73
	s_nop 0
	v_mul_f32_e32 v75, 0x3f317217, v73
	v_fma_f32 v75, v73, s3, -v75
	v_fmac_f32_e32 v75, 0x3377d1cf, v73
	v_fmac_f32_e32 v75, 0x3f317217, v73
	v_cmp_lt_f32_e64 s[6:7], |v73|, s96
	s_nop 1
	v_cndmask_b32_e64 v73, v73, v75, s[6:7]
	v_cndmask_b32_e32 v75, 0, v244, vcc
	v_sub_f32_e32 v73, v73, v75
	v_sub_f32_e32 v73, v74, v73
	v_fmamk_f32 v114, v73, 0x3d800000, v113
	v_fma_f32 v73, s4, v99, v144
	v_readlane_b32 s4, v68, 49
	s_nop 1
	v_fmac_f32_e32 v73, s4, v130
	v_readlane_b32 s4, v68, 50
	s_nop 1
	v_fmac_f32_e32 v73, s4, v98
	v_readlane_b32 s4, v68, 51
	s_nop 1
	v_fmac_f32_e32 v73, s4, v133
	v_readlane_b32 s4, v68, 52
	s_nop 1
	v_fmac_f32_e32 v73, s4, v131
	v_readlane_b32 s4, v68, 53
	s_nop 1
	v_fmac_f32_e32 v73, s4, v132
	v_readlane_b32 s4, v68, 54
	s_nop 1
	v_fmac_f32_e32 v73, s4, v134
	v_readlane_b32 s4, v68, 55
	s_nop 1
	v_fmac_f32_e32 v73, s4, v135
	v_readlane_b32 s4, v68, 56
	s_nop 1
	v_fmac_f32_e32 v73, s4, v137
	v_readlane_b32 s4, v68, 57
	s_nop 1
	v_fmac_f32_e32 v73, s4, v138
	v_readlane_b32 s4, v68, 58
	s_nop 1
	v_fmac_f32_e32 v73, s4, v136
	v_readlane_b32 s4, v68, 59
	s_nop 1
	v_fmac_f32_e32 v73, s4, v141
	v_readlane_b32 s4, v68, 60
	s_nop 1
	v_fmac_f32_e32 v73, s4, v139
	v_readlane_b32 s4, v68, 61
	s_nop 1
	v_fmac_f32_e32 v73, s4, v140
	v_readlane_b32 s4, v68, 62
	s_nop 1
	v_fmac_f32_e32 v73, s4, v142
	v_readlane_b32 s4, v68, 63
	s_nop 1
	v_fmac_f32_e32 v73, s4, v143
	v_min_f32_e32 v68, 0, v73
	v_mul_f32_e64 v73, |v73|, s0
	v_exp_f32_e32 v73, v73
	v_readlane_b32 s4, v69, 0
	v_add_f32_e32 v73, 1.0, v73
	v_cmp_gt_f32_e32 vcc, s92, v73
	s_nop 1
	v_cndmask_b32_e64 v74, 0, 32, vcc
	v_ldexp_f32 v73, v73, v74
	v_log_f32_e32 v73, v73
	s_nop 0
	v_mul_f32_e32 v74, 0x3f317217, v73
	v_fma_f32 v74, v73, s3, -v74
	v_fmac_f32_e32 v74, 0x3377d1cf, v73
	v_fmac_f32_e32 v74, 0x3f317217, v73
	v_cmp_lt_f32_e64 s[6:7], |v73|, s96
	s_nop 1
	v_cndmask_b32_e64 v73, v73, v74, s[6:7]
	v_cndmask_b32_e32 v74, 0, v244, vcc
	v_sub_f32_e32 v73, v73, v74
	v_sub_f32_e32 v68, v68, v73
	v_fmamk_f32 v115, v68, 0x3d800000, v114
	v_fma_f32 v68, s4, v99, v144
	v_readlane_b32 s4, v69, 1
	s_nop 1
	v_fmac_f32_e32 v68, s4, v130
	v_readlane_b32 s4, v69, 2
	s_nop 1
	v_fmac_f32_e32 v68, s4, v98
	v_readlane_b32 s4, v69, 3
	s_nop 1
	v_fmac_f32_e32 v68, s4, v133
	v_readlane_b32 s4, v69, 4
	s_nop 1
	v_fmac_f32_e32 v68, s4, v131
	v_readlane_b32 s4, v69, 5
	s_nop 1
	v_fmac_f32_e32 v68, s4, v132
	v_readlane_b32 s4, v69, 6
	s_nop 1
	v_fmac_f32_e32 v68, s4, v134
	v_readlane_b32 s4, v69, 7
	s_nop 1
	v_fmac_f32_e32 v68, s4, v135
	v_readlane_b32 s4, v69, 8
	s_nop 1
	v_fmac_f32_e32 v68, s4, v137
	v_readlane_b32 s4, v69, 9
	s_nop 1
	v_fmac_f32_e32 v68, s4, v138
	v_readlane_b32 s4, v69, 10
	s_nop 1
	v_fmac_f32_e32 v68, s4, v136
	v_readlane_b32 s4, v69, 11
	s_nop 1
	v_fmac_f32_e32 v68, s4, v141
	v_readlane_b32 s4, v69, 12
	s_nop 1
	v_fmac_f32_e32 v68, s4, v139
	v_readlane_b32 s4, v69, 13
	s_nop 1
	v_fmac_f32_e32 v68, s4, v140
	v_readlane_b32 s4, v69, 14
	s_nop 1
	v_fmac_f32_e32 v68, s4, v142
	v_readlane_b32 s4, v69, 15
	s_nop 1
	v_fmac_f32_e32 v68, s4, v143
	v_min_f32_e32 v73, 0, v68
	v_mul_f32_e64 v68, |v68|, s0
	v_exp_f32_e32 v68, v68
	v_readlane_b32 s4, v69, 16
	v_add_f32_e32 v68, 1.0, v68
	v_cmp_gt_f32_e32 vcc, s92, v68
	s_nop 1
	v_cndmask_b32_e64 v74, 0, 32, vcc
	v_ldexp_f32 v68, v68, v74
	v_log_f32_e32 v68, v68
	s_nop 0
	v_mul_f32_e32 v74, 0x3f317217, v68
	v_fma_f32 v74, v68, s3, -v74
	v_fmac_f32_e32 v74, 0x3377d1cf, v68
	v_fmac_f32_e32 v74, 0x3f317217, v68
	v_cmp_lt_f32_e64 s[6:7], |v68|, s96
	s_nop 1
	v_cndmask_b32_e64 v68, v68, v74, s[6:7]
	v_cndmask_b32_e32 v74, 0, v244, vcc
	v_sub_f32_e32 v68, v68, v74
	v_sub_f32_e32 v68, v73, v68
	v_fmamk_f32 v116, v68, 0x3d800000, v115
	v_fma_f32 v68, s4, v99, v144
	v_readlane_b32 s4, v69, 17
	s_nop 1
	v_fmac_f32_e32 v68, s4, v130
	v_readlane_b32 s4, v69, 18
	s_nop 1
	v_fmac_f32_e32 v68, s4, v98
	v_readlane_b32 s4, v69, 19
	s_nop 1
	v_fmac_f32_e32 v68, s4, v133
	v_readlane_b32 s4, v69, 20
	s_nop 1
	v_fmac_f32_e32 v68, s4, v131
	v_readlane_b32 s4, v69, 21
	s_nop 1
	v_fmac_f32_e32 v68, s4, v132
	v_readlane_b32 s4, v69, 22
	s_nop 1
	v_fmac_f32_e32 v68, s4, v134
	v_readlane_b32 s4, v69, 23
	s_nop 1
	v_fmac_f32_e32 v68, s4, v135
	v_readlane_b32 s4, v69, 24
	s_nop 1
	v_fmac_f32_e32 v68, s4, v137
	v_readlane_b32 s4, v69, 25
	s_nop 1
	v_fmac_f32_e32 v68, s4, v138
	v_readlane_b32 s4, v69, 26
	s_nop 1
	v_fmac_f32_e32 v68, s4, v136
	v_readlane_b32 s4, v69, 27
	s_nop 1
	v_fmac_f32_e32 v68, s4, v141
	v_readlane_b32 s4, v69, 28
	s_nop 1
	v_fmac_f32_e32 v68, s4, v139
	v_readlane_b32 s4, v69, 29
	s_nop 1
	v_fmac_f32_e32 v68, s4, v140
	v_readlane_b32 s4, v69, 30
	s_nop 1
	v_fmac_f32_e32 v68, s4, v142
	v_readlane_b32 s4, v69, 31
	s_nop 1
	v_fmac_f32_e32 v68, s4, v143
	v_min_f32_e32 v73, 0, v68
	v_mul_f32_e64 v68, |v68|, s0
	v_exp_f32_e32 v68, v68
	v_readlane_b32 s4, v69, 32
	v_add_f32_e32 v68, 1.0, v68
	v_cmp_gt_f32_e32 vcc, s92, v68
	s_nop 1
	v_cndmask_b32_e64 v74, 0, 32, vcc
	v_ldexp_f32 v68, v68, v74
	v_log_f32_e32 v68, v68
	s_nop 0
	v_mul_f32_e32 v74, 0x3f317217, v68
	v_fma_f32 v74, v68, s3, -v74
	v_fmac_f32_e32 v74, 0x3377d1cf, v68
	v_fmac_f32_e32 v74, 0x3f317217, v68
	v_cmp_lt_f32_e64 s[6:7], |v68|, s96
	s_nop 1
	v_cndmask_b32_e64 v68, v68, v74, s[6:7]
	v_cndmask_b32_e32 v74, 0, v244, vcc
	v_sub_f32_e32 v68, v68, v74
	v_sub_f32_e32 v68, v73, v68
	v_fmamk_f32 v117, v68, 0x3d800000, v116
	v_fma_f32 v68, s4, v99, v144
	v_readlane_b32 s4, v69, 33
	s_nop 1
	v_fmac_f32_e32 v68, s4, v130
	v_readlane_b32 s4, v69, 34
	s_nop 1
	v_fmac_f32_e32 v68, s4, v98
	v_readlane_b32 s4, v69, 35
	s_nop 1
	v_fmac_f32_e32 v68, s4, v133
	v_readlane_b32 s4, v69, 36
	s_nop 1
	v_fmac_f32_e32 v68, s4, v131
	v_readlane_b32 s4, v69, 37
	s_nop 1
	v_fmac_f32_e32 v68, s4, v132
	v_readlane_b32 s4, v69, 38
	s_nop 1
	v_fmac_f32_e32 v68, s4, v134
	v_readlane_b32 s4, v69, 39
	s_nop 1
	v_fmac_f32_e32 v68, s4, v135
	v_readlane_b32 s4, v69, 40
	s_nop 1
	v_fmac_f32_e32 v68, s4, v137
	v_readlane_b32 s4, v69, 41
	s_nop 1
	v_fmac_f32_e32 v68, s4, v138
	v_readlane_b32 s4, v69, 42
	s_nop 1
	v_fmac_f32_e32 v68, s4, v136
	v_readlane_b32 s4, v69, 43
	s_nop 1
	v_fmac_f32_e32 v68, s4, v141
	v_readlane_b32 s4, v69, 44
	s_nop 1
	v_fmac_f32_e32 v68, s4, v139
	v_readlane_b32 s4, v69, 45
	s_nop 1
	v_fmac_f32_e32 v68, s4, v140
	v_readlane_b32 s4, v69, 46
	s_nop 1
	v_fmac_f32_e32 v68, s4, v142
	v_readlane_b32 s4, v69, 47
	s_nop 1
	v_fmac_f32_e32 v68, s4, v143
	v_min_f32_e32 v73, 0, v68
	v_mul_f32_e64 v68, |v68|, s0
	v_exp_f32_e32 v68, v68
	v_readlane_b32 s4, v69, 48
	v_add_f32_e32 v68, 1.0, v68
	v_cmp_gt_f32_e32 vcc, s92, v68
	s_nop 1
	v_cndmask_b32_e64 v74, 0, 32, vcc
	v_ldexp_f32 v68, v68, v74
	v_log_f32_e32 v68, v68
	s_nop 0
	v_mul_f32_e32 v74, 0x3f317217, v68
	v_fma_f32 v74, v68, s3, -v74
	v_fmac_f32_e32 v74, 0x3377d1cf, v68
	v_fmac_f32_e32 v74, 0x3f317217, v68
	v_cmp_lt_f32_e64 s[6:7], |v68|, s96
	s_nop 1
	v_cndmask_b32_e64 v68, v68, v74, s[6:7]
	v_cndmask_b32_e32 v74, 0, v244, vcc
	v_sub_f32_e32 v68, v68, v74
	v_sub_f32_e32 v68, v73, v68
	v_fmamk_f32 v118, v68, 0x3d800000, v117
	v_fma_f32 v68, s4, v99, v144
	v_readlane_b32 s4, v69, 49
	s_nop 1
	v_fmac_f32_e32 v68, s4, v130
	v_readlane_b32 s4, v69, 50
	s_nop 1
	v_fmac_f32_e32 v68, s4, v98
	v_readlane_b32 s4, v69, 51
	s_nop 1
	v_fmac_f32_e32 v68, s4, v133
	v_readlane_b32 s4, v69, 52
	s_nop 1
	v_fmac_f32_e32 v68, s4, v131
	v_readlane_b32 s4, v69, 53
	s_nop 1
	v_fmac_f32_e32 v68, s4, v132
	v_readlane_b32 s4, v69, 54
	s_nop 1
	v_fmac_f32_e32 v68, s4, v134
	v_readlane_b32 s4, v69, 55
	s_nop 1
	v_fmac_f32_e32 v68, s4, v135
	v_readlane_b32 s4, v69, 56
	s_nop 1
	v_fmac_f32_e32 v68, s4, v137
	v_readlane_b32 s4, v69, 57
	s_nop 1
	v_fmac_f32_e32 v68, s4, v138
	v_readlane_b32 s4, v69, 58
	s_nop 1
	v_fmac_f32_e32 v68, s4, v136
	v_readlane_b32 s4, v69, 59
	s_nop 1
	v_fmac_f32_e32 v68, s4, v141
	v_readlane_b32 s4, v69, 60
	s_nop 1
	v_fmac_f32_e32 v68, s4, v139
	v_readlane_b32 s4, v69, 61
	s_nop 1
	v_fmac_f32_e32 v68, s4, v140
	v_readlane_b32 s4, v69, 62
	s_nop 1
	v_fmac_f32_e32 v68, s4, v142
	v_readlane_b32 s4, v69, 63
	s_nop 1
	v_fmac_f32_e32 v68, s4, v143
	v_min_f32_e32 v69, 0, v68
	v_mul_f32_e64 v68, |v68|, s0
	v_exp_f32_e32 v68, v68
	s_waitcnt lgkmcnt(6)
	v_readlane_b32 s4, v66, 0
	v_add_f32_e32 v68, 1.0, v68
	v_cmp_gt_f32_e32 vcc, s92, v68
	s_nop 1
	v_cndmask_b32_e64 v73, 0, 32, vcc
	v_ldexp_f32 v68, v68, v73
	v_log_f32_e32 v68, v68
	s_nop 0
	v_mul_f32_e32 v73, 0x3f317217, v68
	v_fma_f32 v73, v68, s3, -v73
	v_fmac_f32_e32 v73, 0x3377d1cf, v68
	v_fmac_f32_e32 v73, 0x3f317217, v68
	v_cmp_lt_f32_e64 s[6:7], |v68|, s96
	s_nop 1
	v_cndmask_b32_e64 v68, v68, v73, s[6:7]
	v_cndmask_b32_e32 v73, 0, v244, vcc
	v_sub_f32_e32 v68, v68, v73
	v_sub_f32_e32 v68, v69, v68
	v_fmamk_f32 v119, v68, 0x3d800000, v118
	v_fma_f32 v68, s4, v99, v144
	v_readlane_b32 s4, v66, 1
	s_nop 1
	v_fmac_f32_e32 v68, s4, v130
	v_readlane_b32 s4, v66, 2
	s_nop 1
	v_fmac_f32_e32 v68, s4, v98
	v_readlane_b32 s4, v66, 3
	s_nop 1
	v_fmac_f32_e32 v68, s4, v133
	v_readlane_b32 s4, v66, 4
	s_nop 1
	v_fmac_f32_e32 v68, s4, v131
	v_readlane_b32 s4, v66, 5
	s_nop 1
	v_fmac_f32_e32 v68, s4, v132
	v_readlane_b32 s4, v66, 6
	s_nop 1
	v_fmac_f32_e32 v68, s4, v134
	v_readlane_b32 s4, v66, 7
	s_nop 1
	v_fmac_f32_e32 v68, s4, v135
	v_readlane_b32 s4, v66, 8
	s_nop 1
	v_fmac_f32_e32 v68, s4, v137
	v_readlane_b32 s4, v66, 9
	s_nop 1
	v_fmac_f32_e32 v68, s4, v138
	v_readlane_b32 s4, v66, 10
	s_nop 1
	v_fmac_f32_e32 v68, s4, v136
	v_readlane_b32 s4, v66, 11
	s_nop 1
	v_fmac_f32_e32 v68, s4, v141
	v_readlane_b32 s4, v66, 12
	s_nop 1
	v_fmac_f32_e32 v68, s4, v139
	v_readlane_b32 s4, v66, 13
	s_nop 1
	v_fmac_f32_e32 v68, s4, v140
	v_readlane_b32 s4, v66, 14
	s_nop 1
	v_fmac_f32_e32 v68, s4, v142
	v_readlane_b32 s4, v66, 15
	s_nop 1
	v_fmac_f32_e32 v68, s4, v143
	v_min_f32_e32 v69, 0, v68
	v_mul_f32_e64 v68, |v68|, s0
	v_exp_f32_e32 v68, v68
	v_readlane_b32 s4, v66, 16
	v_add_f32_e32 v68, 1.0, v68
	v_cmp_gt_f32_e32 vcc, s92, v68
	s_nop 1
	v_cndmask_b32_e64 v73, 0, 32, vcc
	v_ldexp_f32 v68, v68, v73
	v_log_f32_e32 v68, v68
	s_nop 0
	v_mul_f32_e32 v73, 0x3f317217, v68
	v_fma_f32 v73, v68, s3, -v73
	v_fmac_f32_e32 v73, 0x3377d1cf, v68
	v_fmac_f32_e32 v73, 0x3f317217, v68
	v_cmp_lt_f32_e64 s[6:7], |v68|, s96
	s_nop 1
	v_cndmask_b32_e64 v68, v68, v73, s[6:7]
	v_cndmask_b32_e32 v73, 0, v244, vcc
	v_sub_f32_e32 v68, v68, v73
	v_sub_f32_e32 v68, v69, v68
	v_fmamk_f32 v120, v68, 0x3d800000, v119
	v_fma_f32 v68, s4, v99, v144
	v_readlane_b32 s4, v66, 17
	s_nop 1
	v_fmac_f32_e32 v68, s4, v130
	v_readlane_b32 s4, v66, 18
	s_nop 1
	v_fmac_f32_e32 v68, s4, v98
	v_readlane_b32 s4, v66, 19
	s_nop 1
	v_fmac_f32_e32 v68, s4, v133
	v_readlane_b32 s4, v66, 20
	s_nop 1
	v_fmac_f32_e32 v68, s4, v131
	v_readlane_b32 s4, v66, 21
	s_nop 1
	v_fmac_f32_e32 v68, s4, v132
	v_readlane_b32 s4, v66, 22
	s_nop 1
	v_fmac_f32_e32 v68, s4, v134
	v_readlane_b32 s4, v66, 23
	s_nop 1
	v_fmac_f32_e32 v68, s4, v135
	v_readlane_b32 s4, v66, 24
	s_nop 1
	v_fmac_f32_e32 v68, s4, v137
	v_readlane_b32 s4, v66, 25
	s_nop 1
	v_fmac_f32_e32 v68, s4, v138
	v_readlane_b32 s4, v66, 26
	s_nop 1
	v_fmac_f32_e32 v68, s4, v136
	v_readlane_b32 s4, v66, 27
	s_nop 1
	v_fmac_f32_e32 v68, s4, v141
	v_readlane_b32 s4, v66, 28
	s_nop 1
	v_fmac_f32_e32 v68, s4, v139
	v_readlane_b32 s4, v66, 29
	s_nop 1
	v_fmac_f32_e32 v68, s4, v140
	v_readlane_b32 s4, v66, 30
	s_nop 1
	v_fmac_f32_e32 v68, s4, v142
	v_readlane_b32 s4, v66, 31
	s_nop 1
	v_fmac_f32_e32 v68, s4, v143
	v_min_f32_e32 v69, 0, v68
	v_mul_f32_e64 v68, |v68|, s0
	v_exp_f32_e32 v68, v68
	v_readlane_b32 s4, v66, 32
	v_add_f32_e32 v68, 1.0, v68
	v_cmp_gt_f32_e32 vcc, s92, v68
	s_nop 1
	v_cndmask_b32_e64 v73, 0, 32, vcc
	v_ldexp_f32 v68, v68, v73
	v_log_f32_e32 v68, v68
	s_nop 0
	v_mul_f32_e32 v73, 0x3f317217, v68
	v_fma_f32 v73, v68, s3, -v73
	v_fmac_f32_e32 v73, 0x3377d1cf, v68
	v_fmac_f32_e32 v73, 0x3f317217, v68
	v_cmp_lt_f32_e64 s[6:7], |v68|, s96
	s_nop 1
	v_cndmask_b32_e64 v68, v68, v73, s[6:7]
	v_cndmask_b32_e32 v73, 0, v244, vcc
	v_sub_f32_e32 v68, v68, v73
	v_sub_f32_e32 v68, v69, v68
	v_fmamk_f32 v121, v68, 0x3d800000, v120
	v_fma_f32 v68, s4, v99, v144
	v_readlane_b32 s4, v66, 33
	s_nop 1
	v_fmac_f32_e32 v68, s4, v130
	v_readlane_b32 s4, v66, 34
	s_nop 1
	v_fmac_f32_e32 v68, s4, v98
	v_readlane_b32 s4, v66, 35
	s_nop 1
	v_fmac_f32_e32 v68, s4, v133
	v_readlane_b32 s4, v66, 36
	s_nop 1
	v_fmac_f32_e32 v68, s4, v131
	v_readlane_b32 s4, v66, 37
	s_nop 1
	v_fmac_f32_e32 v68, s4, v132
	v_readlane_b32 s4, v66, 38
	s_nop 1
	v_fmac_f32_e32 v68, s4, v134
	v_readlane_b32 s4, v66, 39
	s_nop 1
	v_fmac_f32_e32 v68, s4, v135
	v_readlane_b32 s4, v66, 40
	s_nop 1
	v_fmac_f32_e32 v68, s4, v137
	v_readlane_b32 s4, v66, 41
	s_nop 1
	v_fmac_f32_e32 v68, s4, v138
	v_readlane_b32 s4, v66, 42
	s_nop 1
	v_fmac_f32_e32 v68, s4, v136
	v_readlane_b32 s4, v66, 43
	s_nop 1
	v_fmac_f32_e32 v68, s4, v141
	v_readlane_b32 s4, v66, 44
	s_nop 1
	v_fmac_f32_e32 v68, s4, v139
	v_readlane_b32 s4, v66, 45
	s_nop 1
	v_fmac_f32_e32 v68, s4, v140
	v_readlane_b32 s4, v66, 46
	s_nop 1
	v_fmac_f32_e32 v68, s4, v142
	v_readlane_b32 s4, v66, 47
	s_nop 1
	v_fmac_f32_e32 v68, s4, v143
	v_min_f32_e32 v69, 0, v68
	v_mul_f32_e64 v68, |v68|, s0
	v_exp_f32_e32 v68, v68
	v_readlane_b32 s4, v66, 48
	v_add_f32_e32 v68, 1.0, v68
	v_cmp_gt_f32_e32 vcc, s92, v68
	s_nop 1
	v_cndmask_b32_e64 v73, 0, 32, vcc
	v_ldexp_f32 v68, v68, v73
	v_log_f32_e32 v68, v68
	s_nop 0
	v_mul_f32_e32 v73, 0x3f317217, v68
	v_fma_f32 v73, v68, s3, -v73
	v_fmac_f32_e32 v73, 0x3377d1cf, v68
	v_fmac_f32_e32 v73, 0x3f317217, v68
	v_cmp_lt_f32_e64 s[6:7], |v68|, s96
	s_nop 1
	v_cndmask_b32_e64 v68, v68, v73, s[6:7]
	v_cndmask_b32_e32 v73, 0, v244, vcc
	v_sub_f32_e32 v68, v68, v73
	v_sub_f32_e32 v68, v69, v68
	v_fmamk_f32 v122, v68, 0x3d800000, v121
	v_fma_f32 v68, s4, v99, v144
	v_readlane_b32 s4, v66, 49
	s_nop 1
	v_fmac_f32_e32 v68, s4, v130
	v_readlane_b32 s4, v66, 50
	s_nop 1
	v_fmac_f32_e32 v68, s4, v98
	v_readlane_b32 s4, v66, 51
	s_nop 1
	v_fmac_f32_e32 v68, s4, v133
	v_readlane_b32 s4, v66, 52
	s_nop 1
	v_fmac_f32_e32 v68, s4, v131
	v_readlane_b32 s4, v66, 53
	s_nop 1
	v_fmac_f32_e32 v68, s4, v132
	v_readlane_b32 s4, v66, 54
	s_nop 1
	v_fmac_f32_e32 v68, s4, v134
	v_readlane_b32 s4, v66, 55
	s_nop 1
	v_fmac_f32_e32 v68, s4, v135
	v_readlane_b32 s4, v66, 56
	s_nop 1
	v_fmac_f32_e32 v68, s4, v137
	v_readlane_b32 s4, v66, 57
	s_nop 1
	v_fmac_f32_e32 v68, s4, v138
	v_readlane_b32 s4, v66, 58
	s_nop 1
	v_fmac_f32_e32 v68, s4, v136
	v_readlane_b32 s4, v66, 59
	s_nop 1
	v_fmac_f32_e32 v68, s4, v141
	v_readlane_b32 s4, v66, 60
	s_nop 1
	v_fmac_f32_e32 v68, s4, v139
	v_readlane_b32 s4, v66, 61
	s_nop 1
	v_fmac_f32_e32 v68, s4, v140
	v_readlane_b32 s4, v66, 62
	s_nop 1
	v_fmac_f32_e32 v68, s4, v142
	v_readlane_b32 s4, v66, 63
	s_nop 1
	v_fmac_f32_e32 v68, s4, v143
	v_min_f32_e32 v66, 0, v68
	v_mul_f32_e64 v68, |v68|, s0
	v_exp_f32_e32 v68, v68
	v_readlane_b32 s4, v67, 0
	v_add_f32_e32 v68, 1.0, v68
	v_cmp_gt_f32_e32 vcc, s92, v68
	s_nop 1
	v_cndmask_b32_e64 v69, 0, 32, vcc
	v_ldexp_f32 v68, v68, v69
	v_log_f32_e32 v68, v68
	s_nop 0
	v_mul_f32_e32 v69, 0x3f317217, v68
	v_fma_f32 v69, v68, s3, -v69
	v_fmac_f32_e32 v69, 0x3377d1cf, v68
	v_fmac_f32_e32 v69, 0x3f317217, v68
	v_cmp_lt_f32_e64 s[6:7], |v68|, s96
	s_nop 1
	v_cndmask_b32_e64 v68, v68, v69, s[6:7]
	v_cndmask_b32_e32 v69, 0, v244, vcc
	v_sub_f32_e32 v68, v68, v69
	v_sub_f32_e32 v66, v66, v68
	v_fmamk_f32 v123, v66, 0x3d800000, v122
	v_fma_f32 v66, s4, v99, v144
	v_readlane_b32 s4, v67, 1
	s_nop 1
	v_fmac_f32_e32 v66, s4, v130
	v_readlane_b32 s4, v67, 2
	s_nop 1
	v_fmac_f32_e32 v66, s4, v98
	v_readlane_b32 s4, v67, 3
	s_nop 1
	v_fmac_f32_e32 v66, s4, v133
	v_readlane_b32 s4, v67, 4
	s_nop 1
	v_fmac_f32_e32 v66, s4, v131
	v_readlane_b32 s4, v67, 5
	s_nop 1
	v_fmac_f32_e32 v66, s4, v132
	v_readlane_b32 s4, v67, 6
	s_nop 1
	v_fmac_f32_e32 v66, s4, v134
	v_readlane_b32 s4, v67, 7
	s_nop 1
	v_fmac_f32_e32 v66, s4, v135
	v_readlane_b32 s4, v67, 8
	s_nop 1
	v_fmac_f32_e32 v66, s4, v137
	v_readlane_b32 s4, v67, 9
	s_nop 1
	v_fmac_f32_e32 v66, s4, v138
	v_readlane_b32 s4, v67, 10
	s_nop 1
	v_fmac_f32_e32 v66, s4, v136
	v_readlane_b32 s4, v67, 11
	s_nop 1
	v_fmac_f32_e32 v66, s4, v141
	v_readlane_b32 s4, v67, 12
	s_nop 1
	v_fmac_f32_e32 v66, s4, v139
	v_readlane_b32 s4, v67, 13
	s_nop 1
	v_fmac_f32_e32 v66, s4, v140
	v_readlane_b32 s4, v67, 14
	s_nop 1
	v_fmac_f32_e32 v66, s4, v142
	v_readlane_b32 s4, v67, 15
	s_nop 1
	v_fmac_f32_e32 v66, s4, v143
	v_min_f32_e32 v68, 0, v66
	v_mul_f32_e64 v66, |v66|, s0
	v_exp_f32_e32 v66, v66
	v_readlane_b32 s4, v67, 16
	v_add_f32_e32 v66, 1.0, v66
	v_cmp_gt_f32_e32 vcc, s92, v66
	s_nop 1
	v_cndmask_b32_e64 v69, 0, 32, vcc
	v_ldexp_f32 v66, v66, v69
	v_log_f32_e32 v66, v66
	s_nop 0
	v_mul_f32_e32 v69, 0x3f317217, v66
	v_fma_f32 v69, v66, s3, -v69
	v_fmac_f32_e32 v69, 0x3377d1cf, v66
	v_fmac_f32_e32 v69, 0x3f317217, v66
	v_cmp_lt_f32_e64 s[6:7], |v66|, s96
	s_nop 1
	v_cndmask_b32_e64 v66, v66, v69, s[6:7]
	v_cndmask_b32_e32 v69, 0, v244, vcc
	v_sub_f32_e32 v66, v66, v69
	v_sub_f32_e32 v66, v68, v66
	v_fmamk_f32 v124, v66, 0x3d800000, v123
	v_fma_f32 v66, s4, v99, v144
	v_readlane_b32 s4, v67, 17
	s_nop 1
	v_fmac_f32_e32 v66, s4, v130
	v_readlane_b32 s4, v67, 18
	s_nop 1
	v_fmac_f32_e32 v66, s4, v98
	v_readlane_b32 s4, v67, 19
	s_nop 1
	v_fmac_f32_e32 v66, s4, v133
	v_readlane_b32 s4, v67, 20
	s_nop 1
	v_fmac_f32_e32 v66, s4, v131
	v_readlane_b32 s4, v67, 21
	s_nop 1
	v_fmac_f32_e32 v66, s4, v132
	v_readlane_b32 s4, v67, 22
	s_nop 1
	v_fmac_f32_e32 v66, s4, v134
	v_readlane_b32 s4, v67, 23
	s_nop 1
	v_fmac_f32_e32 v66, s4, v135
	v_readlane_b32 s4, v67, 24
	s_nop 1
	v_fmac_f32_e32 v66, s4, v137
	v_readlane_b32 s4, v67, 25
	s_nop 1
	v_fmac_f32_e32 v66, s4, v138
	v_readlane_b32 s4, v67, 26
	s_nop 1
	v_fmac_f32_e32 v66, s4, v136
	v_readlane_b32 s4, v67, 27
	s_nop 1
	v_fmac_f32_e32 v66, s4, v141
	v_readlane_b32 s4, v67, 28
	s_nop 1
	v_fmac_f32_e32 v66, s4, v139
	v_readlane_b32 s4, v67, 29
	s_nop 1
	v_fmac_f32_e32 v66, s4, v140
	v_readlane_b32 s4, v67, 30
	s_nop 1
	v_fmac_f32_e32 v66, s4, v142
	v_readlane_b32 s4, v67, 31
	s_nop 1
	v_fmac_f32_e32 v66, s4, v143
	v_min_f32_e32 v68, 0, v66
	v_mul_f32_e64 v66, |v66|, s0
	v_exp_f32_e32 v66, v66
	v_readlane_b32 s4, v67, 32
	v_add_f32_e32 v66, 1.0, v66
	v_cmp_gt_f32_e32 vcc, s92, v66
	s_nop 1
	v_cndmask_b32_e64 v69, 0, 32, vcc
	v_ldexp_f32 v66, v66, v69
	v_log_f32_e32 v66, v66
	s_nop 0
	v_mul_f32_e32 v69, 0x3f317217, v66
	v_fma_f32 v69, v66, s3, -v69
	v_fmac_f32_e32 v69, 0x3377d1cf, v66
	v_fmac_f32_e32 v69, 0x3f317217, v66
	v_cmp_lt_f32_e64 s[6:7], |v66|, s96
	s_nop 1
	v_cndmask_b32_e64 v66, v66, v69, s[6:7]
	v_cndmask_b32_e32 v69, 0, v244, vcc
	v_sub_f32_e32 v66, v66, v69
	v_sub_f32_e32 v66, v68, v66
	v_fmamk_f32 v125, v66, 0x3d800000, v124
	v_fma_f32 v66, s4, v99, v144
	v_readlane_b32 s4, v67, 33
	s_nop 1
	v_fmac_f32_e32 v66, s4, v130
	v_readlane_b32 s4, v67, 34
	s_nop 1
	v_fmac_f32_e32 v66, s4, v98
	v_readlane_b32 s4, v67, 35
	s_nop 1
	v_fmac_f32_e32 v66, s4, v133
	v_readlane_b32 s4, v67, 36
	s_nop 1
	v_fmac_f32_e32 v66, s4, v131
	v_readlane_b32 s4, v67, 37
	s_nop 1
	v_fmac_f32_e32 v66, s4, v132
	v_readlane_b32 s4, v67, 38
	s_nop 1
	v_fmac_f32_e32 v66, s4, v134
	v_readlane_b32 s4, v67, 39
	s_nop 1
	v_fmac_f32_e32 v66, s4, v135
	v_readlane_b32 s4, v67, 40
	s_nop 1
	v_fmac_f32_e32 v66, s4, v137
	v_readlane_b32 s4, v67, 41
	s_nop 1
	v_fmac_f32_e32 v66, s4, v138
	v_readlane_b32 s4, v67, 42
	s_nop 1
	v_fmac_f32_e32 v66, s4, v136
	v_readlane_b32 s4, v67, 43
	s_nop 1
	v_fmac_f32_e32 v66, s4, v141
	v_readlane_b32 s4, v67, 44
	s_nop 1
	v_fmac_f32_e32 v66, s4, v139
	v_readlane_b32 s4, v67, 45
	s_nop 1
	v_fmac_f32_e32 v66, s4, v140
	v_readlane_b32 s4, v67, 46
	s_nop 1
	v_fmac_f32_e32 v66, s4, v142
	v_readlane_b32 s4, v67, 47
	s_nop 1
	v_fmac_f32_e32 v66, s4, v143
	v_min_f32_e32 v68, 0, v66
	v_mul_f32_e64 v66, |v66|, s0
	v_exp_f32_e32 v66, v66
	v_readlane_b32 s4, v67, 48
	v_add_f32_e32 v66, 1.0, v66
	v_cmp_gt_f32_e32 vcc, s92, v66
	s_nop 1
	v_cndmask_b32_e64 v69, 0, 32, vcc
	v_ldexp_f32 v66, v66, v69
	v_log_f32_e32 v66, v66
	s_nop 0
	v_mul_f32_e32 v69, 0x3f317217, v66
	v_fma_f32 v69, v66, s3, -v69
	v_fmac_f32_e32 v69, 0x3377d1cf, v66
	v_fmac_f32_e32 v69, 0x3f317217, v66
	v_cmp_lt_f32_e64 s[6:7], |v66|, s96
	s_nop 1
	v_cndmask_b32_e64 v66, v66, v69, s[6:7]
	v_cndmask_b32_e32 v69, 0, v244, vcc
	v_sub_f32_e32 v66, v66, v69
	v_sub_f32_e32 v66, v68, v66
	v_fmamk_f32 v126, v66, 0x3d800000, v125
	v_fma_f32 v66, s4, v99, v144
	v_readlane_b32 s4, v67, 49
	s_nop 1
	v_fmac_f32_e32 v66, s4, v130
	v_readlane_b32 s4, v67, 50
	s_nop 1
	v_fmac_f32_e32 v66, s4, v98
	v_readlane_b32 s4, v67, 51
	s_nop 1
	v_fmac_f32_e32 v66, s4, v133
	v_readlane_b32 s4, v67, 52
	s_nop 1
	v_fmac_f32_e32 v66, s4, v131
	v_readlane_b32 s4, v67, 53
	s_nop 1
	v_fmac_f32_e32 v66, s4, v132
	v_readlane_b32 s4, v67, 54
	s_nop 1
	v_fmac_f32_e32 v66, s4, v134
	v_readlane_b32 s4, v67, 55
	s_nop 1
	v_fmac_f32_e32 v66, s4, v135
	v_readlane_b32 s4, v67, 56
	s_nop 1
	v_fmac_f32_e32 v66, s4, v137
	v_readlane_b32 s4, v67, 57
	s_nop 1
	v_fmac_f32_e32 v66, s4, v138
	v_readlane_b32 s4, v67, 58
	s_nop 1
	v_fmac_f32_e32 v66, s4, v136
	v_readlane_b32 s4, v67, 59
	s_nop 1
	v_fmac_f32_e32 v66, s4, v141
	v_readlane_b32 s4, v67, 60
	s_nop 1
	v_fmac_f32_e32 v66, s4, v139
	v_readlane_b32 s4, v67, 61
	s_nop 1
	v_fmac_f32_e32 v66, s4, v140
	v_readlane_b32 s4, v67, 62
	s_nop 1
	v_fmac_f32_e32 v66, s4, v142
	v_readlane_b32 s4, v67, 63
	s_nop 1
	v_fmac_f32_e32 v66, s4, v143
	v_min_f32_e32 v67, 0, v66
	v_mul_f32_e64 v66, |v66|, s0
	v_exp_f32_e32 v66, v66
	s_waitcnt lgkmcnt(5)
	v_readlane_b32 s4, v64, 0
	v_add_f32_e32 v66, 1.0, v66
	v_cmp_gt_f32_e32 vcc, s92, v66
	s_nop 1
	v_cndmask_b32_e64 v68, 0, 32, vcc
	v_ldexp_f32 v66, v66, v68
	v_log_f32_e32 v66, v66
	s_nop 0
	v_mul_f32_e32 v68, 0x3f317217, v66
	v_fma_f32 v68, v66, s3, -v68
	v_fmac_f32_e32 v68, 0x3377d1cf, v66
	v_fmac_f32_e32 v68, 0x3f317217, v66
	v_cmp_lt_f32_e64 s[6:7], |v66|, s96
	s_nop 1
	v_cndmask_b32_e64 v66, v66, v68, s[6:7]
	v_cndmask_b32_e32 v68, 0, v244, vcc
	v_sub_f32_e32 v66, v66, v68
	v_sub_f32_e32 v66, v67, v66
	v_fmamk_f32 v127, v66, 0x3d800000, v126
	v_fma_f32 v66, s4, v99, v144
	v_readlane_b32 s4, v64, 1
	s_nop 1
	v_fmac_f32_e32 v66, s4, v130
	v_readlane_b32 s4, v64, 2
	s_nop 1
	v_fmac_f32_e32 v66, s4, v98
	v_readlane_b32 s4, v64, 3
	s_nop 1
	v_fmac_f32_e32 v66, s4, v133
	v_readlane_b32 s4, v64, 4
	s_nop 1
	v_fmac_f32_e32 v66, s4, v131
	v_readlane_b32 s4, v64, 5
	s_nop 1
	v_fmac_f32_e32 v66, s4, v132
	v_readlane_b32 s4, v64, 6
	s_nop 1
	v_fmac_f32_e32 v66, s4, v134
	v_readlane_b32 s4, v64, 7
	s_nop 1
	v_fmac_f32_e32 v66, s4, v135
	v_readlane_b32 s4, v64, 8
	s_nop 1
	v_fmac_f32_e32 v66, s4, v137
	v_readlane_b32 s4, v64, 9
	s_nop 1
	v_fmac_f32_e32 v66, s4, v138
	v_readlane_b32 s4, v64, 10
	s_nop 1
	v_fmac_f32_e32 v66, s4, v136
	v_readlane_b32 s4, v64, 11
	s_nop 1
	v_fmac_f32_e32 v66, s4, v141
	v_readlane_b32 s4, v64, 12
	s_nop 1
	v_fmac_f32_e32 v66, s4, v139
	v_readlane_b32 s4, v64, 13
	s_nop 1
	v_fmac_f32_e32 v66, s4, v140
	v_readlane_b32 s4, v64, 14
	s_nop 1
	v_fmac_f32_e32 v66, s4, v142
	v_readlane_b32 s4, v64, 15
	s_nop 1
	v_fmac_f32_e32 v66, s4, v143
	v_min_f32_e32 v67, 0, v66
	v_mul_f32_e64 v66, |v66|, s0
	v_exp_f32_e32 v66, v66
	v_readlane_b32 s4, v64, 16
	v_add_f32_e32 v66, 1.0, v66
	v_cmp_gt_f32_e32 vcc, s92, v66
	s_nop 1
	v_cndmask_b32_e64 v68, 0, 32, vcc
	v_ldexp_f32 v66, v66, v68
	v_log_f32_e32 v66, v66
	s_nop 0
	v_mul_f32_e32 v68, 0x3f317217, v66
	v_fma_f32 v68, v66, s3, -v68
	v_fmac_f32_e32 v68, 0x3377d1cf, v66
	v_fmac_f32_e32 v68, 0x3f317217, v66
	v_cmp_lt_f32_e64 s[6:7], |v66|, s96
	s_nop 1
	v_cndmask_b32_e64 v66, v66, v68, s[6:7]
	v_cndmask_b32_e32 v68, 0, v244, vcc
	v_sub_f32_e32 v66, v66, v68
	v_sub_f32_e32 v66, v67, v66
	v_fmamk_f32 v128, v66, 0x3d800000, v127
	v_fma_f32 v66, s4, v99, v144
	v_readlane_b32 s4, v64, 17
	s_nop 1
	v_fmac_f32_e32 v66, s4, v130
	v_readlane_b32 s4, v64, 18
	s_nop 1
	v_fmac_f32_e32 v66, s4, v98
	v_readlane_b32 s4, v64, 19
	s_nop 1
	v_fmac_f32_e32 v66, s4, v133
	v_readlane_b32 s4, v64, 20
	s_nop 1
	v_fmac_f32_e32 v66, s4, v131
	v_readlane_b32 s4, v64, 21
	s_nop 1
	v_fmac_f32_e32 v66, s4, v132
	v_readlane_b32 s4, v64, 22
	s_nop 1
	v_fmac_f32_e32 v66, s4, v134
	v_readlane_b32 s4, v64, 23
	s_nop 1
	v_fmac_f32_e32 v66, s4, v135
	v_readlane_b32 s4, v64, 24
	s_nop 1
	v_fmac_f32_e32 v66, s4, v137
	v_readlane_b32 s4, v64, 25
	s_nop 1
	v_fmac_f32_e32 v66, s4, v138
	v_readlane_b32 s4, v64, 26
	s_nop 1
	v_fmac_f32_e32 v66, s4, v136
	v_readlane_b32 s4, v64, 27
	s_nop 1
	v_fmac_f32_e32 v66, s4, v141
	v_readlane_b32 s4, v64, 28
	s_nop 1
	v_fmac_f32_e32 v66, s4, v139
	v_readlane_b32 s4, v64, 29
	s_nop 1
	v_fmac_f32_e32 v66, s4, v140
	v_readlane_b32 s4, v64, 30
	s_nop 1
	v_fmac_f32_e32 v66, s4, v142
	v_readlane_b32 s4, v64, 31
	s_nop 1
	v_fmac_f32_e32 v66, s4, v143
	v_min_f32_e32 v67, 0, v66
	v_mul_f32_e64 v66, |v66|, s0
	v_exp_f32_e32 v66, v66
	v_readlane_b32 s4, v64, 32
	v_add_f32_e32 v66, 1.0, v66
	v_cmp_gt_f32_e32 vcc, s92, v66
	s_nop 1
	v_cndmask_b32_e64 v68, 0, 32, vcc
	v_ldexp_f32 v66, v66, v68
	v_log_f32_e32 v66, v66
	s_nop 0
	v_mul_f32_e32 v68, 0x3f317217, v66
	v_fma_f32 v68, v66, s3, -v68
	v_fmac_f32_e32 v68, 0x3377d1cf, v66
	v_fmac_f32_e32 v68, 0x3f317217, v66
	v_cmp_lt_f32_e64 s[6:7], |v66|, s96
	s_nop 1
	v_cndmask_b32_e64 v66, v66, v68, s[6:7]
	v_cndmask_b32_e32 v68, 0, v244, vcc
	v_sub_f32_e32 v66, v66, v68
	v_sub_f32_e32 v66, v67, v66
	v_fmamk_f32 v91, v66, 0x3d800000, v128
	v_fma_f32 v66, s4, v99, v144
	v_readlane_b32 s4, v64, 33
	s_nop 1
	v_fmac_f32_e32 v66, s4, v130
	v_readlane_b32 s4, v64, 34
	s_nop 1
	v_fmac_f32_e32 v66, s4, v98
	v_readlane_b32 s4, v64, 35
	s_nop 1
	v_fmac_f32_e32 v66, s4, v133
	v_readlane_b32 s4, v64, 36
	s_nop 1
	v_fmac_f32_e32 v66, s4, v131
	v_readlane_b32 s4, v64, 37
	s_nop 1
	v_fmac_f32_e32 v66, s4, v132
	v_readlane_b32 s4, v64, 38
	s_nop 1
	v_fmac_f32_e32 v66, s4, v134
	v_readlane_b32 s4, v64, 39
	s_nop 1
	v_fmac_f32_e32 v66, s4, v135
	v_readlane_b32 s4, v64, 40
	s_nop 1
	v_fmac_f32_e32 v66, s4, v137
	v_readlane_b32 s4, v64, 41
	s_nop 1
	v_fmac_f32_e32 v66, s4, v138
	v_readlane_b32 s4, v64, 42
	s_nop 1
	v_fmac_f32_e32 v66, s4, v136
	v_readlane_b32 s4, v64, 43
	s_nop 1
	v_fmac_f32_e32 v66, s4, v141
	v_readlane_b32 s4, v64, 44
	s_nop 1
	v_fmac_f32_e32 v66, s4, v139
	v_readlane_b32 s4, v64, 45
	s_nop 1
	v_fmac_f32_e32 v66, s4, v140
	v_readlane_b32 s4, v64, 46
	s_nop 1
	v_fmac_f32_e32 v66, s4, v142
	v_readlane_b32 s4, v64, 47
	s_nop 1
	v_fmac_f32_e32 v66, s4, v143
	v_min_f32_e32 v67, 0, v66
	v_mul_f32_e64 v66, |v66|, s0
	v_exp_f32_e32 v66, v66
	v_readlane_b32 s4, v64, 48
	v_add_f32_e32 v66, 1.0, v66
	v_cmp_gt_f32_e32 vcc, s92, v66
	s_nop 1
	v_cndmask_b32_e64 v68, 0, 32, vcc
	v_ldexp_f32 v66, v66, v68
	v_log_f32_e32 v66, v66
	s_nop 0
	v_mul_f32_e32 v68, 0x3f317217, v66
	v_fma_f32 v68, v66, s3, -v68
	v_fmac_f32_e32 v68, 0x3377d1cf, v66
	v_fmac_f32_e32 v68, 0x3f317217, v66
	v_cmp_lt_f32_e64 s[6:7], |v66|, s96
	s_nop 1
	v_cndmask_b32_e64 v66, v66, v68, s[6:7]
	v_cndmask_b32_e32 v68, 0, v244, vcc
	v_sub_f32_e32 v66, v66, v68
	v_sub_f32_e32 v66, v67, v66
	v_fmamk_f32 v93, v66, 0x3d800000, v91
	v_fma_f32 v66, s4, v99, v144
	v_readlane_b32 s4, v64, 49
	s_nop 1
	v_fmac_f32_e32 v66, s4, v130
	v_readlane_b32 s4, v64, 50
	s_nop 1
	v_fmac_f32_e32 v66, s4, v98
	v_readlane_b32 s4, v64, 51
	s_nop 1
	v_fmac_f32_e32 v66, s4, v133
	v_readlane_b32 s4, v64, 52
	s_nop 1
	v_fmac_f32_e32 v66, s4, v131
	v_readlane_b32 s4, v64, 53
	s_nop 1
	v_fmac_f32_e32 v66, s4, v132
	v_readlane_b32 s4, v64, 54
	s_nop 1
	v_fmac_f32_e32 v66, s4, v134
	v_readlane_b32 s4, v64, 55
	s_nop 1
	v_fmac_f32_e32 v66, s4, v135
	v_readlane_b32 s4, v64, 56
	s_nop 1
	v_fmac_f32_e32 v66, s4, v137
	v_readlane_b32 s4, v64, 57
	s_nop 1
	v_fmac_f32_e32 v66, s4, v138
	v_readlane_b32 s4, v64, 58
	s_nop 1
	v_fmac_f32_e32 v66, s4, v136
	v_readlane_b32 s4, v64, 59
	s_nop 1
	v_fmac_f32_e32 v66, s4, v141
	v_readlane_b32 s4, v64, 60
	s_nop 1
	v_fmac_f32_e32 v66, s4, v139
	v_readlane_b32 s4, v64, 61
	s_nop 1
	v_fmac_f32_e32 v66, s4, v140
	v_readlane_b32 s4, v64, 62
	s_nop 1
	v_fmac_f32_e32 v66, s4, v142
	v_readlane_b32 s4, v64, 63
	s_nop 1
	v_fmac_f32_e32 v66, s4, v143
	v_min_f32_e32 v64, 0, v66
	v_mul_f32_e64 v66, |v66|, s0
	v_exp_f32_e32 v66, v66
	v_readlane_b32 s4, v65, 0
	v_add_f32_e32 v66, 1.0, v66
	v_cmp_gt_f32_e32 vcc, s92, v66
	s_nop 1
	v_cndmask_b32_e64 v67, 0, 32, vcc
	v_ldexp_f32 v66, v66, v67
	v_log_f32_e32 v66, v66
	s_nop 0
	v_mul_f32_e32 v67, 0x3f317217, v66
	v_fma_f32 v67, v66, s3, -v67
	v_fmac_f32_e32 v67, 0x3377d1cf, v66
	v_fmac_f32_e32 v67, 0x3f317217, v66
	v_cmp_lt_f32_e64 s[6:7], |v66|, s96
	s_nop 1
	v_cndmask_b32_e64 v66, v66, v67, s[6:7]
	v_cndmask_b32_e32 v67, 0, v244, vcc
	v_sub_f32_e32 v66, v66, v67
	v_sub_f32_e32 v64, v64, v66
	v_fmamk_f32 v95, v64, 0x3d800000, v93
	v_fma_f32 v64, s4, v99, v144
	v_readlane_b32 s4, v65, 1
	s_nop 1
	v_fmac_f32_e32 v64, s4, v130
	v_readlane_b32 s4, v65, 2
	s_nop 1
	v_fmac_f32_e32 v64, s4, v98
	v_readlane_b32 s4, v65, 3
	s_nop 1
	v_fmac_f32_e32 v64, s4, v133
	v_readlane_b32 s4, v65, 4
	s_nop 1
	v_fmac_f32_e32 v64, s4, v131
	v_readlane_b32 s4, v65, 5
	s_nop 1
	v_fmac_f32_e32 v64, s4, v132
	v_readlane_b32 s4, v65, 6
	s_nop 1
	v_fmac_f32_e32 v64, s4, v134
	v_readlane_b32 s4, v65, 7
	s_nop 1
	v_fmac_f32_e32 v64, s4, v135
	v_readlane_b32 s4, v65, 8
	s_nop 1
	v_fmac_f32_e32 v64, s4, v137
	v_readlane_b32 s4, v65, 9
	s_nop 1
	v_fmac_f32_e32 v64, s4, v138
	v_readlane_b32 s4, v65, 10
	s_nop 1
	v_fmac_f32_e32 v64, s4, v136
	v_readlane_b32 s4, v65, 11
	s_nop 1
	v_fmac_f32_e32 v64, s4, v141
	v_readlane_b32 s4, v65, 12
	s_nop 1
	v_fmac_f32_e32 v64, s4, v139
	v_readlane_b32 s4, v65, 13
	s_nop 1
	v_fmac_f32_e32 v64, s4, v140
	v_readlane_b32 s4, v65, 14
	s_nop 1
	v_fmac_f32_e32 v64, s4, v142
	v_readlane_b32 s4, v65, 15
	s_nop 1
	v_fmac_f32_e32 v64, s4, v143
	v_min_f32_e32 v66, 0, v64
	v_mul_f32_e64 v64, |v64|, s0
	v_exp_f32_e32 v64, v64
	v_readlane_b32 s4, v65, 16
	v_add_f32_e32 v64, 1.0, v64
	v_cmp_gt_f32_e32 vcc, s92, v64
	s_nop 1
	v_cndmask_b32_e64 v67, 0, 32, vcc
	v_ldexp_f32 v64, v64, v67
	v_log_f32_e32 v64, v64
	s_nop 0
	v_mul_f32_e32 v67, 0x3f317217, v64
	v_fma_f32 v67, v64, s3, -v67
	v_fmac_f32_e32 v67, 0x3377d1cf, v64
	v_fmac_f32_e32 v67, 0x3f317217, v64
	v_cmp_lt_f32_e64 s[6:7], |v64|, s96
	s_nop 1
	v_cndmask_b32_e64 v64, v64, v67, s[6:7]
	v_cndmask_b32_e32 v67, 0, v244, vcc
	v_sub_f32_e32 v64, v64, v67
	v_sub_f32_e32 v64, v66, v64
	v_fmamk_f32 v97, v64, 0x3d800000, v95
	v_fma_f32 v64, s4, v99, v144
	v_readlane_b32 s4, v65, 17
	s_nop 1
	v_fmac_f32_e32 v64, s4, v130
	v_readlane_b32 s4, v65, 18
	s_nop 1
	v_fmac_f32_e32 v64, s4, v98
	v_readlane_b32 s4, v65, 19
	s_nop 1
	v_fmac_f32_e32 v64, s4, v133
	v_readlane_b32 s4, v65, 20
	s_nop 1
	v_fmac_f32_e32 v64, s4, v131
	v_readlane_b32 s4, v65, 21
	s_nop 1
	v_fmac_f32_e32 v64, s4, v132
	v_readlane_b32 s4, v65, 22
	s_nop 1
	v_fmac_f32_e32 v64, s4, v134
	v_readlane_b32 s4, v65, 23
	s_nop 1
	v_fmac_f32_e32 v64, s4, v135
	v_readlane_b32 s4, v65, 24
	s_nop 1
	v_fmac_f32_e32 v64, s4, v137
	v_readlane_b32 s4, v65, 25
	s_nop 1
	v_fmac_f32_e32 v64, s4, v138
	v_readlane_b32 s4, v65, 26
	s_nop 1
	v_fmac_f32_e32 v64, s4, v136
	v_readlane_b32 s4, v65, 27
	s_nop 1
	v_fmac_f32_e32 v64, s4, v141
	v_readlane_b32 s4, v65, 28
	s_nop 1
	v_fmac_f32_e32 v64, s4, v139
	v_readlane_b32 s4, v65, 29
	s_nop 1
	v_fmac_f32_e32 v64, s4, v140
	v_readlane_b32 s4, v65, 30
	s_nop 1
	v_fmac_f32_e32 v64, s4, v142
	v_readlane_b32 s4, v65, 31
	s_nop 1
	v_fmac_f32_e32 v64, s4, v143
	v_min_f32_e32 v66, 0, v64
	v_mul_f32_e64 v64, |v64|, s0
	v_exp_f32_e32 v64, v64
	v_readlane_b32 s4, v65, 32
	v_add_f32_e32 v64, 1.0, v64
	v_cmp_gt_f32_e32 vcc, s92, v64
	s_nop 1
	v_cndmask_b32_e64 v67, 0, 32, vcc
	v_ldexp_f32 v64, v64, v67
	v_log_f32_e32 v64, v64
	s_nop 0
	v_mul_f32_e32 v67, 0x3f317217, v64
	v_fma_f32 v67, v64, s3, -v67
	v_fmac_f32_e32 v67, 0x3377d1cf, v64
	v_fmac_f32_e32 v67, 0x3f317217, v64
	v_cmp_lt_f32_e64 s[6:7], |v64|, s96
	s_nop 1
	v_cndmask_b32_e64 v64, v64, v67, s[6:7]
	v_cndmask_b32_e32 v67, 0, v244, vcc
	v_sub_f32_e32 v64, v64, v67
	v_sub_f32_e32 v64, v66, v64
	v_fmamk_f32 v100, v64, 0x3d800000, v97
	v_fma_f32 v64, s4, v99, v144
	v_readlane_b32 s4, v65, 33
	s_nop 1
	v_fmac_f32_e32 v64, s4, v130
	v_readlane_b32 s4, v65, 34
	s_nop 1
	v_fmac_f32_e32 v64, s4, v98
	v_readlane_b32 s4, v65, 35
	s_nop 1
	v_fmac_f32_e32 v64, s4, v133
	v_readlane_b32 s4, v65, 36
	s_nop 1
	v_fmac_f32_e32 v64, s4, v131
	v_readlane_b32 s4, v65, 37
	s_nop 1
	v_fmac_f32_e32 v64, s4, v132
	v_readlane_b32 s4, v65, 38
	s_nop 1
	v_fmac_f32_e32 v64, s4, v134
	v_readlane_b32 s4, v65, 39
	s_nop 1
	v_fmac_f32_e32 v64, s4, v135
	v_readlane_b32 s4, v65, 40
	s_nop 1
	v_fmac_f32_e32 v64, s4, v137
	v_readlane_b32 s4, v65, 41
	s_nop 1
	v_fmac_f32_e32 v64, s4, v138
	v_readlane_b32 s4, v65, 42
	s_nop 1
	v_fmac_f32_e32 v64, s4, v136
	v_readlane_b32 s4, v65, 43
	s_nop 1
	v_fmac_f32_e32 v64, s4, v141
	v_readlane_b32 s4, v65, 44
	s_nop 1
	v_fmac_f32_e32 v64, s4, v139
	v_readlane_b32 s4, v65, 45
	s_nop 1
	v_fmac_f32_e32 v64, s4, v140
	v_readlane_b32 s4, v65, 46
	s_nop 1
	v_fmac_f32_e32 v64, s4, v142
	v_readlane_b32 s4, v65, 47
	s_nop 1
	v_fmac_f32_e32 v64, s4, v143
	v_min_f32_e32 v66, 0, v64
	v_mul_f32_e64 v64, |v64|, s0
	v_exp_f32_e32 v64, v64
	v_readlane_b32 s4, v65, 48
	v_add_f32_e32 v64, 1.0, v64
	v_cmp_gt_f32_e32 vcc, s92, v64
	s_nop 1
	v_cndmask_b32_e64 v67, 0, 32, vcc
	v_ldexp_f32 v64, v64, v67
	v_log_f32_e32 v64, v64
	s_nop 0
	v_mul_f32_e32 v67, 0x3f317217, v64
	v_fma_f32 v67, v64, s3, -v67
	v_fmac_f32_e32 v67, 0x3377d1cf, v64
	v_fmac_f32_e32 v67, 0x3f317217, v64
	v_cmp_lt_f32_e64 s[6:7], |v64|, s96
	s_nop 1
	v_cndmask_b32_e64 v64, v64, v67, s[6:7]
	v_cndmask_b32_e32 v67, 0, v244, vcc
	v_sub_f32_e32 v64, v64, v67
	v_sub_f32_e32 v64, v66, v64
	v_fmamk_f32 v101, v64, 0x3d800000, v100
	v_fma_f32 v64, s4, v99, v144
	v_readlane_b32 s4, v65, 49
	s_nop 1
	v_fmac_f32_e32 v64, s4, v130
	v_readlane_b32 s4, v65, 50
	s_nop 1
	v_fmac_f32_e32 v64, s4, v98
	v_readlane_b32 s4, v65, 51
	s_nop 1
	v_fmac_f32_e32 v64, s4, v133
	v_readlane_b32 s4, v65, 52
	s_nop 1
	v_fmac_f32_e32 v64, s4, v131
	v_readlane_b32 s4, v65, 53
	s_nop 1
	v_fmac_f32_e32 v64, s4, v132
	v_readlane_b32 s4, v65, 54
	s_nop 1
	v_fmac_f32_e32 v64, s4, v134
	v_readlane_b32 s4, v65, 55
	s_nop 1
	v_fmac_f32_e32 v64, s4, v135
	v_readlane_b32 s4, v65, 56
	s_nop 1
	v_fmac_f32_e32 v64, s4, v137
	v_readlane_b32 s4, v65, 57
	s_nop 1
	v_fmac_f32_e32 v64, s4, v138
	v_readlane_b32 s4, v65, 58
	s_nop 1
	v_fmac_f32_e32 v64, s4, v136
	v_readlane_b32 s4, v65, 59
	s_nop 1
	v_fmac_f32_e32 v64, s4, v141
	v_readlane_b32 s4, v65, 60
	s_nop 1
	v_fmac_f32_e32 v64, s4, v139
	v_readlane_b32 s4, v65, 61
	s_nop 1
	v_fmac_f32_e32 v64, s4, v140
	v_readlane_b32 s4, v65, 62
	s_nop 1
	v_fmac_f32_e32 v64, s4, v142
	v_readlane_b32 s4, v65, 63
	s_nop 1
	v_fmac_f32_e32 v64, s4, v143
	v_min_f32_e32 v65, 0, v64
	v_mul_f32_e64 v64, |v64|, s0
	v_exp_f32_e32 v64, v64
	s_waitcnt lgkmcnt(4)
	v_readlane_b32 s4, v62, 0
	v_add_f32_e32 v64, 1.0, v64
	v_cmp_gt_f32_e32 vcc, s92, v64
	s_nop 1
	v_cndmask_b32_e64 v66, 0, 32, vcc
	v_ldexp_f32 v64, v64, v66
	v_log_f32_e32 v64, v64
	s_nop 0
	v_mul_f32_e32 v66, 0x3f317217, v64
	v_fma_f32 v66, v64, s3, -v66
	v_fmac_f32_e32 v66, 0x3377d1cf, v64
	v_fmac_f32_e32 v66, 0x3f317217, v64
	v_cmp_lt_f32_e64 s[6:7], |v64|, s96
	s_nop 1
	v_cndmask_b32_e64 v64, v64, v66, s[6:7]
	v_cndmask_b32_e32 v66, 0, v244, vcc
	v_sub_f32_e32 v64, v64, v66
	v_sub_f32_e32 v64, v65, v64
	v_fmamk_f32 v102, v64, 0x3d800000, v101
	v_fma_f32 v64, s4, v99, v144
	v_readlane_b32 s4, v62, 1
	s_nop 1
	v_fmac_f32_e32 v64, s4, v130
	v_readlane_b32 s4, v62, 2
	s_nop 1
	v_fmac_f32_e32 v64, s4, v98
	v_readlane_b32 s4, v62, 3
	s_nop 1
	v_fmac_f32_e32 v64, s4, v133
	v_readlane_b32 s4, v62, 4
	s_nop 1
	v_fmac_f32_e32 v64, s4, v131
	v_readlane_b32 s4, v62, 5
	s_nop 1
	v_fmac_f32_e32 v64, s4, v132
	v_readlane_b32 s4, v62, 6
	s_nop 1
	v_fmac_f32_e32 v64, s4, v134
	v_readlane_b32 s4, v62, 7
	s_nop 1
	v_fmac_f32_e32 v64, s4, v135
	v_readlane_b32 s4, v62, 8
	s_nop 1
	v_fmac_f32_e32 v64, s4, v137
	v_readlane_b32 s4, v62, 9
	s_nop 1
	v_fmac_f32_e32 v64, s4, v138
	v_readlane_b32 s4, v62, 10
	s_nop 1
	v_fmac_f32_e32 v64, s4, v136
	v_readlane_b32 s4, v62, 11
	s_nop 1
	v_fmac_f32_e32 v64, s4, v141
	v_readlane_b32 s4, v62, 12
	s_nop 1
	v_fmac_f32_e32 v64, s4, v139
	v_readlane_b32 s4, v62, 13
	s_nop 1
	v_fmac_f32_e32 v64, s4, v140
	v_readlane_b32 s4, v62, 14
	s_nop 1
	v_fmac_f32_e32 v64, s4, v142
	v_readlane_b32 s4, v62, 15
	s_nop 1
	v_fmac_f32_e32 v64, s4, v143
	v_min_f32_e32 v65, 0, v64
	v_mul_f32_e64 v64, |v64|, s0
	v_exp_f32_e32 v64, v64
	v_readlane_b32 s4, v62, 16
	v_add_f32_e32 v64, 1.0, v64
	v_cmp_gt_f32_e32 vcc, s92, v64
	s_nop 1
	v_cndmask_b32_e64 v66, 0, 32, vcc
	v_ldexp_f32 v64, v64, v66
	v_log_f32_e32 v64, v64
	s_nop 0
	v_mul_f32_e32 v66, 0x3f317217, v64
	v_fma_f32 v66, v64, s3, -v66
	v_fmac_f32_e32 v66, 0x3377d1cf, v64
	v_fmac_f32_e32 v66, 0x3f317217, v64
	v_cmp_lt_f32_e64 s[6:7], |v64|, s96
	s_nop 1
	v_cndmask_b32_e64 v64, v64, v66, s[6:7]
	v_cndmask_b32_e32 v66, 0, v244, vcc
	v_sub_f32_e32 v64, v64, v66
	v_sub_f32_e32 v64, v65, v64
	v_fmamk_f32 v103, v64, 0x3d800000, v102
	v_fma_f32 v64, s4, v99, v144
	v_readlane_b32 s4, v62, 17
	s_nop 1
	v_fmac_f32_e32 v64, s4, v130
	v_readlane_b32 s4, v62, 18
	s_nop 1
	v_fmac_f32_e32 v64, s4, v98
	v_readlane_b32 s4, v62, 19
	s_nop 1
	v_fmac_f32_e32 v64, s4, v133
	v_readlane_b32 s4, v62, 20
	s_nop 1
	v_fmac_f32_e32 v64, s4, v131
	v_readlane_b32 s4, v62, 21
	s_nop 1
	v_fmac_f32_e32 v64, s4, v132
	v_readlane_b32 s4, v62, 22
	s_nop 1
	v_fmac_f32_e32 v64, s4, v134
	v_readlane_b32 s4, v62, 23
	s_nop 1
	v_fmac_f32_e32 v64, s4, v135
	v_readlane_b32 s4, v62, 24
	s_nop 1
	v_fmac_f32_e32 v64, s4, v137
	v_readlane_b32 s4, v62, 25
	s_nop 1
	v_fmac_f32_e32 v64, s4, v138
	v_readlane_b32 s4, v62, 26
	s_nop 1
	v_fmac_f32_e32 v64, s4, v136
	v_readlane_b32 s4, v62, 27
	s_nop 1
	v_fmac_f32_e32 v64, s4, v141
	v_readlane_b32 s4, v62, 28
	s_nop 1
	v_fmac_f32_e32 v64, s4, v139
	v_readlane_b32 s4, v62, 29
	s_nop 1
	v_fmac_f32_e32 v64, s4, v140
	v_readlane_b32 s4, v62, 30
	s_nop 1
	v_fmac_f32_e32 v64, s4, v142
	v_readlane_b32 s4, v62, 31
	s_nop 1
	v_fmac_f32_e32 v64, s4, v143
	v_min_f32_e32 v65, 0, v64
	v_mul_f32_e64 v64, |v64|, s0
	v_exp_f32_e32 v64, v64
	v_readlane_b32 s4, v62, 32
	v_add_f32_e32 v64, 1.0, v64
	v_cmp_gt_f32_e32 vcc, s92, v64
	s_nop 1
	v_cndmask_b32_e64 v66, 0, 32, vcc
	v_ldexp_f32 v64, v64, v66
	v_log_f32_e32 v64, v64
	s_nop 0
	v_mul_f32_e32 v66, 0x3f317217, v64
	v_fma_f32 v66, v64, s3, -v66
	v_fmac_f32_e32 v66, 0x3377d1cf, v64
	v_fmac_f32_e32 v66, 0x3f317217, v64
	v_cmp_lt_f32_e64 s[6:7], |v64|, s96
	s_nop 1
	v_cndmask_b32_e64 v64, v64, v66, s[6:7]
	v_cndmask_b32_e32 v66, 0, v244, vcc
	v_sub_f32_e32 v64, v64, v66
	v_sub_f32_e32 v64, v65, v64
	v_fmamk_f32 v104, v64, 0x3d800000, v103
	v_fma_f32 v64, s4, v99, v144
	v_readlane_b32 s4, v62, 33
	s_nop 1
	v_fmac_f32_e32 v64, s4, v130
	v_readlane_b32 s4, v62, 34
	s_nop 1
	v_fmac_f32_e32 v64, s4, v98
	v_readlane_b32 s4, v62, 35
	s_nop 1
	v_fmac_f32_e32 v64, s4, v133
	v_readlane_b32 s4, v62, 36
	s_nop 1
	v_fmac_f32_e32 v64, s4, v131
	v_readlane_b32 s4, v62, 37
	s_nop 1
	v_fmac_f32_e32 v64, s4, v132
	v_readlane_b32 s4, v62, 38
	s_nop 1
	v_fmac_f32_e32 v64, s4, v134
	v_readlane_b32 s4, v62, 39
	s_nop 1
	v_fmac_f32_e32 v64, s4, v135
	v_readlane_b32 s4, v62, 40
	s_nop 1
	v_fmac_f32_e32 v64, s4, v137
	v_readlane_b32 s4, v62, 41
	s_nop 1
	v_fmac_f32_e32 v64, s4, v138
	v_readlane_b32 s4, v62, 42
	s_nop 1
	v_fmac_f32_e32 v64, s4, v136
	v_readlane_b32 s4, v62, 43
	s_nop 1
	v_fmac_f32_e32 v64, s4, v141
	v_readlane_b32 s4, v62, 44
	s_nop 1
	v_fmac_f32_e32 v64, s4, v139
	v_readlane_b32 s4, v62, 45
	s_nop 1
	v_fmac_f32_e32 v64, s4, v140
	v_readlane_b32 s4, v62, 46
	s_nop 1
	v_fmac_f32_e32 v64, s4, v142
	v_readlane_b32 s4, v62, 47
	s_nop 1
	v_fmac_f32_e32 v64, s4, v143
	v_min_f32_e32 v65, 0, v64
	v_mul_f32_e64 v64, |v64|, s0
	v_exp_f32_e32 v64, v64
	v_readlane_b32 s4, v62, 48
	v_add_f32_e32 v64, 1.0, v64
	v_cmp_gt_f32_e32 vcc, s92, v64
	s_nop 1
	v_cndmask_b32_e64 v66, 0, 32, vcc
	v_ldexp_f32 v64, v64, v66
	v_log_f32_e32 v64, v64
	s_nop 0
	v_mul_f32_e32 v66, 0x3f317217, v64
	v_fma_f32 v66, v64, s3, -v66
	v_fmac_f32_e32 v66, 0x3377d1cf, v64
	v_fmac_f32_e32 v66, 0x3f317217, v64
	v_cmp_lt_f32_e64 s[6:7], |v64|, s96
	s_nop 1
	v_cndmask_b32_e64 v64, v64, v66, s[6:7]
	v_cndmask_b32_e32 v66, 0, v244, vcc
	v_sub_f32_e32 v64, v64, v66
	v_sub_f32_e32 v64, v65, v64
	v_fmamk_f32 v105, v64, 0x3d800000, v104
	v_fma_f32 v64, s4, v99, v144
	v_readlane_b32 s4, v62, 49
	s_nop 1
	v_fmac_f32_e32 v64, s4, v130
	v_readlane_b32 s4, v62, 50
	s_nop 1
	v_fmac_f32_e32 v64, s4, v98
	v_readlane_b32 s4, v62, 51
	s_nop 1
	v_fmac_f32_e32 v64, s4, v133
	v_readlane_b32 s4, v62, 52
	s_nop 1
	v_fmac_f32_e32 v64, s4, v131
	v_readlane_b32 s4, v62, 53
	s_nop 1
	v_fmac_f32_e32 v64, s4, v132
	v_readlane_b32 s4, v62, 54
	s_nop 1
	v_fmac_f32_e32 v64, s4, v134
	v_readlane_b32 s4, v62, 55
	s_nop 1
	v_fmac_f32_e32 v64, s4, v135
	v_readlane_b32 s4, v62, 56
	s_nop 1
	v_fmac_f32_e32 v64, s4, v137
	v_readlane_b32 s4, v62, 57
	s_nop 1
	v_fmac_f32_e32 v64, s4, v138
	v_readlane_b32 s4, v62, 58
	s_nop 1
	v_fmac_f32_e32 v64, s4, v136
	v_readlane_b32 s4, v62, 59
	s_nop 1
	v_fmac_f32_e32 v64, s4, v141
	v_readlane_b32 s4, v62, 60
	s_nop 1
	v_fmac_f32_e32 v64, s4, v139
	v_readlane_b32 s4, v62, 61
	s_nop 1
	v_fmac_f32_e32 v64, s4, v140
	v_readlane_b32 s4, v62, 62
	s_nop 1
	v_fmac_f32_e32 v64, s4, v142
	v_readlane_b32 s4, v62, 63
	s_nop 1
	v_fmac_f32_e32 v64, s4, v143
	v_min_f32_e32 v62, 0, v64
	v_mul_f32_e64 v64, |v64|, s0
	v_exp_f32_e32 v64, v64
	v_readlane_b32 s4, v63, 0
	v_add_f32_e32 v64, 1.0, v64
	v_cmp_gt_f32_e32 vcc, s92, v64
	s_nop 1
	v_cndmask_b32_e64 v65, 0, 32, vcc
	v_ldexp_f32 v64, v64, v65
	v_log_f32_e32 v64, v64
	s_nop 0
	v_mul_f32_e32 v65, 0x3f317217, v64
	v_fma_f32 v65, v64, s3, -v65
	v_fmac_f32_e32 v65, 0x3377d1cf, v64
	v_fmac_f32_e32 v65, 0x3f317217, v64
	v_cmp_lt_f32_e64 s[6:7], |v64|, s96
	s_nop 1
	v_cndmask_b32_e64 v64, v64, v65, s[6:7]
	v_cndmask_b32_e32 v65, 0, v244, vcc
	v_sub_f32_e32 v64, v64, v65
	v_sub_f32_e32 v62, v62, v64
	v_fmamk_f32 v106, v62, 0x3d800000, v105
	v_fma_f32 v62, s4, v99, v144
	v_readlane_b32 s4, v63, 1
	s_nop 1
	v_fmac_f32_e32 v62, s4, v130
	v_readlane_b32 s4, v63, 2
	s_nop 1
	v_fmac_f32_e32 v62, s4, v98
	v_readlane_b32 s4, v63, 3
	s_nop 1
	v_fmac_f32_e32 v62, s4, v133
	v_readlane_b32 s4, v63, 4
	s_nop 1
	v_fmac_f32_e32 v62, s4, v131
	v_readlane_b32 s4, v63, 5
	s_nop 1
	v_fmac_f32_e32 v62, s4, v132
	v_readlane_b32 s4, v63, 6
	s_nop 1
	v_fmac_f32_e32 v62, s4, v134
	v_readlane_b32 s4, v63, 7
	s_nop 1
	v_fmac_f32_e32 v62, s4, v135
	v_readlane_b32 s4, v63, 8
	s_nop 1
	v_fmac_f32_e32 v62, s4, v137
	v_readlane_b32 s4, v63, 9
	s_nop 1
	v_fmac_f32_e32 v62, s4, v138
	v_readlane_b32 s4, v63, 10
	s_nop 1
	v_fmac_f32_e32 v62, s4, v136
	v_readlane_b32 s4, v63, 11
	s_nop 1
	v_fmac_f32_e32 v62, s4, v141
	v_readlane_b32 s4, v63, 12
	s_nop 1
	v_fmac_f32_e32 v62, s4, v139
	v_readlane_b32 s4, v63, 13
	s_nop 1
	v_fmac_f32_e32 v62, s4, v140
	v_readlane_b32 s4, v63, 14
	s_nop 1
	v_fmac_f32_e32 v62, s4, v142
	v_readlane_b32 s4, v63, 15
	s_nop 1
	v_fmac_f32_e32 v62, s4, v143
	v_min_f32_e32 v64, 0, v62
	v_mul_f32_e64 v62, |v62|, s0
	v_exp_f32_e32 v62, v62
	v_readlane_b32 s4, v63, 16
	v_add_f32_e32 v62, 1.0, v62
	v_cmp_gt_f32_e32 vcc, s92, v62
	s_nop 1
	v_cndmask_b32_e64 v65, 0, 32, vcc
	v_ldexp_f32 v62, v62, v65
	v_log_f32_e32 v62, v62
	s_nop 0
	v_mul_f32_e32 v65, 0x3f317217, v62
	v_fma_f32 v65, v62, s3, -v65
	v_fmac_f32_e32 v65, 0x3377d1cf, v62
	v_fmac_f32_e32 v65, 0x3f317217, v62
	v_cmp_lt_f32_e64 s[6:7], |v62|, s96
	s_nop 1
	v_cndmask_b32_e64 v62, v62, v65, s[6:7]
	v_cndmask_b32_e32 v65, 0, v244, vcc
	v_sub_f32_e32 v62, v62, v65
	v_sub_f32_e32 v62, v64, v62
	v_fmamk_f32 v107, v62, 0x3d800000, v106
	v_fma_f32 v62, s4, v99, v144
	v_readlane_b32 s4, v63, 17
	s_nop 1
	v_fmac_f32_e32 v62, s4, v130
	v_readlane_b32 s4, v63, 18
	s_nop 1
	v_fmac_f32_e32 v62, s4, v98
	v_readlane_b32 s4, v63, 19
	s_nop 1
	v_fmac_f32_e32 v62, s4, v133
	v_readlane_b32 s4, v63, 20
	s_nop 1
	v_fmac_f32_e32 v62, s4, v131
	v_readlane_b32 s4, v63, 21
	s_nop 1
	v_fmac_f32_e32 v62, s4, v132
	v_readlane_b32 s4, v63, 22
	s_nop 1
	v_fmac_f32_e32 v62, s4, v134
	v_readlane_b32 s4, v63, 23
	s_nop 1
	v_fmac_f32_e32 v62, s4, v135
	v_readlane_b32 s4, v63, 24
	s_nop 1
	v_fmac_f32_e32 v62, s4, v137
	v_readlane_b32 s4, v63, 25
	s_nop 1
	v_fmac_f32_e32 v62, s4, v138
	v_readlane_b32 s4, v63, 26
	s_nop 1
	v_fmac_f32_e32 v62, s4, v136
	v_readlane_b32 s4, v63, 27
	s_nop 1
	v_fmac_f32_e32 v62, s4, v141
	v_readlane_b32 s4, v63, 28
	s_nop 1
	v_fmac_f32_e32 v62, s4, v139
	v_readlane_b32 s4, v63, 29
	s_nop 1
	v_fmac_f32_e32 v62, s4, v140
	v_readlane_b32 s4, v63, 30
	s_nop 1
	v_fmac_f32_e32 v62, s4, v142
	v_readlane_b32 s4, v63, 31
	s_nop 1
	v_fmac_f32_e32 v62, s4, v143
	v_min_f32_e32 v64, 0, v62
	v_mul_f32_e64 v62, |v62|, s0
	v_exp_f32_e32 v62, v62
	v_readlane_b32 s4, v63, 32
	v_add_f32_e32 v62, 1.0, v62
	v_cmp_gt_f32_e32 vcc, s92, v62
	s_nop 1
	v_cndmask_b32_e64 v65, 0, 32, vcc
	v_ldexp_f32 v62, v62, v65
	v_log_f32_e32 v62, v62
	s_nop 0
	v_mul_f32_e32 v65, 0x3f317217, v62
	v_fma_f32 v65, v62, s3, -v65
	v_fmac_f32_e32 v65, 0x3377d1cf, v62
	v_fmac_f32_e32 v65, 0x3f317217, v62
	v_cmp_lt_f32_e64 s[6:7], |v62|, s96
	s_nop 1
	v_cndmask_b32_e64 v62, v62, v65, s[6:7]
	v_cndmask_b32_e32 v65, 0, v244, vcc
	v_sub_f32_e32 v62, v62, v65
	v_sub_f32_e32 v62, v64, v62
	v_fmamk_f32 v109, v62, 0x3d800000, v107
	v_fma_f32 v62, s4, v99, v144
	v_readlane_b32 s4, v63, 33
	s_nop 1
	v_fmac_f32_e32 v62, s4, v130
	v_readlane_b32 s4, v63, 34
	s_nop 1
	v_fmac_f32_e32 v62, s4, v98
	v_readlane_b32 s4, v63, 35
	s_nop 1
	v_fmac_f32_e32 v62, s4, v133
	v_readlane_b32 s4, v63, 36
	s_nop 1
	v_fmac_f32_e32 v62, s4, v131
	v_readlane_b32 s4, v63, 37
	s_nop 1
	v_fmac_f32_e32 v62, s4, v132
	v_readlane_b32 s4, v63, 38
	s_nop 1
	v_fmac_f32_e32 v62, s4, v134
	v_readlane_b32 s4, v63, 39
	s_nop 1
	v_fmac_f32_e32 v62, s4, v135
	v_readlane_b32 s4, v63, 40
	s_nop 1
	v_fmac_f32_e32 v62, s4, v137
	v_readlane_b32 s4, v63, 41
	s_nop 1
	v_fmac_f32_e32 v62, s4, v138
	v_readlane_b32 s4, v63, 42
	s_nop 1
	v_fmac_f32_e32 v62, s4, v136
	v_readlane_b32 s4, v63, 43
	s_nop 1
	v_fmac_f32_e32 v62, s4, v141
	v_readlane_b32 s4, v63, 44
	s_nop 1
	v_fmac_f32_e32 v62, s4, v139
	v_readlane_b32 s4, v63, 45
	s_nop 1
	v_fmac_f32_e32 v62, s4, v140
	v_readlane_b32 s4, v63, 46
	s_nop 1
	v_fmac_f32_e32 v62, s4, v142
	v_readlane_b32 s4, v63, 47
	s_nop 1
	v_fmac_f32_e32 v62, s4, v143
	v_min_f32_e32 v64, 0, v62
	v_mul_f32_e64 v62, |v62|, s0
	v_exp_f32_e32 v62, v62
	v_readlane_b32 s4, v63, 48
	v_add_f32_e32 v62, 1.0, v62
	v_cmp_gt_f32_e32 vcc, s92, v62
	s_nop 1
	v_cndmask_b32_e64 v65, 0, 32, vcc
	v_ldexp_f32 v62, v62, v65
	v_log_f32_e32 v62, v62
	s_nop 0
	v_mul_f32_e32 v65, 0x3f317217, v62
	v_fma_f32 v65, v62, s3, -v65
	v_fmac_f32_e32 v65, 0x3377d1cf, v62
	v_fmac_f32_e32 v65, 0x3f317217, v62
	v_cmp_lt_f32_e64 s[6:7], |v62|, s96
	s_nop 1
	v_cndmask_b32_e64 v62, v62, v65, s[6:7]
	v_cndmask_b32_e32 v65, 0, v244, vcc
	v_sub_f32_e32 v62, v62, v65
	v_sub_f32_e32 v62, v64, v62
	v_fmamk_f32 v110, v62, 0x3d800000, v109
	v_fma_f32 v62, s4, v99, v144
	v_readlane_b32 s4, v63, 49
	s_nop 1
	v_fmac_f32_e32 v62, s4, v130
	v_readlane_b32 s4, v63, 50
	s_nop 1
	v_fmac_f32_e32 v62, s4, v98
	v_readlane_b32 s4, v63, 51
	s_nop 1
	v_fmac_f32_e32 v62, s4, v133
	v_readlane_b32 s4, v63, 52
	s_nop 1
	v_fmac_f32_e32 v62, s4, v131
	v_readlane_b32 s4, v63, 53
	s_nop 1
	v_fmac_f32_e32 v62, s4, v132
	v_readlane_b32 s4, v63, 54
	s_nop 1
	v_fmac_f32_e32 v62, s4, v134
	v_readlane_b32 s4, v63, 55
	s_nop 1
	v_fmac_f32_e32 v62, s4, v135
	v_readlane_b32 s4, v63, 56
	s_nop 1
	v_fmac_f32_e32 v62, s4, v137
	v_readlane_b32 s4, v63, 57
	s_nop 1
	v_fmac_f32_e32 v62, s4, v138
	v_readlane_b32 s4, v63, 58
	s_nop 1
	v_fmac_f32_e32 v62, s4, v136
	v_readlane_b32 s4, v63, 59
	s_nop 1
	v_fmac_f32_e32 v62, s4, v141
	v_readlane_b32 s4, v63, 60
	s_nop 1
	v_fmac_f32_e32 v62, s4, v139
	v_readlane_b32 s4, v63, 61
	s_nop 1
	v_fmac_f32_e32 v62, s4, v140
	v_readlane_b32 s4, v63, 62
	s_nop 1
	v_fmac_f32_e32 v62, s4, v142
	v_readlane_b32 s4, v63, 63
	s_nop 1
	v_fmac_f32_e32 v62, s4, v143
	v_min_f32_e32 v63, 0, v62
	v_mul_f32_e64 v62, |v62|, s0
	v_exp_f32_e32 v62, v62
	s_waitcnt lgkmcnt(3)
	v_readlane_b32 s4, v60, 0
	v_add_f32_e32 v62, 1.0, v62
	v_cmp_gt_f32_e32 vcc, s92, v62
	s_nop 1
	v_cndmask_b32_e64 v64, 0, 32, vcc
	v_ldexp_f32 v62, v62, v64
	v_log_f32_e32 v62, v62
	s_nop 0
	v_mul_f32_e32 v64, 0x3f317217, v62
	v_fma_f32 v64, v62, s3, -v64
	v_fmac_f32_e32 v64, 0x3377d1cf, v62
	v_fmac_f32_e32 v64, 0x3f317217, v62
	v_cmp_lt_f32_e64 s[6:7], |v62|, s96
	s_nop 1
	v_cndmask_b32_e64 v62, v62, v64, s[6:7]
	v_cndmask_b32_e32 v64, 0, v244, vcc
	v_sub_f32_e32 v62, v62, v64
	v_sub_f32_e32 v62, v63, v62
	v_fmamk_f32 v111, v62, 0x3d800000, v110
	v_fma_f32 v62, s4, v99, v144
	v_readlane_b32 s4, v60, 1
	s_nop 1
	v_fmac_f32_e32 v62, s4, v130
	v_readlane_b32 s4, v60, 2
	s_nop 1
	v_fmac_f32_e32 v62, s4, v98
	v_readlane_b32 s4, v60, 3
	s_nop 1
	v_fmac_f32_e32 v62, s4, v133
	v_readlane_b32 s4, v60, 4
	s_nop 1
	v_fmac_f32_e32 v62, s4, v131
	v_readlane_b32 s4, v60, 5
	s_nop 1
	v_fmac_f32_e32 v62, s4, v132
	v_readlane_b32 s4, v60, 6
	s_nop 1
	v_fmac_f32_e32 v62, s4, v134
	v_readlane_b32 s4, v60, 7
	s_nop 1
	v_fmac_f32_e32 v62, s4, v135
	v_readlane_b32 s4, v60, 8
	s_nop 1
	v_fmac_f32_e32 v62, s4, v137
	v_readlane_b32 s4, v60, 9
	s_nop 1
	v_fmac_f32_e32 v62, s4, v138
	v_readlane_b32 s4, v60, 10
	s_nop 1
	v_fmac_f32_e32 v62, s4, v136
	v_readlane_b32 s4, v60, 11
	s_nop 1
	v_fmac_f32_e32 v62, s4, v141
	v_readlane_b32 s4, v60, 12
	s_nop 1
	v_fmac_f32_e32 v62, s4, v139
	v_readlane_b32 s4, v60, 13
	s_nop 1
	v_fmac_f32_e32 v62, s4, v140
	v_readlane_b32 s4, v60, 14
	s_nop 1
	v_fmac_f32_e32 v62, s4, v142
	v_readlane_b32 s4, v60, 15
	s_nop 1
	v_fmac_f32_e32 v62, s4, v143
	v_min_f32_e32 v63, 0, v62
	v_mul_f32_e64 v62, |v62|, s0
	v_exp_f32_e32 v62, v62
	v_readlane_b32 s4, v60, 16
	v_add_f32_e32 v62, 1.0, v62
	v_cmp_gt_f32_e32 vcc, s92, v62
	s_nop 1
	v_cndmask_b32_e64 v64, 0, 32, vcc
	v_ldexp_f32 v62, v62, v64
	v_log_f32_e32 v62, v62
	s_nop 0
	v_mul_f32_e32 v64, 0x3f317217, v62
	v_fma_f32 v64, v62, s3, -v64
	v_fmac_f32_e32 v64, 0x3377d1cf, v62
	v_fmac_f32_e32 v64, 0x3f317217, v62
	v_cmp_lt_f32_e64 s[6:7], |v62|, s96
	s_nop 1
	v_cndmask_b32_e64 v62, v62, v64, s[6:7]
	v_cndmask_b32_e32 v64, 0, v244, vcc
	v_sub_f32_e32 v62, v62, v64
	v_sub_f32_e32 v62, v63, v62
	v_fmamk_f32 v112, v62, 0x3d800000, v111
	v_fma_f32 v62, s4, v99, v144
	v_readlane_b32 s4, v60, 17
	s_nop 1
	v_fmac_f32_e32 v62, s4, v130
	v_readlane_b32 s4, v60, 18
	s_nop 1
	v_fmac_f32_e32 v62, s4, v98
	v_readlane_b32 s4, v60, 19
	s_nop 1
	v_fmac_f32_e32 v62, s4, v133
	v_readlane_b32 s4, v60, 20
	s_nop 1
	v_fmac_f32_e32 v62, s4, v131
	v_readlane_b32 s4, v60, 21
	s_nop 1
	v_fmac_f32_e32 v62, s4, v132
	v_readlane_b32 s4, v60, 22
	s_nop 1
	v_fmac_f32_e32 v62, s4, v134
	v_readlane_b32 s4, v60, 23
	s_nop 1
	v_fmac_f32_e32 v62, s4, v135
	v_readlane_b32 s4, v60, 24
	s_nop 1
	v_fmac_f32_e32 v62, s4, v137
	v_readlane_b32 s4, v60, 25
	s_nop 1
	v_fmac_f32_e32 v62, s4, v138
	v_readlane_b32 s4, v60, 26
	s_nop 1
	v_fmac_f32_e32 v62, s4, v136
	v_readlane_b32 s4, v60, 27
	s_nop 1
	v_fmac_f32_e32 v62, s4, v141
	v_readlane_b32 s4, v60, 28
	s_nop 1
	v_fmac_f32_e32 v62, s4, v139
	v_readlane_b32 s4, v60, 29
	s_nop 1
	v_fmac_f32_e32 v62, s4, v140
	v_readlane_b32 s4, v60, 30
	s_nop 1
	v_fmac_f32_e32 v62, s4, v142
	v_readlane_b32 s4, v60, 31
	s_nop 1
	v_fmac_f32_e32 v62, s4, v143
	v_min_f32_e32 v63, 0, v62
	v_mul_f32_e64 v62, |v62|, s0
	v_exp_f32_e32 v62, v62
	v_readlane_b32 s4, v60, 32
	v_add_f32_e32 v62, 1.0, v62
	v_cmp_gt_f32_e32 vcc, s92, v62
	s_nop 1
	v_cndmask_b32_e64 v64, 0, 32, vcc
	v_ldexp_f32 v62, v62, v64
	v_log_f32_e32 v62, v62
	s_nop 0
	v_mul_f32_e32 v64, 0x3f317217, v62
	v_fma_f32 v64, v62, s3, -v64
	v_fmac_f32_e32 v64, 0x3377d1cf, v62
	v_fmac_f32_e32 v64, 0x3f317217, v62
	v_cmp_lt_f32_e64 s[6:7], |v62|, s96
	s_nop 1
	v_cndmask_b32_e64 v62, v62, v64, s[6:7]
	v_cndmask_b32_e32 v64, 0, v244, vcc
	v_sub_f32_e32 v62, v62, v64
	v_sub_f32_e32 v62, v63, v62
	v_fma_f32 v63, s4, v99, v144
	v_readlane_b32 s4, v60, 33
	v_fmamk_f32 v62, v62, 0x3d800000, v112
	s_nop 0
	v_fmac_f32_e32 v63, s4, v130
	v_readlane_b32 s4, v60, 34
	s_nop 1
	v_fmac_f32_e32 v63, s4, v98
	v_readlane_b32 s4, v60, 35
	s_nop 1
	v_fmac_f32_e32 v63, s4, v133
	v_readlane_b32 s4, v60, 36
	s_nop 1
	v_fmac_f32_e32 v63, s4, v131
	v_readlane_b32 s4, v60, 37
	s_nop 1
	v_fmac_f32_e32 v63, s4, v132
	v_readlane_b32 s4, v60, 38
	s_nop 1
	v_fmac_f32_e32 v63, s4, v134
	v_readlane_b32 s4, v60, 39
	s_nop 1
	v_fmac_f32_e32 v63, s4, v135
	v_readlane_b32 s4, v60, 40
	s_nop 1
	v_fmac_f32_e32 v63, s4, v137
	v_readlane_b32 s4, v60, 41
	s_nop 1
	v_fmac_f32_e32 v63, s4, v138
	v_readlane_b32 s4, v60, 42
	s_nop 1
	v_fmac_f32_e32 v63, s4, v136
	v_readlane_b32 s4, v60, 43
	s_nop 1
	v_fmac_f32_e32 v63, s4, v141
	v_readlane_b32 s4, v60, 44
	s_nop 1
	v_fmac_f32_e32 v63, s4, v139
	v_readlane_b32 s4, v60, 45
	s_nop 1
	v_fmac_f32_e32 v63, s4, v140
	v_readlane_b32 s4, v60, 46
	s_nop 1
	v_fmac_f32_e32 v63, s4, v142
	v_readlane_b32 s4, v60, 47
	s_nop 1
	v_fmac_f32_e32 v63, s4, v143
	v_min_f32_e32 v64, 0, v63
	v_mul_f32_e64 v63, |v63|, s0
	v_exp_f32_e32 v63, v63
	v_readlane_b32 s4, v60, 48
	v_add_f32_e32 v63, 1.0, v63
	v_cmp_gt_f32_e32 vcc, s92, v63
	s_nop 1
	v_cndmask_b32_e64 v65, 0, 32, vcc
	v_ldexp_f32 v63, v63, v65
	v_log_f32_e32 v63, v63
	s_nop 0
	v_mul_f32_e32 v65, 0x3f317217, v63
	v_fma_f32 v65, v63, s3, -v65
	v_fmac_f32_e32 v65, 0x3377d1cf, v63
	v_fmac_f32_e32 v65, 0x3f317217, v63
	v_cmp_lt_f32_e64 s[6:7], |v63|, s96
	s_nop 1
	v_cndmask_b32_e64 v63, v63, v65, s[6:7]
	v_cndmask_b32_e32 v65, 0, v244, vcc
	v_sub_f32_e32 v63, v63, v65
	v_sub_f32_e32 v63, v64, v63
	v_fma_f32 v64, s4, v99, v144
	v_readlane_b32 s4, v60, 49
	v_fmamk_f32 v63, v63, 0x3d800000, v62
	s_nop 0
	v_fmac_f32_e32 v64, s4, v130
	v_readlane_b32 s4, v60, 50
	s_nop 1
	v_fmac_f32_e32 v64, s4, v98
	v_readlane_b32 s4, v60, 51
	s_nop 1
	v_fmac_f32_e32 v64, s4, v133
	v_readlane_b32 s4, v60, 52
	s_nop 1
	v_fmac_f32_e32 v64, s4, v131
	v_readlane_b32 s4, v60, 53
	s_nop 1
	v_fmac_f32_e32 v64, s4, v132
	v_readlane_b32 s4, v60, 54
	s_nop 1
	v_fmac_f32_e32 v64, s4, v134
	v_readlane_b32 s4, v60, 55
	s_nop 1
	v_fmac_f32_e32 v64, s4, v135
	v_readlane_b32 s4, v60, 56
	s_nop 1
	v_fmac_f32_e32 v64, s4, v137
	v_readlane_b32 s4, v60, 57
	s_nop 1
	v_fmac_f32_e32 v64, s4, v138
	v_readlane_b32 s4, v60, 58
	s_nop 1
	v_fmac_f32_e32 v64, s4, v136
	v_readlane_b32 s4, v60, 59
	s_nop 1
	v_fmac_f32_e32 v64, s4, v141
	v_readlane_b32 s4, v60, 60
	s_nop 1
	v_fmac_f32_e32 v64, s4, v139
	v_readlane_b32 s4, v60, 61
	s_nop 1
	v_fmac_f32_e32 v64, s4, v140
	v_readlane_b32 s4, v60, 62
	s_nop 1
	v_fmac_f32_e32 v64, s4, v142
	v_readlane_b32 s4, v60, 63
	s_nop 1
	v_fmac_f32_e32 v64, s4, v143
	v_min_f32_e32 v60, 0, v64
	v_mul_f32_e64 v64, |v64|, s0
	v_exp_f32_e32 v64, v64
	v_readlane_b32 s4, v61, 0
	v_add_f32_e32 v64, 1.0, v64
	v_cmp_gt_f32_e32 vcc, s92, v64
	s_nop 1
	v_cndmask_b32_e64 v65, 0, 32, vcc
	v_ldexp_f32 v64, v64, v65
	v_log_f32_e32 v64, v64
	s_nop 0
	v_mul_f32_e32 v65, 0x3f317217, v64
	v_fma_f32 v65, v64, s3, -v65
	v_fmac_f32_e32 v65, 0x3377d1cf, v64
	v_fmac_f32_e32 v65, 0x3f317217, v64
	v_cmp_lt_f32_e64 s[6:7], |v64|, s96
	s_nop 1
	v_cndmask_b32_e64 v64, v64, v65, s[6:7]
	v_cndmask_b32_e32 v65, 0, v244, vcc
	v_sub_f32_e32 v64, v64, v65
	v_sub_f32_e32 v60, v60, v64
	v_fmamk_f32 v64, v60, 0x3d800000, v63
	v_fma_f32 v60, s4, v99, v144
	v_readlane_b32 s4, v61, 1
	s_nop 1
	v_fmac_f32_e32 v60, s4, v130
	v_readlane_b32 s4, v61, 2
	s_nop 1
	v_fmac_f32_e32 v60, s4, v98
	v_readlane_b32 s4, v61, 3
	s_nop 1
	v_fmac_f32_e32 v60, s4, v133
	v_readlane_b32 s4, v61, 4
	s_nop 1
	v_fmac_f32_e32 v60, s4, v131
	v_readlane_b32 s4, v61, 5
	s_nop 1
	v_fmac_f32_e32 v60, s4, v132
	v_readlane_b32 s4, v61, 6
	s_nop 1
	v_fmac_f32_e32 v60, s4, v134
	v_readlane_b32 s4, v61, 7
	s_nop 1
	v_fmac_f32_e32 v60, s4, v135
	v_readlane_b32 s4, v61, 8
	s_nop 1
	v_fmac_f32_e32 v60, s4, v137
	v_readlane_b32 s4, v61, 9
	s_nop 1
	v_fmac_f32_e32 v60, s4, v138
	v_readlane_b32 s4, v61, 10
	s_nop 1
	v_fmac_f32_e32 v60, s4, v136
	v_readlane_b32 s4, v61, 11
	s_nop 1
	v_fmac_f32_e32 v60, s4, v141
	v_readlane_b32 s4, v61, 12
	s_nop 1
	v_fmac_f32_e32 v60, s4, v139
	v_readlane_b32 s4, v61, 13
	s_nop 1
	v_fmac_f32_e32 v60, s4, v140
	v_readlane_b32 s4, v61, 14
	s_nop 1
	v_fmac_f32_e32 v60, s4, v142
	v_readlane_b32 s4, v61, 15
	s_nop 1
	v_fmac_f32_e32 v60, s4, v143
	v_min_f32_e32 v65, 0, v60
	v_mul_f32_e64 v60, |v60|, s0
	v_exp_f32_e32 v60, v60
	v_readlane_b32 s4, v61, 16
	v_add_f32_e32 v60, 1.0, v60
	v_cmp_gt_f32_e32 vcc, s92, v60
	s_nop 1
	v_cndmask_b32_e64 v66, 0, 32, vcc
	v_ldexp_f32 v60, v60, v66
	v_log_f32_e32 v60, v60
	s_nop 0
	v_mul_f32_e32 v66, 0x3f317217, v60
	v_fma_f32 v66, v60, s3, -v66
	v_fmac_f32_e32 v66, 0x3377d1cf, v60
	v_fmac_f32_e32 v66, 0x3f317217, v60
	v_cmp_lt_f32_e64 s[6:7], |v60|, s96
	s_nop 1
	v_cndmask_b32_e64 v60, v60, v66, s[6:7]
	v_cndmask_b32_e32 v66, 0, v244, vcc
	v_sub_f32_e32 v60, v60, v66
	v_sub_f32_e32 v60, v65, v60
	v_fmamk_f32 v65, v60, 0x3d800000, v64
	v_fma_f32 v60, s4, v99, v144
	v_readlane_b32 s4, v61, 17
	s_nop 1
	v_fmac_f32_e32 v60, s4, v130
	v_readlane_b32 s4, v61, 18
	s_nop 1
	v_fmac_f32_e32 v60, s4, v98
	v_readlane_b32 s4, v61, 19
	s_nop 1
	v_fmac_f32_e32 v60, s4, v133
	v_readlane_b32 s4, v61, 20
	s_nop 1
	v_fmac_f32_e32 v60, s4, v131
	v_readlane_b32 s4, v61, 21
	s_nop 1
	v_fmac_f32_e32 v60, s4, v132
	v_readlane_b32 s4, v61, 22
	s_nop 1
	v_fmac_f32_e32 v60, s4, v134
	v_readlane_b32 s4, v61, 23
	s_nop 1
	v_fmac_f32_e32 v60, s4, v135
	v_readlane_b32 s4, v61, 24
	s_nop 1
	v_fmac_f32_e32 v60, s4, v137
	v_readlane_b32 s4, v61, 25
	s_nop 1
	v_fmac_f32_e32 v60, s4, v138
	v_readlane_b32 s4, v61, 26
	s_nop 1
	v_fmac_f32_e32 v60, s4, v136
	v_readlane_b32 s4, v61, 27
	s_nop 1
	v_fmac_f32_e32 v60, s4, v141
	v_readlane_b32 s4, v61, 28
	s_nop 1
	v_fmac_f32_e32 v60, s4, v139
	v_readlane_b32 s4, v61, 29
	s_nop 1
	v_fmac_f32_e32 v60, s4, v140
	v_readlane_b32 s4, v61, 30
	s_nop 1
	v_fmac_f32_e32 v60, s4, v142
	v_readlane_b32 s4, v61, 31
	s_nop 1
	v_fmac_f32_e32 v60, s4, v143
	v_min_f32_e32 v66, 0, v60
	v_mul_f32_e64 v60, |v60|, s0
	v_exp_f32_e32 v60, v60
	v_readlane_b32 s4, v61, 32
	v_add_f32_e32 v60, 1.0, v60
	v_cmp_gt_f32_e32 vcc, s92, v60
	s_nop 1
	v_cndmask_b32_e64 v67, 0, 32, vcc
	v_ldexp_f32 v60, v60, v67
	v_log_f32_e32 v60, v60
	s_nop 0
	v_mul_f32_e32 v67, 0x3f317217, v60
	v_fma_f32 v67, v60, s3, -v67
	v_fmac_f32_e32 v67, 0x3377d1cf, v60
	v_fmac_f32_e32 v67, 0x3f317217, v60
	v_cmp_lt_f32_e64 s[6:7], |v60|, s96
	s_nop 1
	v_cndmask_b32_e64 v60, v60, v67, s[6:7]
	v_cndmask_b32_e32 v67, 0, v244, vcc
	v_sub_f32_e32 v60, v60, v67
	v_sub_f32_e32 v60, v66, v60
	v_fmamk_f32 v66, v60, 0x3d800000, v65
	v_fma_f32 v60, s4, v99, v144
	v_readlane_b32 s4, v61, 33
	s_nop 1
	v_fmac_f32_e32 v60, s4, v130
	v_readlane_b32 s4, v61, 34
	s_nop 1
	v_fmac_f32_e32 v60, s4, v98
	v_readlane_b32 s4, v61, 35
	s_nop 1
	v_fmac_f32_e32 v60, s4, v133
	v_readlane_b32 s4, v61, 36
	s_nop 1
	v_fmac_f32_e32 v60, s4, v131
	v_readlane_b32 s4, v61, 37
	s_nop 1
	v_fmac_f32_e32 v60, s4, v132
	v_readlane_b32 s4, v61, 38
	s_nop 1
	v_fmac_f32_e32 v60, s4, v134
	v_readlane_b32 s4, v61, 39
	s_nop 1
	v_fmac_f32_e32 v60, s4, v135
	v_readlane_b32 s4, v61, 40
	s_nop 1
	v_fmac_f32_e32 v60, s4, v137
	v_readlane_b32 s4, v61, 41
	s_nop 1
	v_fmac_f32_e32 v60, s4, v138
	v_readlane_b32 s4, v61, 42
	s_nop 1
	v_fmac_f32_e32 v60, s4, v136
	v_readlane_b32 s4, v61, 43
	s_nop 1
	v_fmac_f32_e32 v60, s4, v141
	v_readlane_b32 s4, v61, 44
	s_nop 1
	v_fmac_f32_e32 v60, s4, v139
	v_readlane_b32 s4, v61, 45
	s_nop 1
	v_fmac_f32_e32 v60, s4, v140
	v_readlane_b32 s4, v61, 46
	s_nop 1
	v_fmac_f32_e32 v60, s4, v142
	v_readlane_b32 s4, v61, 47
	s_nop 1
	v_fmac_f32_e32 v60, s4, v143
	v_min_f32_e32 v67, 0, v60
	v_mul_f32_e64 v60, |v60|, s0
	v_exp_f32_e32 v60, v60
	v_readlane_b32 s4, v61, 48
	v_add_f32_e32 v60, 1.0, v60
	v_cmp_gt_f32_e32 vcc, s92, v60
	s_nop 1
	v_cndmask_b32_e64 v68, 0, 32, vcc
	v_ldexp_f32 v60, v60, v68
	v_log_f32_e32 v60, v60
	s_nop 0
	v_mul_f32_e32 v68, 0x3f317217, v60
	v_fma_f32 v68, v60, s3, -v68
	v_fmac_f32_e32 v68, 0x3377d1cf, v60
	v_fmac_f32_e32 v68, 0x3f317217, v60
	v_cmp_lt_f32_e64 s[6:7], |v60|, s96
	s_nop 1
	v_cndmask_b32_e64 v60, v60, v68, s[6:7]
	v_cndmask_b32_e32 v68, 0, v244, vcc
	v_sub_f32_e32 v60, v60, v68
	v_sub_f32_e32 v60, v67, v60
	v_fmamk_f32 v67, v60, 0x3d800000, v66
	v_fma_f32 v60, s4, v99, v144
	v_readlane_b32 s4, v61, 49
	s_nop 1
	v_fmac_f32_e32 v60, s4, v130
	v_readlane_b32 s4, v61, 50
	s_nop 1
	v_fmac_f32_e32 v60, s4, v98
	v_readlane_b32 s4, v61, 51
	s_nop 1
	v_fmac_f32_e32 v60, s4, v133
	v_readlane_b32 s4, v61, 52
	s_nop 1
	v_fmac_f32_e32 v60, s4, v131
	v_readlane_b32 s4, v61, 53
	s_nop 1
	v_fmac_f32_e32 v60, s4, v132
	v_readlane_b32 s4, v61, 54
	s_nop 1
	v_fmac_f32_e32 v60, s4, v134
	v_readlane_b32 s4, v61, 55
	s_nop 1
	v_fmac_f32_e32 v60, s4, v135
	v_readlane_b32 s4, v61, 56
	s_nop 1
	v_fmac_f32_e32 v60, s4, v137
	v_readlane_b32 s4, v61, 57
	s_nop 1
	v_fmac_f32_e32 v60, s4, v138
	v_readlane_b32 s4, v61, 58
	s_nop 1
	v_fmac_f32_e32 v60, s4, v136
	v_readlane_b32 s4, v61, 59
	s_nop 1
	v_fmac_f32_e32 v60, s4, v141
	v_readlane_b32 s4, v61, 60
	s_nop 1
	v_fmac_f32_e32 v60, s4, v139
	v_readlane_b32 s4, v61, 61
	s_nop 1
	v_fmac_f32_e32 v60, s4, v140
	v_readlane_b32 s4, v61, 62
	s_nop 1
	v_fmac_f32_e32 v60, s4, v142
	v_readlane_b32 s4, v61, 63
	s_nop 1
	v_fmac_f32_e32 v60, s4, v143
	v_min_f32_e32 v61, 0, v60
	v_mul_f32_e64 v60, |v60|, s0
	v_exp_f32_e32 v60, v60
	s_waitcnt lgkmcnt(2)
	v_readlane_b32 s4, v58, 0
	v_add_f32_e32 v60, 1.0, v60
	v_cmp_gt_f32_e32 vcc, s92, v60
	s_nop 1
	v_cndmask_b32_e64 v68, 0, 32, vcc
	v_ldexp_f32 v60, v60, v68
	v_log_f32_e32 v60, v60
	s_nop 0
	v_mul_f32_e32 v68, 0x3f317217, v60
	v_fma_f32 v68, v60, s3, -v68
	v_fmac_f32_e32 v68, 0x3377d1cf, v60
	v_fmac_f32_e32 v68, 0x3f317217, v60
	v_cmp_lt_f32_e64 s[6:7], |v60|, s96
	s_nop 1
	v_cndmask_b32_e64 v60, v60, v68, s[6:7]
	v_cndmask_b32_e32 v68, 0, v244, vcc
	v_sub_f32_e32 v60, v60, v68
	v_sub_f32_e32 v60, v61, v60
	v_fmamk_f32 v61, v60, 0x3d800000, v67
	v_fma_f32 v60, s4, v99, v144
	v_readlane_b32 s4, v58, 1
	s_nop 1
	v_fmac_f32_e32 v60, s4, v130
	v_readlane_b32 s4, v58, 2
	s_nop 1
	v_fmac_f32_e32 v60, s4, v98
	v_readlane_b32 s4, v58, 3
	s_nop 1
	v_fmac_f32_e32 v60, s4, v133
	v_readlane_b32 s4, v58, 4
	s_nop 1
	v_fmac_f32_e32 v60, s4, v131
	v_readlane_b32 s4, v58, 5
	s_nop 1
	v_fmac_f32_e32 v60, s4, v132
	v_readlane_b32 s4, v58, 6
	s_nop 1
	v_fmac_f32_e32 v60, s4, v134
	v_readlane_b32 s4, v58, 7
	s_nop 1
	v_fmac_f32_e32 v60, s4, v135
	v_readlane_b32 s4, v58, 8
	s_nop 1
	v_fmac_f32_e32 v60, s4, v137
	v_readlane_b32 s4, v58, 9
	s_nop 1
	v_fmac_f32_e32 v60, s4, v138
	v_readlane_b32 s4, v58, 10
	s_nop 1
	v_fmac_f32_e32 v60, s4, v136
	v_readlane_b32 s4, v58, 11
	s_nop 1
	v_fmac_f32_e32 v60, s4, v141
	v_readlane_b32 s4, v58, 12
	s_nop 1
	v_fmac_f32_e32 v60, s4, v139
	v_readlane_b32 s4, v58, 13
	s_nop 1
	v_fmac_f32_e32 v60, s4, v140
	v_readlane_b32 s4, v58, 14
	s_nop 1
	v_fmac_f32_e32 v60, s4, v142
	v_readlane_b32 s4, v58, 15
	s_nop 1
	v_fmac_f32_e32 v60, s4, v143
	v_min_f32_e32 v68, 0, v60
	v_mul_f32_e64 v60, |v60|, s0
	v_exp_f32_e32 v60, v60
	v_readlane_b32 s4, v58, 16
	v_add_f32_e32 v60, 1.0, v60
	v_cmp_gt_f32_e32 vcc, s92, v60
	s_nop 1
	v_cndmask_b32_e64 v69, 0, 32, vcc
	v_ldexp_f32 v60, v60, v69
	v_log_f32_e32 v60, v60
	s_nop 0
	v_mul_f32_e32 v69, 0x3f317217, v60
	v_fma_f32 v69, v60, s3, -v69
	v_fmac_f32_e32 v69, 0x3377d1cf, v60
	v_fmac_f32_e32 v69, 0x3f317217, v60
	v_cmp_lt_f32_e64 s[6:7], |v60|, s96
	s_nop 1
	v_cndmask_b32_e64 v60, v60, v69, s[6:7]
	v_cndmask_b32_e32 v69, 0, v244, vcc
	v_sub_f32_e32 v60, v60, v69
	v_sub_f32_e32 v60, v68, v60
	v_fmamk_f32 v68, v60, 0x3d800000, v61
	v_fma_f32 v60, s4, v99, v144
	v_readlane_b32 s4, v58, 17
	s_nop 1
	v_fmac_f32_e32 v60, s4, v130
	v_readlane_b32 s4, v58, 18
	s_nop 1
	v_fmac_f32_e32 v60, s4, v98
	v_readlane_b32 s4, v58, 19
	s_nop 1
	v_fmac_f32_e32 v60, s4, v133
	v_readlane_b32 s4, v58, 20
	s_nop 1
	v_fmac_f32_e32 v60, s4, v131
	v_readlane_b32 s4, v58, 21
	s_nop 1
	v_fmac_f32_e32 v60, s4, v132
	v_readlane_b32 s4, v58, 22
	s_nop 1
	v_fmac_f32_e32 v60, s4, v134
	v_readlane_b32 s4, v58, 23
	s_nop 1
	v_fmac_f32_e32 v60, s4, v135
	v_readlane_b32 s4, v58, 24
	s_nop 1
	v_fmac_f32_e32 v60, s4, v137
	v_readlane_b32 s4, v58, 25
	s_nop 1
	v_fmac_f32_e32 v60, s4, v138
	v_readlane_b32 s4, v58, 26
	s_nop 1
	v_fmac_f32_e32 v60, s4, v136
	v_readlane_b32 s4, v58, 27
	s_nop 1
	v_fmac_f32_e32 v60, s4, v141
	v_readlane_b32 s4, v58, 28
	s_nop 1
	v_fmac_f32_e32 v60, s4, v139
	v_readlane_b32 s4, v58, 29
	s_nop 1
	v_fmac_f32_e32 v60, s4, v140
	v_readlane_b32 s4, v58, 30
	s_nop 1
	v_fmac_f32_e32 v60, s4, v142
	v_readlane_b32 s4, v58, 31
	s_nop 1
	v_fmac_f32_e32 v60, s4, v143
	v_min_f32_e32 v69, 0, v60
	v_mul_f32_e64 v60, |v60|, s0
	v_exp_f32_e32 v60, v60
	v_readlane_b32 s4, v58, 32
	v_add_f32_e32 v60, 1.0, v60
	v_cmp_gt_f32_e32 vcc, s92, v60
	s_nop 1
	v_cndmask_b32_e64 v73, 0, 32, vcc
	v_ldexp_f32 v60, v60, v73
	v_log_f32_e32 v60, v60
	s_nop 0
	v_mul_f32_e32 v73, 0x3f317217, v60
	v_fma_f32 v73, v60, s3, -v73
	v_fmac_f32_e32 v73, 0x3377d1cf, v60
	v_fmac_f32_e32 v73, 0x3f317217, v60
	v_cmp_lt_f32_e64 s[6:7], |v60|, s96
	s_nop 1
	v_cndmask_b32_e64 v60, v60, v73, s[6:7]
	v_cndmask_b32_e32 v73, 0, v244, vcc
	v_sub_f32_e32 v60, v60, v73
	v_sub_f32_e32 v60, v69, v60
	v_fmamk_f32 v69, v60, 0x3d800000, v68
	v_fma_f32 v60, s4, v99, v144
	v_readlane_b32 s4, v58, 33
	s_nop 1
	v_fmac_f32_e32 v60, s4, v130
	v_readlane_b32 s4, v58, 34
	s_nop 1
	v_fmac_f32_e32 v60, s4, v98
	v_readlane_b32 s4, v58, 35
	s_nop 1
	v_fmac_f32_e32 v60, s4, v133
	v_readlane_b32 s4, v58, 36
	s_nop 1
	v_fmac_f32_e32 v60, s4, v131
	v_readlane_b32 s4, v58, 37
	s_nop 1
	v_fmac_f32_e32 v60, s4, v132
	v_readlane_b32 s4, v58, 38
	s_nop 1
	v_fmac_f32_e32 v60, s4, v134
	v_readlane_b32 s4, v58, 39
	s_nop 1
	v_fmac_f32_e32 v60, s4, v135
	v_readlane_b32 s4, v58, 40
	s_nop 1
	v_fmac_f32_e32 v60, s4, v137
	v_readlane_b32 s4, v58, 41
	s_nop 1
	v_fmac_f32_e32 v60, s4, v138
	v_readlane_b32 s4, v58, 42
	s_nop 1
	v_fmac_f32_e32 v60, s4, v136
	v_readlane_b32 s4, v58, 43
	s_nop 1
	v_fmac_f32_e32 v60, s4, v141
	v_readlane_b32 s4, v58, 44
	s_nop 1
	v_fmac_f32_e32 v60, s4, v139
	v_readlane_b32 s4, v58, 45
	s_nop 1
	v_fmac_f32_e32 v60, s4, v140
	v_readlane_b32 s4, v58, 46
	s_nop 1
	v_fmac_f32_e32 v60, s4, v142
	v_readlane_b32 s4, v58, 47
	s_nop 1
	v_fmac_f32_e32 v60, s4, v143
	v_min_f32_e32 v73, 0, v60
	v_mul_f32_e64 v60, |v60|, s0
	v_exp_f32_e32 v60, v60
	v_readlane_b32 s4, v58, 48
	v_add_f32_e32 v60, 1.0, v60
	v_cmp_gt_f32_e32 vcc, s92, v60
	s_nop 1
	v_cndmask_b32_e64 v74, 0, 32, vcc
	v_ldexp_f32 v60, v60, v74
	v_log_f32_e32 v60, v60
	s_nop 0
	v_mul_f32_e32 v74, 0x3f317217, v60
	v_fma_f32 v74, v60, s3, -v74
	v_fmac_f32_e32 v74, 0x3377d1cf, v60
	v_fmac_f32_e32 v74, 0x3f317217, v60
	v_cmp_lt_f32_e64 s[6:7], |v60|, s96
	s_nop 1
	v_cndmask_b32_e64 v60, v60, v74, s[6:7]
	v_cndmask_b32_e32 v74, 0, v244, vcc
	v_sub_f32_e32 v60, v60, v74
	v_sub_f32_e32 v60, v73, v60
	v_fmamk_f32 v73, v60, 0x3d800000, v69
	v_fma_f32 v60, s4, v99, v144
	v_readlane_b32 s4, v58, 49
	s_nop 1
	v_fmac_f32_e32 v60, s4, v130
	v_readlane_b32 s4, v58, 50
	s_nop 1
	v_fmac_f32_e32 v60, s4, v98
	v_readlane_b32 s4, v58, 51
	s_nop 1
	v_fmac_f32_e32 v60, s4, v133
	v_readlane_b32 s4, v58, 52
	s_nop 1
	v_fmac_f32_e32 v60, s4, v131
	v_readlane_b32 s4, v58, 53
	s_nop 1
	v_fmac_f32_e32 v60, s4, v132
	v_readlane_b32 s4, v58, 54
	s_nop 1
	v_fmac_f32_e32 v60, s4, v134
	v_readlane_b32 s4, v58, 55
	s_nop 1
	v_fmac_f32_e32 v60, s4, v135
	v_readlane_b32 s4, v58, 56
	s_nop 1
	v_fmac_f32_e32 v60, s4, v137
	v_readlane_b32 s4, v58, 57
	s_nop 1
	v_fmac_f32_e32 v60, s4, v138
	v_readlane_b32 s4, v58, 58
	s_nop 1
	v_fmac_f32_e32 v60, s4, v136
	v_readlane_b32 s4, v58, 59
	s_nop 1
	v_fmac_f32_e32 v60, s4, v141
	v_readlane_b32 s4, v58, 60
	s_nop 1
	v_fmac_f32_e32 v60, s4, v139
	v_readlane_b32 s4, v58, 61
	s_nop 1
	v_fmac_f32_e32 v60, s4, v140
	v_readlane_b32 s4, v58, 62
	s_nop 1
	v_fmac_f32_e32 v60, s4, v142
	v_readlane_b32 s4, v58, 63
	s_nop 1
	v_fmac_f32_e32 v60, s4, v143
	v_min_f32_e32 v58, 0, v60
	v_mul_f32_e64 v60, |v60|, s0
	v_exp_f32_e32 v60, v60
	v_readlane_b32 s4, v59, 0
	v_add_f32_e32 v60, 1.0, v60
	v_cmp_gt_f32_e32 vcc, s92, v60
	s_nop 1
	v_cndmask_b32_e64 v74, 0, 32, vcc
	v_ldexp_f32 v60, v60, v74
	v_log_f32_e32 v60, v60
	s_nop 0
	v_mul_f32_e32 v74, 0x3f317217, v60
	v_fma_f32 v74, v60, s3, -v74
	v_fmac_f32_e32 v74, 0x3377d1cf, v60
	v_fmac_f32_e32 v74, 0x3f317217, v60
	v_cmp_lt_f32_e64 s[6:7], |v60|, s96
	s_nop 1
	v_cndmask_b32_e64 v60, v60, v74, s[6:7]
	v_cndmask_b32_e32 v74, 0, v244, vcc
	v_sub_f32_e32 v60, v60, v74
	v_sub_f32_e32 v58, v58, v60
	v_fmamk_f32 v74, v58, 0x3d800000, v73
	v_fma_f32 v58, s4, v99, v144
	v_readlane_b32 s4, v59, 1
	s_nop 1
	v_fmac_f32_e32 v58, s4, v130
	v_readlane_b32 s4, v59, 2
	s_nop 1
	v_fmac_f32_e32 v58, s4, v98
	v_readlane_b32 s4, v59, 3
	s_nop 1
	v_fmac_f32_e32 v58, s4, v133
	v_readlane_b32 s4, v59, 4
	s_nop 1
	v_fmac_f32_e32 v58, s4, v131
	v_readlane_b32 s4, v59, 5
	s_nop 1
	v_fmac_f32_e32 v58, s4, v132
	v_readlane_b32 s4, v59, 6
	s_nop 1
	v_fmac_f32_e32 v58, s4, v134
	v_readlane_b32 s4, v59, 7
	s_nop 1
	v_fmac_f32_e32 v58, s4, v135
	v_readlane_b32 s4, v59, 8
	s_nop 1
	v_fmac_f32_e32 v58, s4, v137
	v_readlane_b32 s4, v59, 9
	s_nop 1
	v_fmac_f32_e32 v58, s4, v138
	v_readlane_b32 s4, v59, 10
	s_nop 1
	v_fmac_f32_e32 v58, s4, v136
	v_readlane_b32 s4, v59, 11
	s_nop 1
	v_fmac_f32_e32 v58, s4, v141
	v_readlane_b32 s4, v59, 12
	s_nop 1
	v_fmac_f32_e32 v58, s4, v139
	v_readlane_b32 s4, v59, 13
	s_nop 1
	v_fmac_f32_e32 v58, s4, v140
	v_readlane_b32 s4, v59, 14
	s_nop 1
	v_fmac_f32_e32 v58, s4, v142
	v_readlane_b32 s4, v59, 15
	s_nop 1
	v_fmac_f32_e32 v58, s4, v143
	v_min_f32_e32 v60, 0, v58
	v_mul_f32_e64 v58, |v58|, s0
	v_exp_f32_e32 v58, v58
	v_readlane_b32 s4, v59, 16
	v_add_f32_e32 v58, 1.0, v58
	v_cmp_gt_f32_e32 vcc, s92, v58
	s_nop 1
	v_cndmask_b32_e64 v75, 0, 32, vcc
	v_ldexp_f32 v58, v58, v75
	v_log_f32_e32 v58, v58
	s_nop 0
	v_mul_f32_e32 v75, 0x3f317217, v58
	v_fma_f32 v75, v58, s3, -v75
	v_fmac_f32_e32 v75, 0x3377d1cf, v58
	v_fmac_f32_e32 v75, 0x3f317217, v58
	v_cmp_lt_f32_e64 s[6:7], |v58|, s96
	s_nop 1
	v_cndmask_b32_e64 v58, v58, v75, s[6:7]
	v_cndmask_b32_e32 v75, 0, v244, vcc
	v_sub_f32_e32 v58, v58, v75
	v_sub_f32_e32 v58, v60, v58
	v_fmamk_f32 v75, v58, 0x3d800000, v74
	v_fma_f32 v58, s4, v99, v144
	v_readlane_b32 s4, v59, 17
	s_nop 1
	v_fmac_f32_e32 v58, s4, v130
	v_readlane_b32 s4, v59, 18
	s_nop 1
	v_fmac_f32_e32 v58, s4, v98
	v_readlane_b32 s4, v59, 19
	s_nop 1
	v_fmac_f32_e32 v58, s4, v133
	v_readlane_b32 s4, v59, 20
	s_nop 1
	v_fmac_f32_e32 v58, s4, v131
	v_readlane_b32 s4, v59, 21
	s_nop 1
	v_fmac_f32_e32 v58, s4, v132
	v_readlane_b32 s4, v59, 22
	s_nop 1
	v_fmac_f32_e32 v58, s4, v134
	v_readlane_b32 s4, v59, 23
	s_nop 1
	v_fmac_f32_e32 v58, s4, v135
	v_readlane_b32 s4, v59, 24
	s_nop 1
	v_fmac_f32_e32 v58, s4, v137
	v_readlane_b32 s4, v59, 25
	s_nop 1
	v_fmac_f32_e32 v58, s4, v138
	v_readlane_b32 s4, v59, 26
	s_nop 1
	v_fmac_f32_e32 v58, s4, v136
	v_readlane_b32 s4, v59, 27
	s_nop 1
	v_fmac_f32_e32 v58, s4, v141
	v_readlane_b32 s4, v59, 28
	s_nop 1
	v_fmac_f32_e32 v58, s4, v139
	v_readlane_b32 s4, v59, 29
	s_nop 1
	v_fmac_f32_e32 v58, s4, v140
	v_readlane_b32 s4, v59, 30
	s_nop 1
	v_fmac_f32_e32 v58, s4, v142
	v_readlane_b32 s4, v59, 31
	s_nop 1
	v_fmac_f32_e32 v58, s4, v143
	v_min_f32_e32 v60, 0, v58
	v_mul_f32_e64 v58, |v58|, s0
	v_exp_f32_e32 v58, v58
	v_readlane_b32 s4, v59, 32
	v_add_f32_e32 v58, 1.0, v58
	v_cmp_gt_f32_e32 vcc, s92, v58
	s_nop 1
	v_cndmask_b32_e64 v76, 0, 32, vcc
	v_ldexp_f32 v58, v58, v76
	v_log_f32_e32 v58, v58
	s_nop 0
	v_mul_f32_e32 v76, 0x3f317217, v58
	v_fma_f32 v76, v58, s3, -v76
	v_fmac_f32_e32 v76, 0x3377d1cf, v58
	v_fmac_f32_e32 v76, 0x3f317217, v58
	v_cmp_lt_f32_e64 s[6:7], |v58|, s96
	s_nop 1
	v_cndmask_b32_e64 v58, v58, v76, s[6:7]
	v_cndmask_b32_e32 v76, 0, v244, vcc
	v_sub_f32_e32 v58, v58, v76
	v_sub_f32_e32 v58, v60, v58
	v_fmamk_f32 v76, v58, 0x3d800000, v75
	v_fma_f32 v58, s4, v99, v144
	v_readlane_b32 s4, v59, 33
	s_nop 1
	v_fmac_f32_e32 v58, s4, v130
	v_readlane_b32 s4, v59, 34
	s_nop 1
	v_fmac_f32_e32 v58, s4, v98
	v_readlane_b32 s4, v59, 35
	s_nop 1
	v_fmac_f32_e32 v58, s4, v133
	v_readlane_b32 s4, v59, 36
	s_nop 1
	v_fmac_f32_e32 v58, s4, v131
	v_readlane_b32 s4, v59, 37
	s_nop 1
	v_fmac_f32_e32 v58, s4, v132
	v_readlane_b32 s4, v59, 38
	s_nop 1
	v_fmac_f32_e32 v58, s4, v134
	v_readlane_b32 s4, v59, 39
	s_nop 1
	v_fmac_f32_e32 v58, s4, v135
	v_readlane_b32 s4, v59, 40
	s_nop 1
	v_fmac_f32_e32 v58, s4, v137
	v_readlane_b32 s4, v59, 41
	s_nop 1
	v_fmac_f32_e32 v58, s4, v138
	v_readlane_b32 s4, v59, 42
	s_nop 1
	v_fmac_f32_e32 v58, s4, v136
	v_readlane_b32 s4, v59, 43
	s_nop 1
	v_fmac_f32_e32 v58, s4, v141
	v_readlane_b32 s4, v59, 44
	s_nop 1
	v_fmac_f32_e32 v58, s4, v139
	v_readlane_b32 s4, v59, 45
	s_nop 1
	v_fmac_f32_e32 v58, s4, v140
	v_readlane_b32 s4, v59, 46
	s_nop 1
	v_fmac_f32_e32 v58, s4, v142
	v_readlane_b32 s4, v59, 47
	s_nop 1
	v_fmac_f32_e32 v58, s4, v143
	v_min_f32_e32 v60, 0, v58
	v_mul_f32_e64 v58, |v58|, s0
	v_exp_f32_e32 v58, v58
	v_readlane_b32 s4, v59, 48
	v_add_f32_e32 v58, 1.0, v58
	v_cmp_gt_f32_e32 vcc, s92, v58
	s_nop 1
	v_cndmask_b32_e64 v77, 0, 32, vcc
	v_ldexp_f32 v58, v58, v77
	v_log_f32_e32 v58, v58
	s_nop 0
	v_mul_f32_e32 v77, 0x3f317217, v58
	v_fma_f32 v77, v58, s3, -v77
	v_fmac_f32_e32 v77, 0x3377d1cf, v58
	v_fmac_f32_e32 v77, 0x3f317217, v58
	v_cmp_lt_f32_e64 s[6:7], |v58|, s96
	s_nop 1
	v_cndmask_b32_e64 v58, v58, v77, s[6:7]
	v_cndmask_b32_e32 v77, 0, v244, vcc
	v_sub_f32_e32 v58, v58, v77
	v_sub_f32_e32 v58, v60, v58
	v_fmamk_f32 v77, v58, 0x3d800000, v76
	v_fma_f32 v58, s4, v99, v144
	v_readlane_b32 s4, v59, 49
	s_nop 1
	v_fmac_f32_e32 v58, s4, v130
	v_readlane_b32 s4, v59, 50
	s_nop 1
	v_fmac_f32_e32 v58, s4, v98
	v_readlane_b32 s4, v59, 51
	s_nop 1
	v_fmac_f32_e32 v58, s4, v133
	v_readlane_b32 s4, v59, 52
	s_nop 1
	v_fmac_f32_e32 v58, s4, v131
	v_readlane_b32 s4, v59, 53
	s_nop 1
	v_fmac_f32_e32 v58, s4, v132
	v_readlane_b32 s4, v59, 54
	s_nop 1
	v_fmac_f32_e32 v58, s4, v134
	v_readlane_b32 s4, v59, 55
	s_nop 1
	v_fmac_f32_e32 v58, s4, v135
	v_readlane_b32 s4, v59, 56
	s_nop 1
	v_fmac_f32_e32 v58, s4, v137
	v_readlane_b32 s4, v59, 57
	s_nop 1
	v_fmac_f32_e32 v58, s4, v138
	v_readlane_b32 s4, v59, 58
	s_nop 1
	v_fmac_f32_e32 v58, s4, v136
	v_readlane_b32 s4, v59, 59
	s_nop 1
	v_fmac_f32_e32 v58, s4, v141
	v_readlane_b32 s4, v59, 60
	s_nop 1
	v_fmac_f32_e32 v58, s4, v139
	v_readlane_b32 s4, v59, 61
	s_nop 1
	v_fmac_f32_e32 v58, s4, v140
	v_readlane_b32 s4, v59, 62
	s_nop 1
	v_fmac_f32_e32 v58, s4, v142
	v_readlane_b32 s4, v59, 63
	s_nop 1
	v_fmac_f32_e32 v58, s4, v143
	v_min_f32_e32 v59, 0, v58
	v_mul_f32_e64 v58, |v58|, s0
	v_exp_f32_e32 v58, v58
	s_waitcnt lgkmcnt(1)
	v_readlane_b32 s4, v56, 0
	v_add_f32_e32 v58, 1.0, v58
	v_cmp_gt_f32_e32 vcc, s92, v58
	s_nop 1
	v_cndmask_b32_e64 v60, 0, 32, vcc
	v_ldexp_f32 v58, v58, v60
	v_log_f32_e32 v58, v58
	s_nop 0
	v_mul_f32_e32 v60, 0x3f317217, v58
	v_fma_f32 v60, v58, s3, -v60
	v_fmac_f32_e32 v60, 0x3377d1cf, v58
	v_fmac_f32_e32 v60, 0x3f317217, v58
	v_cmp_lt_f32_e64 s[6:7], |v58|, s96
	s_nop 1
	v_cndmask_b32_e64 v58, v58, v60, s[6:7]
	v_cndmask_b32_e32 v60, 0, v244, vcc
	v_sub_f32_e32 v58, v58, v60
	v_sub_f32_e32 v58, v59, v58
	v_fmamk_f32 v78, v58, 0x3d800000, v77
	v_fma_f32 v58, s4, v99, v144
	v_readlane_b32 s4, v56, 1
	s_nop 1
	v_fmac_f32_e32 v58, s4, v130
	v_readlane_b32 s4, v56, 2
	s_nop 1
	v_fmac_f32_e32 v58, s4, v98
	v_readlane_b32 s4, v56, 3
	s_nop 1
	v_fmac_f32_e32 v58, s4, v133
	v_readlane_b32 s4, v56, 4
	s_nop 1
	v_fmac_f32_e32 v58, s4, v131
	v_readlane_b32 s4, v56, 5
	s_nop 1
	v_fmac_f32_e32 v58, s4, v132
	v_readlane_b32 s4, v56, 6
	s_nop 1
	v_fmac_f32_e32 v58, s4, v134
	v_readlane_b32 s4, v56, 7
	s_nop 1
	v_fmac_f32_e32 v58, s4, v135
	v_readlane_b32 s4, v56, 8
	s_nop 1
	v_fmac_f32_e32 v58, s4, v137
	v_readlane_b32 s4, v56, 9
	s_nop 1
	v_fmac_f32_e32 v58, s4, v138
	v_readlane_b32 s4, v56, 10
	s_nop 1
	v_fmac_f32_e32 v58, s4, v136
	v_readlane_b32 s4, v56, 11
	s_nop 1
	v_fmac_f32_e32 v58, s4, v141
	v_readlane_b32 s4, v56, 12
	s_nop 1
	v_fmac_f32_e32 v58, s4, v139
	v_readlane_b32 s4, v56, 13
	s_nop 1
	v_fmac_f32_e32 v58, s4, v140
	v_readlane_b32 s4, v56, 14
	s_nop 1
	v_fmac_f32_e32 v58, s4, v142
	v_readlane_b32 s4, v56, 15
	s_nop 1
	v_fmac_f32_e32 v58, s4, v143
	v_min_f32_e32 v59, 0, v58
	v_mul_f32_e64 v58, |v58|, s0
	v_exp_f32_e32 v58, v58
	v_readlane_b32 s4, v56, 16
	v_add_f32_e32 v58, 1.0, v58
	v_cmp_gt_f32_e32 vcc, s92, v58
	s_nop 1
	v_cndmask_b32_e64 v60, 0, 32, vcc
	v_ldexp_f32 v58, v58, v60
	v_log_f32_e32 v58, v58
	s_nop 0
	v_mul_f32_e32 v60, 0x3f317217, v58
	v_fma_f32 v60, v58, s3, -v60
	v_fmac_f32_e32 v60, 0x3377d1cf, v58
	v_fmac_f32_e32 v60, 0x3f317217, v58
	v_cmp_lt_f32_e64 s[6:7], |v58|, s96
	s_nop 1
	v_cndmask_b32_e64 v58, v58, v60, s[6:7]
	v_cndmask_b32_e32 v60, 0, v244, vcc
	v_sub_f32_e32 v58, v58, v60
	v_sub_f32_e32 v58, v59, v58
	v_fmamk_f32 v79, v58, 0x3d800000, v78
	v_fma_f32 v58, s4, v99, v144
	v_readlane_b32 s4, v56, 17
	s_nop 1
	v_fmac_f32_e32 v58, s4, v130
	v_readlane_b32 s4, v56, 18
	s_nop 1
	v_fmac_f32_e32 v58, s4, v98
	v_readlane_b32 s4, v56, 19
	s_nop 1
	v_fmac_f32_e32 v58, s4, v133
	v_readlane_b32 s4, v56, 20
	s_nop 1
	v_fmac_f32_e32 v58, s4, v131
	v_readlane_b32 s4, v56, 21
	s_nop 1
	v_fmac_f32_e32 v58, s4, v132
	v_readlane_b32 s4, v56, 22
	s_nop 1
	v_fmac_f32_e32 v58, s4, v134
	v_readlane_b32 s4, v56, 23
	s_nop 1
	v_fmac_f32_e32 v58, s4, v135
	v_readlane_b32 s4, v56, 24
	s_nop 1
	v_fmac_f32_e32 v58, s4, v137
	v_readlane_b32 s4, v56, 25
	s_nop 1
	v_fmac_f32_e32 v58, s4, v138
	v_readlane_b32 s4, v56, 26
	s_nop 1
	v_fmac_f32_e32 v58, s4, v136
	v_readlane_b32 s4, v56, 27
	s_nop 1
	v_fmac_f32_e32 v58, s4, v141
	v_readlane_b32 s4, v56, 28
	s_nop 1
	v_fmac_f32_e32 v58, s4, v139
	v_readlane_b32 s4, v56, 29
	s_nop 1
	v_fmac_f32_e32 v58, s4, v140
	v_readlane_b32 s4, v56, 30
	s_nop 1
	v_fmac_f32_e32 v58, s4, v142
	v_readlane_b32 s4, v56, 31
	s_nop 1
	v_fmac_f32_e32 v58, s4, v143
	v_min_f32_e32 v59, 0, v58
	v_mul_f32_e64 v58, |v58|, s0
	v_exp_f32_e32 v58, v58
	v_readlane_b32 s4, v56, 32
	v_add_f32_e32 v58, 1.0, v58
	v_cmp_gt_f32_e32 vcc, s92, v58
	s_nop 1
	v_cndmask_b32_e64 v60, 0, 32, vcc
	v_ldexp_f32 v58, v58, v60
	v_log_f32_e32 v58, v58
	s_nop 0
	v_mul_f32_e32 v60, 0x3f317217, v58
	v_fma_f32 v60, v58, s3, -v60
	v_fmac_f32_e32 v60, 0x3377d1cf, v58
	v_fmac_f32_e32 v60, 0x3f317217, v58
	v_cmp_lt_f32_e64 s[6:7], |v58|, s96
	s_nop 1
	v_cndmask_b32_e64 v58, v58, v60, s[6:7]
	v_cndmask_b32_e32 v60, 0, v244, vcc
	v_sub_f32_e32 v58, v58, v60
	v_sub_f32_e32 v58, v59, v58
	v_fmamk_f32 v80, v58, 0x3d800000, v79
	v_fma_f32 v58, s4, v99, v144
	v_readlane_b32 s4, v56, 33
	s_nop 1
	v_fmac_f32_e32 v58, s4, v130
	v_readlane_b32 s4, v56, 34
	s_nop 1
	v_fmac_f32_e32 v58, s4, v98
	v_readlane_b32 s4, v56, 35
	s_nop 1
	v_fmac_f32_e32 v58, s4, v133
	v_readlane_b32 s4, v56, 36
	s_nop 1
	v_fmac_f32_e32 v58, s4, v131
	v_readlane_b32 s4, v56, 37
	s_nop 1
	v_fmac_f32_e32 v58, s4, v132
	v_readlane_b32 s4, v56, 38
	s_nop 1
	v_fmac_f32_e32 v58, s4, v134
	v_readlane_b32 s4, v56, 39
	s_nop 1
	v_fmac_f32_e32 v58, s4, v135
	v_readlane_b32 s4, v56, 40
	s_nop 1
	v_fmac_f32_e32 v58, s4, v137
	v_readlane_b32 s4, v56, 41
	s_nop 1
	v_fmac_f32_e32 v58, s4, v138
	v_readlane_b32 s4, v56, 42
	s_nop 1
	v_fmac_f32_e32 v58, s4, v136
	v_readlane_b32 s4, v56, 43
	s_nop 1
	v_fmac_f32_e32 v58, s4, v141
	v_readlane_b32 s4, v56, 44
	s_nop 1
	v_fmac_f32_e32 v58, s4, v139
	v_readlane_b32 s4, v56, 45
	s_nop 1
	v_fmac_f32_e32 v58, s4, v140
	v_readlane_b32 s4, v56, 46
	s_nop 1
	v_fmac_f32_e32 v58, s4, v142
	v_readlane_b32 s4, v56, 47
	s_nop 1
	v_fmac_f32_e32 v58, s4, v143
	v_min_f32_e32 v59, 0, v58
	v_mul_f32_e64 v58, |v58|, s0
	v_exp_f32_e32 v58, v58
	v_readlane_b32 s4, v56, 48
	v_add_f32_e32 v58, 1.0, v58
	v_cmp_gt_f32_e32 vcc, s92, v58
	s_nop 1
	v_cndmask_b32_e64 v60, 0, 32, vcc
	v_ldexp_f32 v58, v58, v60
	v_log_f32_e32 v58, v58
	s_nop 0
	v_mul_f32_e32 v60, 0x3f317217, v58
	v_fma_f32 v60, v58, s3, -v60
	v_fmac_f32_e32 v60, 0x3377d1cf, v58
	v_fmac_f32_e32 v60, 0x3f317217, v58
	v_cmp_lt_f32_e64 s[6:7], |v58|, s96
	s_nop 1
	v_cndmask_b32_e64 v58, v58, v60, s[6:7]
	v_cndmask_b32_e32 v60, 0, v244, vcc
	v_sub_f32_e32 v58, v58, v60
	v_sub_f32_e32 v58, v59, v58
	v_fmamk_f32 v81, v58, 0x3d800000, v80
	v_fma_f32 v58, s4, v99, v144
	v_readlane_b32 s4, v56, 49
	v_bfe_u32 v60, v108, 4, 2
	s_nop 0
	v_fmac_f32_e32 v58, s4, v130
	v_readlane_b32 s4, v56, 50
	s_nop 1
	v_fmac_f32_e32 v58, s4, v98
	v_readlane_b32 s4, v56, 51
	s_nop 1
	v_fmac_f32_e32 v58, s4, v133
	v_readlane_b32 s4, v56, 52
	s_nop 1
	v_fmac_f32_e32 v58, s4, v131
	v_readlane_b32 s4, v56, 53
	s_nop 1
	v_fmac_f32_e32 v58, s4, v132
	v_readlane_b32 s4, v56, 54
	s_nop 1
	v_fmac_f32_e32 v58, s4, v134
	v_readlane_b32 s4, v56, 55
	s_nop 1
	v_fmac_f32_e32 v58, s4, v135
	v_readlane_b32 s4, v56, 56
	s_nop 1
	v_fmac_f32_e32 v58, s4, v137
	v_readlane_b32 s4, v56, 57
	s_nop 1
	v_fmac_f32_e32 v58, s4, v138
	v_readlane_b32 s4, v56, 58
	s_nop 1
	v_fmac_f32_e32 v58, s4, v136
	v_readlane_b32 s4, v56, 59
	s_nop 1
	v_fmac_f32_e32 v58, s4, v141
	v_readlane_b32 s4, v56, 60
	s_nop 1
	v_fmac_f32_e32 v58, s4, v139
	v_readlane_b32 s4, v56, 61
	s_nop 1
	v_fmac_f32_e32 v58, s4, v140
	v_readlane_b32 s4, v56, 62
	s_nop 1
	v_fmac_f32_e32 v58, s4, v142
	v_readlane_b32 s4, v56, 63
	s_nop 1
	v_fmac_f32_e32 v58, s4, v143
	v_min_f32_e32 v56, 0, v58
	v_mul_f32_e64 v58, |v58|, s0
	v_exp_f32_e32 v58, v58
	v_readlane_b32 s4, v57, 0
	v_add_f32_e32 v58, 1.0, v58
	v_cmp_gt_f32_e32 vcc, s92, v58
	s_nop 1
	v_cndmask_b32_e64 v59, 0, 32, vcc
	v_ldexp_f32 v58, v58, v59
	v_log_f32_e32 v58, v58
	s_nop 0
	v_mul_f32_e32 v59, 0x3f317217, v58
	v_fma_f32 v59, v58, s3, -v59
	v_fmac_f32_e32 v59, 0x3377d1cf, v58
	v_fmac_f32_e32 v59, 0x3f317217, v58
	v_cmp_lt_f32_e64 s[6:7], |v58|, s96
	s_nop 1
	v_cndmask_b32_e64 v58, v58, v59, s[6:7]
	v_cndmask_b32_e32 v59, 0, v244, vcc
	v_sub_f32_e32 v58, v58, v59
	v_sub_f32_e32 v56, v56, v58
	v_fmamk_f32 v82, v56, 0x3d800000, v81
	v_fma_f32 v56, s4, v99, v144
	v_readlane_b32 s4, v57, 1
	s_nop 1
	v_fmac_f32_e32 v56, s4, v130
	v_readlane_b32 s4, v57, 2
	s_nop 1
	v_fmac_f32_e32 v56, s4, v98
	v_readlane_b32 s4, v57, 3
	s_nop 1
	v_fmac_f32_e32 v56, s4, v133
	v_readlane_b32 s4, v57, 4
	s_nop 1
	v_fmac_f32_e32 v56, s4, v131
	v_readlane_b32 s4, v57, 5
	s_nop 1
	v_fmac_f32_e32 v56, s4, v132
	v_readlane_b32 s4, v57, 6
	s_nop 1
	v_fmac_f32_e32 v56, s4, v134
	v_readlane_b32 s4, v57, 7
	s_nop 1
	v_fmac_f32_e32 v56, s4, v135
	v_readlane_b32 s4, v57, 8
	s_nop 1
	v_fmac_f32_e32 v56, s4, v137
	v_readlane_b32 s4, v57, 9
	s_nop 1
	v_fmac_f32_e32 v56, s4, v138
	v_readlane_b32 s4, v57, 10
	s_nop 1
	v_fmac_f32_e32 v56, s4, v136
	v_readlane_b32 s4, v57, 11
	s_nop 1
	v_fmac_f32_e32 v56, s4, v141
	v_readlane_b32 s4, v57, 12
	s_nop 1
	v_fmac_f32_e32 v56, s4, v139
	v_readlane_b32 s4, v57, 13
	s_nop 1
	v_fmac_f32_e32 v56, s4, v140
	v_readlane_b32 s4, v57, 14
	s_nop 1
	v_fmac_f32_e32 v56, s4, v142
	v_readlane_b32 s4, v57, 15
	s_nop 1
	v_fmac_f32_e32 v56, s4, v143
	v_min_f32_e32 v58, 0, v56
	v_mul_f32_e64 v56, |v56|, s0
	v_exp_f32_e32 v56, v56
	v_readlane_b32 s4, v57, 16
	v_add_f32_e32 v56, 1.0, v56
	v_cmp_gt_f32_e32 vcc, s92, v56
	s_nop 1
	v_cndmask_b32_e64 v59, 0, 32, vcc
	v_ldexp_f32 v56, v56, v59
	v_log_f32_e32 v56, v56
	s_nop 0
	v_mul_f32_e32 v59, 0x3f317217, v56
	v_fma_f32 v59, v56, s3, -v59
	v_fmac_f32_e32 v59, 0x3377d1cf, v56
	v_fmac_f32_e32 v59, 0x3f317217, v56
	v_cmp_lt_f32_e64 s[6:7], |v56|, s96
	s_nop 1
	v_cndmask_b32_e64 v56, v56, v59, s[6:7]
	v_cndmask_b32_e32 v59, 0, v244, vcc
	v_sub_f32_e32 v56, v56, v59
	v_sub_f32_e32 v56, v58, v56
	v_fmamk_f32 v83, v56, 0x3d800000, v82
	v_fma_f32 v56, s4, v99, v144
	v_readlane_b32 s4, v57, 17
	s_nop 1
	v_fmac_f32_e32 v56, s4, v130
	v_readlane_b32 s4, v57, 18
	s_nop 1
	v_fmac_f32_e32 v56, s4, v98
	v_readlane_b32 s4, v57, 19
	s_nop 1
	v_fmac_f32_e32 v56, s4, v133
	v_readlane_b32 s4, v57, 20
	s_nop 1
	v_fmac_f32_e32 v56, s4, v131
	v_readlane_b32 s4, v57, 21
	s_nop 1
	v_fmac_f32_e32 v56, s4, v132
	v_readlane_b32 s4, v57, 22
	s_nop 1
	v_fmac_f32_e32 v56, s4, v134
	v_readlane_b32 s4, v57, 23
	s_nop 1
	v_fmac_f32_e32 v56, s4, v135
	v_readlane_b32 s4, v57, 24
	s_nop 1
	v_fmac_f32_e32 v56, s4, v137
	v_readlane_b32 s4, v57, 25
	s_nop 1
	v_fmac_f32_e32 v56, s4, v138
	v_readlane_b32 s4, v57, 26
	s_nop 1
	v_fmac_f32_e32 v56, s4, v136
	v_readlane_b32 s4, v57, 27
	s_nop 1
	v_fmac_f32_e32 v56, s4, v141
	v_readlane_b32 s4, v57, 28
	s_nop 1
	v_fmac_f32_e32 v56, s4, v139
	v_readlane_b32 s4, v57, 29
	s_nop 1
	v_fmac_f32_e32 v56, s4, v140
	v_readlane_b32 s4, v57, 30
	s_nop 1
	v_fmac_f32_e32 v56, s4, v142
	v_readlane_b32 s4, v57, 31
	s_nop 1
	v_fmac_f32_e32 v56, s4, v143
	v_min_f32_e32 v58, 0, v56
	v_mul_f32_e64 v56, |v56|, s0
	v_exp_f32_e32 v56, v56
	v_readlane_b32 s4, v57, 32
	v_add_f32_e32 v56, 1.0, v56
	v_cmp_gt_f32_e32 vcc, s92, v56
	s_nop 1
	v_cndmask_b32_e64 v59, 0, 32, vcc
	v_ldexp_f32 v56, v56, v59
	v_log_f32_e32 v56, v56
	s_nop 0
	v_mul_f32_e32 v59, 0x3f317217, v56
	v_fma_f32 v59, v56, s3, -v59
	v_fmac_f32_e32 v59, 0x3377d1cf, v56
	v_fmac_f32_e32 v59, 0x3f317217, v56
	v_cmp_lt_f32_e64 s[6:7], |v56|, s96
	s_nop 1
	v_cndmask_b32_e64 v56, v56, v59, s[6:7]
	v_cndmask_b32_e32 v59, 0, v244, vcc
	v_sub_f32_e32 v56, v56, v59
	v_sub_f32_e32 v56, v58, v56
	v_fmamk_f32 v84, v56, 0x3d800000, v83
	v_fma_f32 v56, s4, v99, v144
	v_readlane_b32 s4, v57, 33
	s_nop 1
	v_fmac_f32_e32 v56, s4, v130
	v_readlane_b32 s4, v57, 34
	s_nop 1
	v_fmac_f32_e32 v56, s4, v98
	v_readlane_b32 s4, v57, 35
	s_nop 1
	v_fmac_f32_e32 v56, s4, v133
	v_readlane_b32 s4, v57, 36
	s_nop 1
	v_fmac_f32_e32 v56, s4, v131
	v_readlane_b32 s4, v57, 37
	s_nop 1
	v_fmac_f32_e32 v56, s4, v132
	v_readlane_b32 s4, v57, 38
	s_nop 1
	v_fmac_f32_e32 v56, s4, v134
	v_readlane_b32 s4, v57, 39
	s_nop 1
	v_fmac_f32_e32 v56, s4, v135
	v_readlane_b32 s4, v57, 40
	s_nop 1
	v_fmac_f32_e32 v56, s4, v137
	v_readlane_b32 s4, v57, 41
	s_nop 1
	v_fmac_f32_e32 v56, s4, v138
	v_readlane_b32 s4, v57, 42
	s_nop 1
	v_fmac_f32_e32 v56, s4, v136
	v_readlane_b32 s4, v57, 43
	s_nop 1
	v_fmac_f32_e32 v56, s4, v141
	v_readlane_b32 s4, v57, 44
	s_nop 1
	v_fmac_f32_e32 v56, s4, v139
	v_readlane_b32 s4, v57, 45
	s_nop 1
	v_fmac_f32_e32 v56, s4, v140
	v_readlane_b32 s4, v57, 46
	s_nop 1
	v_fmac_f32_e32 v56, s4, v142
	v_readlane_b32 s4, v57, 47
	s_nop 1
	v_fmac_f32_e32 v56, s4, v143
	v_min_f32_e32 v58, 0, v56
	v_mul_f32_e64 v56, |v56|, s0
	v_exp_f32_e32 v56, v56
	v_readlane_b32 s4, v57, 48
	v_add_f32_e32 v56, 1.0, v56
	v_cmp_gt_f32_e32 vcc, s92, v56
	s_nop 1
	v_cndmask_b32_e64 v59, 0, 32, vcc
	v_ldexp_f32 v56, v56, v59
	v_log_f32_e32 v56, v56
	s_nop 0
	v_mul_f32_e32 v59, 0x3f317217, v56
	v_fma_f32 v59, v56, s3, -v59
	v_fmac_f32_e32 v59, 0x3377d1cf, v56
	v_fmac_f32_e32 v59, 0x3f317217, v56
	v_cmp_lt_f32_e64 s[6:7], |v56|, s96
	s_nop 1
	v_cndmask_b32_e64 v56, v56, v59, s[6:7]
	v_cndmask_b32_e32 v59, 0, v244, vcc
	v_sub_f32_e32 v56, v56, v59
	v_sub_f32_e32 v56, v58, v56
	v_fmamk_f32 v85, v56, 0x3d800000, v84
	v_fma_f32 v56, s4, v99, v144
	v_readlane_b32 s4, v57, 49
	s_nop 1
	v_fmac_f32_e32 v56, s4, v130
	v_readlane_b32 s4, v57, 50
	s_nop 1
	v_fmac_f32_e32 v56, s4, v98
	v_readlane_b32 s4, v57, 51
	s_nop 1
	v_fmac_f32_e32 v56, s4, v133
	v_readlane_b32 s4, v57, 52
	s_nop 1
	v_fmac_f32_e32 v56, s4, v131
	v_readlane_b32 s4, v57, 53
	s_nop 1
	v_fmac_f32_e32 v56, s4, v132
	v_readlane_b32 s4, v57, 54
	s_nop 1
	v_fmac_f32_e32 v56, s4, v134
	v_readlane_b32 s4, v57, 55
	s_nop 1
	v_fmac_f32_e32 v56, s4, v135
	v_readlane_b32 s4, v57, 56
	s_nop 1
	v_fmac_f32_e32 v56, s4, v137
	v_readlane_b32 s4, v57, 57
	s_nop 1
	v_fmac_f32_e32 v56, s4, v138
	v_readlane_b32 s4, v57, 58
	s_nop 1
	v_fmac_f32_e32 v56, s4, v136
	v_readlane_b32 s4, v57, 59
	s_nop 1
	v_fmac_f32_e32 v56, s4, v141
	v_readlane_b32 s4, v57, 60
	s_nop 1
	v_fmac_f32_e32 v56, s4, v139
	v_readlane_b32 s4, v57, 61
	s_nop 1
	v_fmac_f32_e32 v56, s4, v140
	v_readlane_b32 s4, v57, 62
	s_nop 1
	v_fmac_f32_e32 v56, s4, v142
	v_readlane_b32 s4, v57, 63
	s_nop 1
	v_fmac_f32_e32 v56, s4, v143
	v_min_f32_e32 v57, 0, v56
	v_mul_f32_e64 v56, |v56|, s0
	v_exp_f32_e32 v56, v56
	s_waitcnt lgkmcnt(0)
	v_readlane_b32 s4, v54, 0
	v_add_f32_e32 v56, 1.0, v56
	v_cmp_gt_f32_e32 vcc, s92, v56
	s_nop 1
	v_cndmask_b32_e64 v58, 0, 32, vcc
	v_ldexp_f32 v56, v56, v58
	v_log_f32_e32 v56, v56
	s_nop 0
	v_mul_f32_e32 v58, 0x3f317217, v56
	v_fma_f32 v58, v56, s3, -v58
	v_fmac_f32_e32 v58, 0x3377d1cf, v56
	v_fmac_f32_e32 v58, 0x3f317217, v56
	v_cmp_lt_f32_e64 s[6:7], |v56|, s96
	s_nop 1
	v_cndmask_b32_e64 v56, v56, v58, s[6:7]
	v_cndmask_b32_e32 v58, 0, v244, vcc
	v_sub_f32_e32 v56, v56, v58
	v_sub_f32_e32 v56, v57, v56
	v_fmamk_f32 v86, v56, 0x3d800000, v85
	v_fma_f32 v56, s4, v99, v144
	v_readlane_b32 s4, v54, 1
	s_nop 1
	v_fmac_f32_e32 v56, s4, v130
	v_readlane_b32 s4, v54, 2
	s_nop 1
	v_fmac_f32_e32 v56, s4, v98
	v_readlane_b32 s4, v54, 3
	s_nop 1
	v_fmac_f32_e32 v56, s4, v133
	v_readlane_b32 s4, v54, 4
	s_nop 1
	v_fmac_f32_e32 v56, s4, v131
	v_readlane_b32 s4, v54, 5
	s_nop 1
	v_fmac_f32_e32 v56, s4, v132
	v_readlane_b32 s4, v54, 6
	s_nop 1
	v_fmac_f32_e32 v56, s4, v134
	v_readlane_b32 s4, v54, 7
	s_nop 1
	v_fmac_f32_e32 v56, s4, v135
	v_readlane_b32 s4, v54, 8
	s_nop 1
	v_fmac_f32_e32 v56, s4, v137
	v_readlane_b32 s4, v54, 9
	s_nop 1
	v_fmac_f32_e32 v56, s4, v138
	v_readlane_b32 s4, v54, 10
	s_nop 1
	v_fmac_f32_e32 v56, s4, v136
	v_readlane_b32 s4, v54, 11
	s_nop 1
	v_fmac_f32_e32 v56, s4, v141
	v_readlane_b32 s4, v54, 12
	s_nop 1
	v_fmac_f32_e32 v56, s4, v139
	v_readlane_b32 s4, v54, 13
	s_nop 1
	v_fmac_f32_e32 v56, s4, v140
	v_readlane_b32 s4, v54, 14
	s_nop 1
	v_fmac_f32_e32 v56, s4, v142
	v_readlane_b32 s4, v54, 15
	s_nop 1
	v_fmac_f32_e32 v56, s4, v143
	v_min_f32_e32 v57, 0, v56
	v_mul_f32_e64 v56, |v56|, s0
	v_exp_f32_e32 v56, v56
	v_readlane_b32 s4, v54, 16
	v_add_f32_e32 v56, 1.0, v56
	v_cmp_gt_f32_e32 vcc, s92, v56
	s_nop 1
	v_cndmask_b32_e64 v58, 0, 32, vcc
	v_ldexp_f32 v56, v56, v58
	v_log_f32_e32 v56, v56
	s_nop 0
	v_mul_f32_e32 v58, 0x3f317217, v56
	v_fma_f32 v58, v56, s3, -v58
	v_fmac_f32_e32 v58, 0x3377d1cf, v56
	v_fmac_f32_e32 v58, 0x3f317217, v56
	v_cmp_lt_f32_e64 s[6:7], |v56|, s96
	s_nop 1
	v_cndmask_b32_e64 v56, v56, v58, s[6:7]
	v_cndmask_b32_e32 v58, 0, v244, vcc
	v_sub_f32_e32 v56, v56, v58
	v_sub_f32_e32 v56, v57, v56
	v_fmamk_f32 v87, v56, 0x3d800000, v86
	v_fma_f32 v56, s4, v99, v144
	v_readlane_b32 s4, v54, 17
	s_nop 1
	v_fmac_f32_e32 v56, s4, v130
	v_readlane_b32 s4, v54, 18
	s_nop 1
	v_fmac_f32_e32 v56, s4, v98
	v_readlane_b32 s4, v54, 19
	s_nop 1
	v_fmac_f32_e32 v56, s4, v133
	v_readlane_b32 s4, v54, 20
	s_nop 1
	v_fmac_f32_e32 v56, s4, v131
	v_readlane_b32 s4, v54, 21
	s_nop 1
	v_fmac_f32_e32 v56, s4, v132
	v_readlane_b32 s4, v54, 22
	s_nop 1
	v_fmac_f32_e32 v56, s4, v134
	v_readlane_b32 s4, v54, 23
	s_nop 1
	v_fmac_f32_e32 v56, s4, v135
	v_readlane_b32 s4, v54, 24
	s_nop 1
	v_fmac_f32_e32 v56, s4, v137
	v_readlane_b32 s4, v54, 25
	s_nop 1
	v_fmac_f32_e32 v56, s4, v138
	v_readlane_b32 s4, v54, 26
	s_nop 1
	v_fmac_f32_e32 v56, s4, v136
	v_readlane_b32 s4, v54, 27
	s_nop 1
	v_fmac_f32_e32 v56, s4, v141
	v_readlane_b32 s4, v54, 28
	s_nop 1
	v_fmac_f32_e32 v56, s4, v139
	v_readlane_b32 s4, v54, 29
	s_nop 1
	v_fmac_f32_e32 v56, s4, v140
	v_readlane_b32 s4, v54, 30
	s_nop 1
	v_fmac_f32_e32 v56, s4, v142
	v_readlane_b32 s4, v54, 31
	s_nop 1
	v_fmac_f32_e32 v56, s4, v143
	v_min_f32_e32 v57, 0, v56
	v_mul_f32_e64 v56, |v56|, s0
	v_exp_f32_e32 v56, v56
	v_readlane_b32 s4, v54, 32
	v_add_f32_e32 v56, 1.0, v56
	v_cmp_gt_f32_e32 vcc, s92, v56
	s_nop 1
	v_cndmask_b32_e64 v58, 0, 32, vcc
	v_ldexp_f32 v56, v56, v58
	v_log_f32_e32 v56, v56
	s_nop 0
	v_mul_f32_e32 v58, 0x3f317217, v56
	v_fma_f32 v58, v56, s3, -v58
	v_fmac_f32_e32 v58, 0x3377d1cf, v56
	v_fmac_f32_e32 v58, 0x3f317217, v56
	v_cmp_lt_f32_e64 s[6:7], |v56|, s96
	s_nop 1
	v_cndmask_b32_e64 v56, v56, v58, s[6:7]
	v_cndmask_b32_e32 v58, 0, v244, vcc
	v_sub_f32_e32 v56, v56, v58
	v_sub_f32_e32 v56, v57, v56
	v_fmamk_f32 v88, v56, 0x3d800000, v87
	v_fma_f32 v56, s4, v99, v144
	v_readlane_b32 s4, v54, 33
	s_nop 1
	v_fmac_f32_e32 v56, s4, v130
	v_readlane_b32 s4, v54, 34
	s_nop 1
	v_fmac_f32_e32 v56, s4, v98
	v_readlane_b32 s4, v54, 35
	s_nop 1
	v_fmac_f32_e32 v56, s4, v133
	v_readlane_b32 s4, v54, 36
	s_nop 1
	v_fmac_f32_e32 v56, s4, v131
	v_readlane_b32 s4, v54, 37
	s_nop 1
	v_fmac_f32_e32 v56, s4, v132
	v_readlane_b32 s4, v54, 38
	s_nop 1
	v_fmac_f32_e32 v56, s4, v134
	v_readlane_b32 s4, v54, 39
	s_nop 1
	v_fmac_f32_e32 v56, s4, v135
	v_readlane_b32 s4, v54, 40
	s_nop 1
	v_fmac_f32_e32 v56, s4, v137
	v_readlane_b32 s4, v54, 41
	s_nop 1
	v_fmac_f32_e32 v56, s4, v138
	v_readlane_b32 s4, v54, 42
	s_nop 1
	v_fmac_f32_e32 v56, s4, v136
	v_readlane_b32 s4, v54, 43
	s_nop 1
	v_fmac_f32_e32 v56, s4, v141
	v_readlane_b32 s4, v54, 44
	s_nop 1
	v_fmac_f32_e32 v56, s4, v139
	v_readlane_b32 s4, v54, 45
	s_nop 1
	v_fmac_f32_e32 v56, s4, v140
	v_readlane_b32 s4, v54, 46
	s_nop 1
	v_fmac_f32_e32 v56, s4, v142
	v_readlane_b32 s4, v54, 47
	s_nop 1
	v_fmac_f32_e32 v56, s4, v143
	v_min_f32_e32 v57, 0, v56
	v_mul_f32_e64 v56, |v56|, s0
	v_exp_f32_e32 v56, v56
	v_readlane_b32 s4, v54, 48
	v_add_f32_e32 v56, 1.0, v56
	v_cmp_gt_f32_e32 vcc, s92, v56
	s_nop 1
	v_cndmask_b32_e64 v58, 0, 32, vcc
	v_ldexp_f32 v56, v56, v58
	v_log_f32_e32 v56, v56
	s_nop 0
	v_mul_f32_e32 v58, 0x3f317217, v56
	v_fma_f32 v58, v56, s3, -v58
	v_fmac_f32_e32 v58, 0x3377d1cf, v56
	v_fmac_f32_e32 v58, 0x3f317217, v56
	v_cmp_lt_f32_e64 s[6:7], |v56|, s96
	s_nop 1
	v_cndmask_b32_e64 v56, v56, v58, s[6:7]
	v_cndmask_b32_e32 v58, 0, v244, vcc
	v_sub_f32_e32 v56, v56, v58
	v_sub_f32_e32 v56, v57, v56
	v_fmamk_f32 v89, v56, 0x3d800000, v88
	v_fma_f32 v56, s4, v99, v144
	v_readlane_b32 s4, v54, 49
	s_nop 1
	v_fmac_f32_e32 v56, s4, v130
	v_readlane_b32 s4, v54, 50
	s_nop 1
	v_fmac_f32_e32 v56, s4, v98
	v_readlane_b32 s4, v54, 51
	s_nop 1
	v_fmac_f32_e32 v56, s4, v133
	v_readlane_b32 s4, v54, 52
	s_nop 1
	v_fmac_f32_e32 v56, s4, v131
	v_readlane_b32 s4, v54, 53
	s_nop 1
	v_fmac_f32_e32 v56, s4, v132
	v_readlane_b32 s4, v54, 54
	s_nop 1
	v_fmac_f32_e32 v56, s4, v134
	v_readlane_b32 s4, v54, 55
	s_nop 1
	v_fmac_f32_e32 v56, s4, v135
	v_readlane_b32 s4, v54, 56
	s_nop 1
	v_fmac_f32_e32 v56, s4, v137
	v_readlane_b32 s4, v54, 57
	s_nop 1
	v_fmac_f32_e32 v56, s4, v138
	v_readlane_b32 s4, v54, 58
	s_nop 1
	v_fmac_f32_e32 v56, s4, v136
	v_readlane_b32 s4, v54, 59
	s_nop 1
	v_fmac_f32_e32 v56, s4, v141
	v_readlane_b32 s4, v54, 60
	s_nop 1
	v_fmac_f32_e32 v56, s4, v139
	v_readlane_b32 s4, v54, 61
	s_nop 1
	v_fmac_f32_e32 v56, s4, v140
	v_readlane_b32 s4, v54, 62
	s_nop 1
	v_fmac_f32_e32 v56, s4, v142
	v_readlane_b32 s4, v54, 63
	s_nop 1
	v_fmac_f32_e32 v56, s4, v143
	v_min_f32_e32 v54, 0, v56
	v_mul_f32_e64 v56, |v56|, s0
	v_exp_f32_e32 v56, v56
	v_readlane_b32 s4, v55, 0
	v_add_f32_e32 v56, 1.0, v56
	v_cmp_gt_f32_e32 vcc, s92, v56
	s_nop 1
	v_cndmask_b32_e64 v57, 0, 32, vcc
	v_ldexp_f32 v56, v56, v57
	v_log_f32_e32 v56, v56
	s_nop 0
	v_mul_f32_e32 v57, 0x3f317217, v56
	v_fma_f32 v57, v56, s3, -v57
	v_fmac_f32_e32 v57, 0x3377d1cf, v56
	v_fmac_f32_e32 v57, 0x3f317217, v56
	v_cmp_lt_f32_e64 s[6:7], |v56|, s96
	s_nop 1
	v_cndmask_b32_e64 v56, v56, v57, s[6:7]
	v_cndmask_b32_e32 v57, 0, v244, vcc
	v_sub_f32_e32 v56, v56, v57
	v_sub_f32_e32 v54, v54, v56
	v_fmamk_f32 v90, v54, 0x3d800000, v89
	v_fma_f32 v54, s4, v99, v144
	v_readlane_b32 s4, v55, 1
	s_nop 1
	v_fmac_f32_e32 v54, s4, v130
	v_readlane_b32 s4, v55, 2
	s_nop 1
	v_fmac_f32_e32 v54, s4, v98
	v_readlane_b32 s4, v55, 3
	s_nop 1
	v_fmac_f32_e32 v54, s4, v133
	v_readlane_b32 s4, v55, 4
	s_nop 1
	v_fmac_f32_e32 v54, s4, v131
	v_readlane_b32 s4, v55, 5
	s_nop 1
	v_fmac_f32_e32 v54, s4, v132
	v_readlane_b32 s4, v55, 6
	s_nop 1
	v_fmac_f32_e32 v54, s4, v134
	v_readlane_b32 s4, v55, 7
	s_nop 1
	v_fmac_f32_e32 v54, s4, v135
	v_readlane_b32 s4, v55, 8
	s_nop 1
	v_fmac_f32_e32 v54, s4, v137
	v_readlane_b32 s4, v55, 9
	s_nop 1
	v_fmac_f32_e32 v54, s4, v138
	v_readlane_b32 s4, v55, 10
	s_nop 1
	v_fmac_f32_e32 v54, s4, v136
	v_readlane_b32 s4, v55, 11
	s_nop 1
	v_fmac_f32_e32 v54, s4, v141
	v_readlane_b32 s4, v55, 12
	s_nop 1
	v_fmac_f32_e32 v54, s4, v139
	v_readlane_b32 s4, v55, 13
	s_nop 1
	v_fmac_f32_e32 v54, s4, v140
	v_readlane_b32 s4, v55, 14
	s_nop 1
	v_fmac_f32_e32 v54, s4, v142
	v_readlane_b32 s4, v55, 15
	s_nop 1
	v_fmac_f32_e32 v54, s4, v143
	v_min_f32_e32 v56, 0, v54
	v_mul_f32_e64 v54, |v54|, s0
	v_exp_f32_e32 v54, v54
	v_readlane_b32 s4, v55, 16
	v_add_f32_e32 v54, 1.0, v54
	v_cmp_gt_f32_e32 vcc, s92, v54
	s_nop 1
	v_cndmask_b32_e64 v57, 0, 32, vcc
	v_ldexp_f32 v54, v54, v57
	v_log_f32_e32 v54, v54
	s_nop 0
	v_mul_f32_e32 v57, 0x3f317217, v54
	v_fma_f32 v57, v54, s3, -v57
	v_fmac_f32_e32 v57, 0x3377d1cf, v54
	v_fmac_f32_e32 v57, 0x3f317217, v54
	v_cmp_lt_f32_e64 s[6:7], |v54|, s96
	s_nop 1
	v_cndmask_b32_e64 v54, v54, v57, s[6:7]
	v_cndmask_b32_e32 v57, 0, v244, vcc
	v_sub_f32_e32 v54, v54, v57
	v_sub_f32_e32 v54, v56, v54
	v_fmamk_f32 v92, v54, 0x3d800000, v90
	v_fma_f32 v54, s4, v99, v144
	v_readlane_b32 s4, v55, 17
	s_nop 1
	v_fmac_f32_e32 v54, s4, v130
	v_readlane_b32 s4, v55, 18
	s_nop 1
	v_fmac_f32_e32 v54, s4, v98
	v_readlane_b32 s4, v55, 19
	s_nop 1
	v_fmac_f32_e32 v54, s4, v133
	v_readlane_b32 s4, v55, 20
	s_nop 1
	v_fmac_f32_e32 v54, s4, v131
	v_readlane_b32 s4, v55, 21
	s_nop 1
	v_fmac_f32_e32 v54, s4, v132
	v_readlane_b32 s4, v55, 22
	s_nop 1
	v_fmac_f32_e32 v54, s4, v134
	v_readlane_b32 s4, v55, 23
	s_nop 1
	v_fmac_f32_e32 v54, s4, v135
	v_readlane_b32 s4, v55, 24
	s_nop 1
	v_fmac_f32_e32 v54, s4, v137
	v_readlane_b32 s4, v55, 25
	s_nop 1
	v_fmac_f32_e32 v54, s4, v138
	v_readlane_b32 s4, v55, 26
	s_nop 1
	v_fmac_f32_e32 v54, s4, v136
	v_readlane_b32 s4, v55, 27
	s_nop 1
	v_fmac_f32_e32 v54, s4, v141
	v_readlane_b32 s4, v55, 28
	s_nop 1
	v_fmac_f32_e32 v54, s4, v139
	v_readlane_b32 s4, v55, 29
	s_nop 1
	v_fmac_f32_e32 v54, s4, v140
	v_readlane_b32 s4, v55, 30
	s_nop 1
	v_fmac_f32_e32 v54, s4, v142
	v_readlane_b32 s4, v55, 31
	s_nop 1
	v_fmac_f32_e32 v54, s4, v143
	v_min_f32_e32 v56, 0, v54
	v_mul_f32_e64 v54, |v54|, s0
	v_exp_f32_e32 v54, v54
	v_readlane_b32 s4, v55, 32
	v_add_f32_e32 v54, 1.0, v54
	v_cmp_gt_f32_e32 vcc, s92, v54
	s_nop 1
	v_cndmask_b32_e64 v57, 0, 32, vcc
	v_ldexp_f32 v54, v54, v57
	v_log_f32_e32 v54, v54
	s_nop 0
	v_mul_f32_e32 v57, 0x3f317217, v54
	v_fma_f32 v57, v54, s3, -v57
	v_fmac_f32_e32 v57, 0x3377d1cf, v54
	v_fmac_f32_e32 v57, 0x3f317217, v54
	v_cmp_lt_f32_e64 s[6:7], |v54|, s96
	s_nop 1
	v_cndmask_b32_e64 v54, v54, v57, s[6:7]
	v_cndmask_b32_e32 v57, 0, v244, vcc
	v_sub_f32_e32 v54, v54, v57
	v_sub_f32_e32 v54, v56, v54
	v_fmamk_f32 v94, v54, 0x3d800000, v92
	v_fma_f32 v54, s4, v99, v144
	v_readlane_b32 s4, v55, 33
	s_nop 1
	v_fmac_f32_e32 v54, s4, v130
	v_readlane_b32 s4, v55, 34
	s_nop 1
	v_fmac_f32_e32 v54, s4, v98
	v_readlane_b32 s4, v55, 35
	s_nop 1
	v_fmac_f32_e32 v54, s4, v133
	v_readlane_b32 s4, v55, 36
	s_nop 1
	v_fmac_f32_e32 v54, s4, v131
	v_readlane_b32 s4, v55, 37
	s_nop 1
	v_fmac_f32_e32 v54, s4, v132
	v_readlane_b32 s4, v55, 38
	s_nop 1
	v_fmac_f32_e32 v54, s4, v134
	v_readlane_b32 s4, v55, 39
	s_nop 1
	v_fmac_f32_e32 v54, s4, v135
	v_readlane_b32 s4, v55, 40
	s_nop 1
	v_fmac_f32_e32 v54, s4, v137
	v_readlane_b32 s4, v55, 41
	s_nop 1
	v_fmac_f32_e32 v54, s4, v138
	v_readlane_b32 s4, v55, 42
	s_nop 1
	v_fmac_f32_e32 v54, s4, v136
	v_readlane_b32 s4, v55, 43
	s_nop 1
	v_fmac_f32_e32 v54, s4, v141
	v_readlane_b32 s4, v55, 44
	s_nop 1
	v_fmac_f32_e32 v54, s4, v139
	v_readlane_b32 s4, v55, 45
	s_nop 1
	v_fmac_f32_e32 v54, s4, v140
	v_readlane_b32 s4, v55, 46
	s_nop 1
	v_fmac_f32_e32 v54, s4, v142
	v_readlane_b32 s4, v55, 47
	s_nop 1
	v_fmac_f32_e32 v54, s4, v143
	v_readlane_b32 s4, v55, 48
	v_min_f32_e32 v56, 0, v54
	v_mul_f32_e64 v54, |v54|, s0
	v_fmac_f32_e32 v144, s4, v99
	v_readlane_b32 s4, v55, 49
	v_exp_f32_e32 v54, v54
	s_nop 0
	v_fmac_f32_e32 v144, s4, v130
	v_readlane_b32 s4, v55, 50
	v_add_f32_e32 v54, 1.0, v54
	v_cmp_gt_f32_e32 vcc, s92, v54
	v_fmac_f32_e32 v144, s4, v98
	v_readlane_b32 s4, v55, 51
	v_cndmask_b32_e64 v57, 0, 32, vcc
	v_ldexp_f32 v54, v54, v57
	v_fmac_f32_e32 v144, s4, v133
	v_readlane_b32 s4, v55, 52
	v_log_f32_e32 v54, v54
	s_nop 0
	v_fmac_f32_e32 v144, s4, v131
	v_readlane_b32 s4, v55, 53
	v_mul_f32_e32 v57, 0x3f317217, v54
	v_fma_f32 v57, v54, s3, -v57
	v_fmac_f32_e32 v144, s4, v132
	v_readlane_b32 s4, v55, 54
	v_fmac_f32_e32 v57, 0x3377d1cf, v54
	v_fmac_f32_e32 v57, 0x3f317217, v54
	v_fmac_f32_e32 v144, s4, v134
	v_readlane_b32 s4, v55, 55
	v_cmp_lt_f32_e64 s[6:7], |v54|, s96
	v_mul_f32_e32 v134, 0x3fb8aa3b, v129
	v_fmac_f32_e32 v144, s4, v135
	v_readlane_b32 s4, v55, 56
	v_cndmask_b32_e64 v54, v54, v57, s[6:7]
	v_cndmask_b32_e32 v57, 0, v244, vcc
	v_fmac_f32_e32 v144, s4, v137
	v_readlane_b32 s4, v55, 57
	v_sub_f32_e32 v54, v54, v57
	v_sub_f32_e32 v54, v56, v54
	v_fmac_f32_e32 v144, s4, v138
	v_readlane_b32 s4, v55, 58
	v_fmamk_f32 v96, v54, 0x3d800000, v94
	v_mul_f32_e32 v129, 0xbfb8aa3b, v129
	v_fmac_f32_e32 v144, s4, v136
	v_readlane_b32 s4, v55, 59
	v_exp_f32_e32 v129, v129
	v_exp_f32_e32 v134, v134
	v_fmac_f32_e32 v144, s4, v141
	v_readlane_b32 s4, v55, 60
	s_nop 1
	v_fmac_f32_e32 v144, s4, v139
	v_readlane_b32 s4, v55, 61
	s_nop 1
	v_fmac_f32_e32 v144, s4, v140
	v_readlane_b32 s4, v55, 62
	s_nop 1
	v_fmac_f32_e32 v144, s4, v142
	v_readlane_b32 s4, v55, 63
	s_nop 1
	v_fmac_f32_e32 v144, s4, v143
	v_mul_f32_e64 v55, |v144|, s0
	v_exp_f32_e32 v55, v55
	v_min_f32_e32 v54, 0, v144
	s_mul_hi_i32 s4, s8, 6
	v_add_f32_e32 v55, 1.0, v55
	v_cmp_gt_f32_e32 vcc, s92, v55
	s_nop 1
	v_cndmask_b32_e64 v56, 0, 32, vcc
	v_ldexp_f32 v55, v55, v56
	v_log_f32_e32 v55, v55
	s_nop 0
	v_mul_f32_e32 v56, 0x3f317217, v55
	v_fma_f32 v56, v55, s3, -v56
	v_fmac_f32_e32 v56, 0x3377d1cf, v55
	v_fmac_f32_e32 v56, 0x3f317217, v55
	v_cmp_lt_f32_e64 s[6:7], |v55|, s96
	s_nop 1
	v_cndmask_b32_e64 v55, v55, v56, s[6:7]
	v_cndmask_b32_e32 v56, 0, v244, vcc
	v_sub_f32_e32 v55, v55, v56
	v_sub_f32_e32 v54, v54, v55
	v_fmamk_f32 v99, v54, 0x3d800000, v96
	v_mul_f32_e32 v54, 0x3fb8aa3b, v99
	v_exp_f32_e32 v98, v54
	v_add_co_u32_e32 v54, vcc, s1, v52
	s_ashr_i32 s7, s30, 31
	s_nop 0
	v_addc_co_u32_e32 v55, vcc, 0, v53, vcc
	global_load_ushort v130, v[54:55], off offset:3328
	global_load_ushort v133, v[54:55], off offset:2560
	v_add_co_u32_e32 v54, vcc, s79, v52
	s_add_u32 s6, s5, s30
	s_nop 0
	v_addc_co_u32_e32 v55, vcc, 0, v53, vcc
	global_load_ushort v160, v[54:55], off offset:2304
	global_load_ushort v161, v[54:55], off offset:1536
	v_add_co_u32_e32 v54, vcc, s41, v52
	s_addc_u32 s7, s4, s7
	s_nop 0
	v_addc_co_u32_e32 v55, vcc, 0, v53, vcc
	global_load_ushort v158, v[54:55], off offset:1280
	global_load_ushort v159, v[54:55], off offset:512
	v_add_co_u32_e32 v54, vcc, s50, v52
	s_lshl_b64 s[4:5], s[6:7], 8
	s_nop 0
	v_addc_co_u32_e32 v55, vcc, 0, v53, vcc
	global_load_ushort v156, v[54:55], off offset:256
	v_add_co_u32_e32 v54, vcc, s93, v52
	s_add_u32 s4, s21, s4
	s_nop 0
	v_addc_co_u32_e32 v55, vcc, 0, v53, vcc
	global_load_ushort v157, v[54:55], off offset:3584
	v_add_co_u32_e32 v54, vcc, s52, v52
	s_addc_u32 s5, s22, s5
	s_nop 0
	v_addc_co_u32_e32 v55, vcc, 0, v53, vcc
	global_load_ushort v154, v[54:55], off offset:3328
	global_load_ushort v155, v[54:55], off offset:2560
	v_add_co_u32_e32 v54, vcc, s48, v52
	s_waitcnt vmcnt(9)
	v_lshlrev_b32_e32 v130, 16, v130
	v_addc_co_u32_e32 v55, vcc, 0, v53, vcc
	global_load_ushort v152, v[54:55], off offset:2304
	global_load_ushort v153, v[54:55], off offset:1536
	v_add_co_u32_e32 v54, vcc, s45, v52
	s_waitcnt vmcnt(10)
	v_lshlrev_b32_e32 v133, 16, v133
	v_addc_co_u32_e32 v55, vcc, 0, v53, vcc
	global_load_ushort v150, v[54:55], off offset:1280
	global_load_ushort v151, v[54:55], off offset:512
	v_add_co_u32_e32 v54, vcc, s54, v52
	v_mul_f32_e32 v162, v129, v130
	s_nop 0
	v_addc_co_u32_e32 v55, vcc, 0, v53, vcc
	global_load_ushort v148, v[54:55], off offset:256
	v_add_co_u32_e32 v54, vcc, s78, v52
	v_mul_f32_e32 v129, 0x3e000000, v133
	s_nop 0
	v_addc_co_u32_e32 v55, vcc, 0, v53, vcc
	global_load_ushort v149, v[54:55], off offset:3584
	v_add_co_u32_e32 v54, vcc, s55, v52
	v_mul_f32_e32 v129, v129, v134
	s_nop 0
	v_addc_co_u32_e32 v55, vcc, 0, v53, vcc
	global_load_ushort v145, v[54:55], off offset:3328
	global_load_ushort v146, v[54:55], off offset:2560
	v_add_co_u32_e32 v54, vcc, s65, v52
	v_cvt_pk_bf16_f32 v163, v129, s0
	s_nop 0
	v_addc_co_u32_e32 v55, vcc, 0, v53, vcc
	global_load_ushort v143, v[54:55], off offset:2304
	global_load_ushort v144, v[54:55], off offset:1536
	v_add_co_u32_e32 v54, vcc, s56, v52
	s_waitcnt vmcnt(17)
	v_lshlrev_b32_e32 v160, 16, v160
	v_addc_co_u32_e32 v55, vcc, 0, v53, vcc
	global_load_ushort v141, v[54:55], off offset:1280
	global_load_ushort v142, v[54:55], off offset:512
	v_add_co_u32_e32 v54, vcc, s51, v52
	s_waitcnt vmcnt(18)
	v_lshlrev_b32_e32 v161, 16, v161
	v_addc_co_u32_e32 v55, vcc, 0, v53, vcc
	global_load_ushort v139, v[54:55], off offset:256
	v_add_co_u32_e32 v54, vcc, s61, v52
	s_waitcnt vmcnt(18)
	v_lshlrev_b32_e32 v158, 16, v158
	v_addc_co_u32_e32 v55, vcc, 0, v53, vcc
	global_load_ushort v140, v[54:55], off offset:3584
	v_add_co_u32_e32 v54, vcc, s66, v52
	s_waitcnt vmcnt(18)
	v_lshlrev_b32_e32 v159, 16, v159
	v_addc_co_u32_e32 v55, vcc, 0, v53, vcc
	global_load_ushort v137, v[54:55], off offset:3328
	global_load_ushort v138, v[54:55], off offset:2560
	v_add_co_u32_e32 v54, vcc, s67, v52
	s_waitcnt vmcnt(19)
	v_lshlrev_b32_e32 v156, 16, v156
	v_addc_co_u32_e32 v55, vcc, 0, v53, vcc
	global_load_ushort v135, v[54:55], off offset:2304
	global_load_ushort v136, v[54:55], off offset:1536
	v_add_co_u32_e32 v54, vcc, s68, v52
	s_waitcnt vmcnt(20)
	v_lshlrev_b32_e32 v157, 16, v157
	v_addc_co_u32_e32 v55, vcc, 0, v53, vcc
	global_load_ushort v131, v[54:55], off offset:1280
	global_load_ushort v132, v[54:55], off offset:512
	v_add_co_u32_e32 v54, vcc, s72, v52
	global_store_dword v70, v98, s[4:5]
	s_mul_i32 s5, s8, 0xc000
	s_mul_hi_i32 s4, s8, 0xc000
	s_add_u32 s8, s23, s5
	v_addc_co_u32_e32 v55, vcc, 0, v53, vcc
	s_addc_u32 s9, s24, s4
	global_load_ushort v58, v[54:55], off offset:256
	v_add_co_u32_e32 v54, vcc, s73, v52
	s_add_u32 s8, s8, s10
	s_nop 0
	v_addc_co_u32_e32 v55, vcc, 0, v53, vcc
	s_addc_u32 s9, s9, s11
	s_add_u32 s5, s25, s5
	v_add_co_u32_e32 v164, vcc, s76, v52
	s_addc_u32 s4, s26, s4
	s_nop 0
	v_addc_co_u32_e32 v165, vcc, 0, v53, vcc
	global_load_ushort v59, v[54:55], off offset:3584
	s_add_u32 s10, s5, s10
	global_load_ushort v133, v[164:165], off offset:3328
	global_load_ushort v134, v[164:165], off offset:2560
	v_add_co_u32_e32 v164, vcc, s80, v52
	s_addc_u32 s11, s4, s11
	s_nop 0
	v_addc_co_u32_e32 v165, vcc, 0, v53, vcc
	s_mov_b32 s4, 0x33000
	v_add_co_u32_e32 v166, vcc, s4, v52
	s_mov_b32 s4, 0x36000
	s_nop 0
	v_addc_co_u32_e32 v167, vcc, 0, v53, vcc
	global_load_ushort v129, v[164:165], off offset:2304
	global_load_ushort v130, v[164:165], off offset:1536
	s_nop 0
	global_load_ushort v164, v[166:167], off offset:1280
	global_load_ushort v165, v[166:167], off offset:512
	v_add_co_u32_e32 v166, vcc, s4, v52
	s_mov_b32 s4, 0x35000
	s_nop 0
	v_addc_co_u32_e32 v167, vcc, 0, v53, vcc
	v_add_co_u32_e32 v168, vcc, s4, v52
	s_mov_b32 s4, 0x38000
	s_nop 0
	v_addc_co_u32_e32 v169, vcc, 0, v53, vcc
	global_load_ushort v166, v[166:167], off offset:256
	v_lshl_add_u64 v[54:55], s[8:9], 0, v[4:5]
	global_load_ushort v174, v[168:169], off offset:3584
	v_add_co_u32_e32 v168, vcc, s4, v52
	s_mov_b32 s4, 0x3b000
	s_nop 0
	v_addc_co_u32_e32 v169, vcc, 0, v53, vcc
	v_add_co_u32_e32 v170, vcc, s4, v52
	s_mov_b32 s4, 0x3e000
	s_nop 0
	v_addc_co_u32_e32 v171, vcc, 0, v53, vcc
	v_add_co_u32_e32 v176, vcc, s4, v52
	s_mov_b32 s4, 0x41000
	s_nop 0
	v_addc_co_u32_e32 v177, vcc, 0, v53, vcc
	global_load_ushort v172, v[168:169], off offset:3328
	global_load_ushort v173, v[168:169], off offset:2560
	s_nop 0
	global_load_ushort v168, v[170:171], off offset:2304
	global_load_ushort v169, v[170:171], off offset:1536
	s_nop 0
	global_load_ushort v170, v[176:177], off offset:1280
	global_load_ushort v171, v[176:177], off offset:512
	v_add_co_u32_e32 v176, vcc, s4, v52
	s_mov_b32 s4, 0x40000
	s_nop 0
	v_addc_co_u32_e32 v177, vcc, 0, v53, vcc
	global_load_ushort v167, v[176:177], off offset:256
	v_add_co_u32_e32 v176, vcc, s4, v52
	s_mov_b32 s4, 0x43000
	s_nop 0
	v_addc_co_u32_e32 v177, vcc, 0, v53, vcc
	global_load_ushort v182, v[176:177], off offset:3584
	v_add_co_u32_e32 v176, vcc, s4, v52
	s_mov_b32 s4, 0x46000
	s_nop 0
	v_addc_co_u32_e32 v177, vcc, 0, v53, vcc
	global_load_ushort v179, v[176:177], off offset:3328
	global_load_ushort v180, v[176:177], off offset:2560
	v_add_co_u32_e32 v176, vcc, s4, v52
	s_mov_b32 s4, 0x49000
	s_nop 0
	v_addc_co_u32_e32 v177, vcc, 0, v53, vcc
	v_add_co_u32_e32 v184, vcc, s4, v52
	s_mov_b32 s4, 0x4c000
	s_nop 0
	v_addc_co_u32_e32 v185, vcc, 0, v53, vcc
	global_load_ushort v175, v[176:177], off offset:2304
	s_nop 0
	global_load_ushort v176, v[176:177], off offset:1536
	s_nop 0
	global_load_ushort v177, v[184:185], off offset:1280
	global_load_ushort v178, v[184:185], off offset:512
	v_add_co_u32_e32 v184, vcc, s4, v52
	s_mov_b32 s4, 0x4b000
	s_nop 0
	v_addc_co_u32_e32 v185, vcc, 0, v53, vcc
	global_load_ushort v181, v[184:185], off offset:256
	v_add_co_u32_e32 v184, vcc, s4, v52
	s_mov_b32 s4, 0x4e000
	s_nop 0
	v_addc_co_u32_e32 v185, vcc, 0, v53, vcc
	global_load_ushort v190, v[184:185], off offset:3584
	v_add_co_u32_e32 v184, vcc, s4, v52
	s_mov_b32 s4, 0x51000
	s_nop 0
	v_addc_co_u32_e32 v185, vcc, 0, v53, vcc
	global_load_ushort v187, v[184:185], off offset:3328
	global_load_ushort v188, v[184:185], off offset:2560
	v_add_co_u32_e32 v184, vcc, s4, v52
	s_mov_b32 s4, 0x54000
	s_nop 0
	v_addc_co_u32_e32 v185, vcc, 0, v53, vcc
	v_add_co_u32_e32 v192, vcc, s4, v52
	s_mov_b32 s4, 0x57000
	s_nop 0
	v_addc_co_u32_e32 v193, vcc, 0, v53, vcc
	global_load_ushort v183, v[184:185], off offset:2304
	s_nop 0
	global_load_ushort v184, v[184:185], off offset:1536
	s_nop 0
	global_load_ushort v185, v[192:193], off offset:1280
	global_load_ushort v186, v[192:193], off offset:512
	v_add_co_u32_e32 v192, vcc, s4, v52
	s_mov_b32 s4, 0x56000
	s_nop 0
	v_addc_co_u32_e32 v193, vcc, 0, v53, vcc
	global_load_ushort v189, v[192:193], off offset:256
	v_add_co_u32_e32 v192, vcc, s4, v52
	v_mbcnt_lo_u32_b32 v196, -1, 0
	v_mbcnt_hi_u32_b32 v196, -1, v196
	v_and_b32_e32 v194, 3, v196
	v_mul_u32_u24_e32 v194, 0x2fe, v194
	v_and_b32_e32 v195, 1, v196
	v_lshlrev_b32_e32 v195, 4, v195
	v_add_u32_e32 v194, v194, v4
	s_mov_b32 s31, 0xffff
	s_mov_b32 s34, 0xcccccccc
	s_mov_b32 s35, 0xcccccccc
	v_lshlrev_b32_e64 v195, v195, s31
	v_and_b32_e32 v204, s31, v163
	s_nop 0
	v_addc_co_u32_e32 v193, vcc, 0, v53, vcc
	global_load_ushort v191, v[192:193], off offset:3584
	v_cvt_pk_bf16_f32 v163, v162, s0
	v_mul_f32_e32 v162, v162, v98
	v_lshlrev_b32_e32 v192, 5, v60
	v_and_b32_e32 v206, s31, v163
	v_cvt_pk_bf16_f32 v163, v162, s0
	v_add3_u32 v162, s13, v192, v147
	ds_write_b16 v162, v163
	v_mul_f32_e32 v163, 0x3fb8aa3b, v113
	v_mul_f32_e32 v113, 0xbfb8aa3b, v113
	v_exp_f32_e32 v113, v113
	v_exp_f32_e32 v163, v163
	v_lshl_add_u64 v[56:57], s[10:11], 0, v[4:5]
	s_waitcnt vmcnt(32)
	v_lshlrev_b32_e32 v59, 16, v59
	v_mul_f32_e32 v113, v113, v160
	v_mul_f32_e32 v160, 0x3e000000, v161
	v_mul_f32_e32 v160, v160, v163
	v_cvt_pk_bf16_f32 v160, v160, s0
	v_lshl_or_b32 v204, v160, 16, v204
	v_cvt_pk_bf16_f32 v160, v113, s0
	v_mul_f32_e32 v113, v113, v98
	v_cvt_pk_bf16_f32 v113, v113, s0
	ds_write_b16 v162, v113 offset:128
	v_mul_f32_e32 v113, 0x3fb8aa3b, v114
	v_mul_f32_e32 v114, 0xbfb8aa3b, v114
	v_exp_f32_e32 v114, v114
	v_exp_f32_e32 v113, v113
	v_lshl_or_b32 v206, v160, 16, v206
	v_mul_f32_e32 v59, 0x3e000000, v59
	v_mul_f32_e32 v114, v114, v158
	v_mul_f32_e32 v158, 0x3e000000, v159
	v_mul_f32_e32 v113, v158, v113
	v_cvt_pk_bf16_f32 v113, v113, s0
	v_and_b32_e32 v205, s31, v113
	v_cvt_pk_bf16_f32 v113, v114, s0
	v_and_b32_e32 v207, s31, v113
	v_mul_f32_e32 v113, v114, v98
	v_cvt_pk_bf16_f32 v114, v113, s0
	v_xor_b32_e32 v113, 32, v192
	v_add3_u32 v113, s13, v113, v147
	ds_write_b16 v113, v114 offset:256
	v_mul_f32_e32 v114, 0x3fb8aa3b, v115
	v_mul_f32_e32 v115, 0xbfb8aa3b, v115
	v_exp_f32_e32 v115, v115
	v_exp_f32_e32 v114, v114
	v_lshlrev_b32_e32 v58, 16, v58
	s_mov_b32 s4, 0x59000
	v_mul_f32_e32 v115, v115, v156
	v_mul_f32_e32 v156, 0x3e000000, v157
	v_mul_f32_e32 v114, v156, v114
	v_cvt_pk_bf16_f32 v114, v114, s0
	v_lshl_or_b32 v205, v114, 16, v205
	s_nop 1
	v_mov_b32_dpp v196, v204 quad_perm:[1,0,3,2] row_mask:0xf bank_mask:0xf
	v_mov_b32_dpp v199, v205 quad_perm:[1,0,3,2] row_mask:0xf bank_mask:0xf
	v_alignbit_b32 v196, v196, v196, 16
	v_alignbit_b32 v199, v199, v199, 16
	v_bfi_b32 v197, v195, v204, v196
	v_bfi_b32 v198, v195, v205, v199
	s_nop 1
	v_mov_b32_dpp v199, v197 quad_perm:[2,3,0,1] row_mask:0xf bank_mask:0xf
	v_mov_b32_dpp v200, v198 quad_perm:[2,3,0,1] row_mask:0xf bank_mask:0xf
	v_cndmask_b32_e64 v202, v197, v200, s[34:35]
	v_cndmask_b32_e64 v203, v199, v198, s[34:35]
	global_store_dwordx2 v194, v[202:203], s[8:9]
	v_cvt_pk_bf16_f32 v114, v115, s0
	v_lshl_or_b32 v207, v114, 16, v207
	s_nop 1
	v_mov_b32_dpp v196, v206 quad_perm:[1,0,3,2] row_mask:0xf bank_mask:0xf
	v_mov_b32_dpp v199, v207 quad_perm:[1,0,3,2] row_mask:0xf bank_mask:0xf
	v_alignbit_b32 v196, v196, v196, 16
	v_alignbit_b32 v199, v199, v199, 16
	v_bfi_b32 v197, v195, v206, v196
	v_bfi_b32 v198, v195, v207, v199
	s_nop 1
	v_mov_b32_dpp v199, v197 quad_perm:[2,3,0,1] row_mask:0xf bank_mask:0xf
	v_mov_b32_dpp v200, v198 quad_perm:[2,3,0,1] row_mask:0xf bank_mask:0xf
	v_cndmask_b32_e64 v202, v197, v200, s[34:35]
	v_cndmask_b32_e64 v203, v199, v198, s[34:35]
	global_store_dwordx2 v194, v[202:203], s[10:11]
	v_mul_f32_e32 v114, v115, v98
	v_cvt_pk_bf16_f32 v114, v114, s0
	v_mul_f32_e32 v115, 0xbfb8aa3b, v116
	ds_write_b16 v113, v114 offset:384
	v_mul_f32_e32 v114, 0x3fb8aa3b, v116
	v_exp_f32_e32 v115, v115
	v_exp_f32_e32 v114, v114
	v_lshlrev_b32_e32 v116, 16, v154
	v_lshlrev_b32_e32 v154, 16, v155
	v_mul_f32_e32 v115, v115, v116
	v_mul_f32_e32 v116, 0x3e000000, v154
	v_mul_f32_e32 v114, v116, v114
	v_cvt_pk_bf16_f32 v114, v114, s0
	v_and_b32_e32 v208, s31, v114
	v_cvt_pk_bf16_f32 v114, v115, s0
	v_and_b32_e32 v212, s31, v114
	v_mul_f32_e32 v114, v115, v98
	v_cvt_pk_bf16_f32 v114, v114, s0
	v_mul_f32_e32 v115, 0xbfb8aa3b, v117
	ds_write_b16 v162, v114 offset:512
	v_mul_f32_e32 v114, 0x3fb8aa3b, v117
	v_exp_f32_e32 v115, v115
	v_exp_f32_e32 v114, v114
	v_lshlrev_b32_e32 v116, 16, v152
	v_lshlrev_b32_e32 v117, 16, v153
	v_mul_f32_e32 v115, v115, v116
	v_mul_f32_e32 v116, 0x3e000000, v117
	v_mul_f32_e32 v114, v116, v114
	v_cvt_pk_bf16_f32 v114, v114, s0
	v_lshl_or_b32 v208, v114, 16, v208
	v_cvt_pk_bf16_f32 v114, v115, s0
	v_lshl_or_b32 v212, v114, 16, v212
	v_mul_f32_e32 v4, v115, v98
	v_cvt_pk_bf16_f32 v4, v4, s0
	v_mul_f32_e32 v114, 0xbfb8aa3b, v118
	ds_write_b16 v162, v4 offset:640
	v_mul_f32_e32 v4, 0x3fb8aa3b, v118
	v_exp_f32_e32 v114, v114
	v_exp_f32_e32 v4, v4
	v_lshlrev_b32_e32 v115, 16, v150
	v_lshlrev_b32_e32 v116, 16, v151
	v_mul_f32_e32 v118, v114, v115
	v_mul_f32_e32 v114, 0x3e000000, v116
	v_mul_f32_e32 v4, v114, v4
	v_add_co_u32_e32 v114, vcc, s1, v54
	v_cvt_pk_bf16_f32 v4, v4, s0
	s_nop 0
	v_addc_co_u32_e32 v115, vcc, 0, v55, vcc
	v_add_co_u32_e32 v116, vcc, s1, v56
	v_and_b32_e32 v209, s31, v4
	v_cvt_pk_bf16_f32 v4, v118, s0
	v_addc_co_u32_e32 v117, vcc, 0, v57, vcc
	v_and_b32_e32 v213, s31, v4
	v_mul_f32_e32 v4, v118, v98
	v_cvt_pk_bf16_f32 v4, v4, s0
	v_mul_f32_e32 v118, 0xbfb8aa3b, v119
	ds_write_b16 v113, v4 offset:768
	v_mul_f32_e32 v4, 0x3fb8aa3b, v119
	v_exp_f32_e32 v118, v118
	v_exp_f32_e32 v4, v4
	v_lshlrev_b32_e32 v119, 16, v148
	v_lshlrev_b32_e32 v148, 16, v149
	v_mul_f32_e32 v118, v118, v119
	v_mul_f32_e32 v119, 0x3e000000, v148
	v_mul_f32_e32 v4, v119, v4
	v_cvt_pk_bf16_f32 v4, v4, s0
	v_lshl_or_b32 v209, v4, 16, v209
	s_nop 1
	v_mov_b32_dpp v196, v208 quad_perm:[1,0,3,2] row_mask:0xf bank_mask:0xf
	v_mov_b32_dpp v199, v209 quad_perm:[1,0,3,2] row_mask:0xf bank_mask:0xf
	v_alignbit_b32 v196, v196, v196, 16
	v_alignbit_b32 v199, v199, v199, 16
	v_bfi_b32 v197, v195, v208, v196
	v_bfi_b32 v198, v195, v209, v199
	s_nop 1
	v_mov_b32_dpp v199, v197 quad_perm:[2,3,0,1] row_mask:0xf bank_mask:0xf
	v_mov_b32_dpp v200, v198 quad_perm:[2,3,0,1] row_mask:0xf bank_mask:0xf
	v_cndmask_b32_e64 v202, v197, v200, s[34:35]
	v_cndmask_b32_e64 v203, v199, v198, s[34:35]
	global_store_dwordx2 v194, v[202:203], s[8:9] offset:3072
	v_cvt_pk_bf16_f32 v4, v118, s0
	v_lshl_or_b32 v213, v4, 16, v213
	s_nop 1
	v_mov_b32_dpp v196, v212 quad_perm:[1,0,3,2] row_mask:0xf bank_mask:0xf
	v_mov_b32_dpp v199, v213 quad_perm:[1,0,3,2] row_mask:0xf bank_mask:0xf
	v_alignbit_b32 v196, v196, v196, 16
	v_alignbit_b32 v199, v199, v199, 16
	v_bfi_b32 v197, v195, v212, v196
	v_bfi_b32 v198, v195, v213, v199
	s_nop 1
	v_mov_b32_dpp v199, v197 quad_perm:[2,3,0,1] row_mask:0xf bank_mask:0xf
	v_mov_b32_dpp v200, v198 quad_perm:[2,3,0,1] row_mask:0xf bank_mask:0xf
	v_cndmask_b32_e64 v202, v197, v200, s[34:35]
	v_cndmask_b32_e64 v203, v199, v198, s[34:35]
	global_store_dwordx2 v194, v[202:203], s[10:11] offset:3072
	v_mul_f32_e32 v4, v118, v98
	v_cvt_pk_bf16_f32 v4, v4, s0
	v_mul_f32_e32 v118, 0xbfb8aa3b, v120
	ds_write_b16 v113, v4 offset:896
	v_mul_f32_e32 v4, 0x3fb8aa3b, v120
	v_exp_f32_e32 v118, v118
	v_exp_f32_e32 v4, v4
	v_lshlrev_b32_e32 v119, 16, v145
	v_lshlrev_b32_e32 v120, 16, v146
	v_mul_f32_e32 v118, v118, v119
	v_mul_f32_e32 v119, 0x3e000000, v120
	v_mul_f32_e32 v4, v119, v4
	v_cvt_pk_bf16_f32 v4, v4, s0
	v_and_b32_e32 v214, s31, v4
	v_cvt_pk_bf16_f32 v4, v118, s0
	v_and_b32_e32 v216, s31, v4
	v_mul_f32_e32 v4, v118, v98
	v_cvt_pk_bf16_f32 v118, v4, s0
	v_xor_b32_e32 v4, 64, v192
	v_add3_u32 v4, s13, v4, v147
	v_mul_f32_e32 v119, 0xbfb8aa3b, v121
	ds_write_b16 v4, v118 offset:1024
	v_mul_f32_e32 v118, 0x3fb8aa3b, v121
	v_exp_f32_e32 v119, v119
	v_exp_f32_e32 v118, v118
	v_lshlrev_b32_e32 v120, 16, v143
	v_lshlrev_b32_e32 v121, 16, v144
	v_mul_f32_e32 v119, v119, v120
	v_mul_f32_e32 v120, 0x3e000000, v121
	v_mul_f32_e32 v118, v120, v118
	v_cvt_pk_bf16_f32 v118, v118, s0
	v_lshl_or_b32 v214, v118, 16, v214
	v_cvt_pk_bf16_f32 v118, v119, s0
	v_lshl_or_b32 v216, v118, 16, v216
	v_mul_f32_e32 v118, v119, v98
	v_cvt_pk_bf16_f32 v118, v118, s0
	v_mul_f32_e32 v119, 0xbfb8aa3b, v122
	ds_write_b16 v4, v118 offset:1152
	v_mul_f32_e32 v118, 0x3fb8aa3b, v122
	v_exp_f32_e32 v119, v119
	v_exp_f32_e32 v118, v118
	v_lshlrev_b32_e32 v120, 16, v141
	v_lshlrev_b32_e32 v121, 16, v142
	v_mul_f32_e32 v119, v119, v120
	v_mul_f32_e32 v120, 0x3e000000, v121
	v_mul_f32_e32 v118, v120, v118
	v_cvt_pk_bf16_f32 v118, v118, s0
	v_and_b32_e32 v215, s31, v118
	v_cvt_pk_bf16_f32 v114, v119, s0
	v_and_b32_e32 v217, s31, v114
	v_mul_f32_e32 v114, v119, v98
	v_cvt_pk_bf16_f32 v115, v114, s0
	v_xor_b32_e32 v114, 0x60, v192
	v_add3_u32 v114, s13, v114, v147
	v_mul_f32_e32 v116, 0xbfb8aa3b, v123
	ds_write_b16 v114, v115 offset:1280
	v_mul_f32_e32 v115, 0x3fb8aa3b, v123
	v_exp_f32_e32 v116, v116
	v_exp_f32_e32 v115, v115
	v_lshlrev_b32_e32 v117, 16, v139
	v_lshlrev_b32_e32 v118, 16, v140
	v_mul_f32_e32 v120, v116, v117
	v_mul_f32_e32 v116, 0x3e000000, v118
	v_mul_f32_e32 v115, v116, v115
	v_add_co_u32_e32 v116, vcc, s75, v54
	v_cvt_pk_bf16_f32 v115, v115, s0
	s_nop 0
	v_addc_co_u32_e32 v117, vcc, 0, v55, vcc
	v_add_co_u32_e32 v118, vcc, s75, v56
	v_lshl_or_b32 v215, v115, 16, v215
	s_nop 1
	v_mov_b32_dpp v196, v214 quad_perm:[1,0,3,2] row_mask:0xf bank_mask:0xf
	v_mov_b32_dpp v199, v215 quad_perm:[1,0,3,2] row_mask:0xf bank_mask:0xf
	v_alignbit_b32 v196, v196, v196, 16
	v_alignbit_b32 v199, v199, v199, 16
	v_bfi_b32 v197, v195, v214, v196
	v_bfi_b32 v198, v195, v215, v199
	s_nop 1
	v_mov_b32_dpp v199, v197 quad_perm:[2,3,0,1] row_mask:0xf bank_mask:0xf
	v_mov_b32_dpp v200, v198 quad_perm:[2,3,0,1] row_mask:0xf bank_mask:0xf
	v_cndmask_b32_e64 v202, v197, v200, s[34:35]
	v_cndmask_b32_e64 v203, v199, v198, s[34:35]
	v_add_u32_e32 v201, 0x1800, v194
	global_store_dwordx2 v201, v[202:203], s[8:9]
	v_cvt_pk_bf16_f32 v115, v120, s0
	v_addc_co_u32_e32 v119, vcc, 0, v57, vcc
	v_lshl_or_b32 v217, v115, 16, v217
	s_nop 1
	v_mov_b32_dpp v196, v216 quad_perm:[1,0,3,2] row_mask:0xf bank_mask:0xf
	v_mov_b32_dpp v199, v217 quad_perm:[1,0,3,2] row_mask:0xf bank_mask:0xf
	v_alignbit_b32 v196, v196, v196, 16
	v_alignbit_b32 v199, v199, v199, 16
	v_bfi_b32 v197, v195, v216, v196
	v_bfi_b32 v198, v195, v217, v199
	s_nop 1
	v_mov_b32_dpp v199, v197 quad_perm:[2,3,0,1] row_mask:0xf bank_mask:0xf
	v_mov_b32_dpp v200, v198 quad_perm:[2,3,0,1] row_mask:0xf bank_mask:0xf
	v_cndmask_b32_e64 v202, v197, v200, s[34:35]
	v_cndmask_b32_e64 v203, v199, v198, s[34:35]
	v_add_u32_e32 v201, 0x1800, v194
	global_store_dwordx2 v201, v[202:203], s[10:11]
	v_mul_f32_e32 v115, v120, v98
	v_cvt_pk_bf16_f32 v115, v115, s0
	v_mul_f32_e32 v120, 0xbfb8aa3b, v124
	ds_write_b16 v114, v115 offset:1408
	v_mul_f32_e32 v115, 0x3fb8aa3b, v124
	v_exp_f32_e32 v120, v120
	v_exp_f32_e32 v115, v115
	v_lshlrev_b32_e32 v121, 16, v137
	v_lshlrev_b32_e32 v122, 16, v138
	v_mul_f32_e32 v120, v120, v121
	v_mul_f32_e32 v121, 0x3e000000, v122
	v_mul_f32_e32 v115, v121, v115
	v_cvt_pk_bf16_f32 v115, v115, s0
	v_and_b32_e32 v218, s31, v115
	v_cvt_pk_bf16_f32 v115, v120, s0
	v_and_b32_e32 v220, s31, v115
	v_mul_f32_e32 v115, v120, v98
	v_cvt_pk_bf16_f32 v115, v115, s0
	v_mul_f32_e32 v120, 0xbfb8aa3b, v125
	ds_write_b16 v4, v115 offset:1536
	v_mul_f32_e32 v115, 0x3fb8aa3b, v125
	v_exp_f32_e32 v120, v120
	v_exp_f32_e32 v115, v115
	v_lshlrev_b32_e32 v121, 16, v135
	v_lshlrev_b32_e32 v122, 16, v136
	v_mul_f32_e32 v120, v120, v121
	v_mul_f32_e32 v121, 0x3e000000, v122
	v_mul_f32_e32 v115, v121, v115
	v_cvt_pk_bf16_f32 v115, v115, s0
	v_lshl_or_b32 v218, v115, 16, v218
	v_cvt_pk_bf16_f32 v115, v120, s0
	v_lshl_or_b32 v220, v115, 16, v220
	v_mul_f32_e32 v115, v120, v98
	v_cvt_pk_bf16_f32 v115, v115, s0
	v_mul_f32_e32 v120, 0xbfb8aa3b, v126
	ds_write_b16 v4, v115 offset:1664
	v_mul_f32_e32 v115, 0x3fb8aa3b, v126
	v_exp_f32_e32 v120, v120
	v_exp_f32_e32 v115, v115
	v_lshlrev_b32_e32 v121, 16, v131
	v_lshlrev_b32_e32 v122, 16, v132
	v_mul_f32_e32 v120, v120, v121
	v_mul_f32_e32 v121, 0x3e000000, v122
	v_mul_f32_e32 v115, v121, v115
	v_cvt_pk_bf16_f32 v115, v115, s0
	v_and_b32_e32 v219, s31, v115
	v_cvt_pk_bf16_f32 v115, v120, s0
	v_and_b32_e32 v221, s31, v115
	v_mul_f32_e32 v115, v120, v98
	v_cvt_pk_bf16_f32 v115, v115, s0
	ds_write_b16 v114, v115 offset:1792
	v_mul_f32_e32 v115, 0x3fb8aa3b, v127
	v_exp_f32_e32 v115, v115
	v_mul_f32_e32 v120, 0xbfb8aa3b, v127
	v_exp_f32_e32 v120, v120
	s_waitcnt vmcnt(35)
	v_lshlrev_b32_e32 v129, 16, v129
	v_mul_f32_e32 v59, v59, v115
	v_cvt_pk_bf16_f32 v59, v59, s0
	v_mul_f32_e32 v58, v120, v58
	v_lshl_or_b32 v219, v59, 16, v219
	s_nop 1
	v_mov_b32_dpp v196, v218 quad_perm:[1,0,3,2] row_mask:0xf bank_mask:0xf
	v_mov_b32_dpp v199, v219 quad_perm:[1,0,3,2] row_mask:0xf bank_mask:0xf
	v_alignbit_b32 v196, v196, v196, 16
	v_alignbit_b32 v199, v199, v199, 16
	v_bfi_b32 v197, v195, v218, v196
	v_bfi_b32 v198, v195, v219, v199
	s_nop 1
	v_mov_b32_dpp v199, v197 quad_perm:[2,3,0,1] row_mask:0xf bank_mask:0xf
	v_mov_b32_dpp v200, v198 quad_perm:[2,3,0,1] row_mask:0xf bank_mask:0xf
	v_cndmask_b32_e64 v202, v197, v200, s[34:35]
	v_cndmask_b32_e64 v203, v199, v198, s[34:35]
	v_add_u32_e32 v201, 0x2400, v194
	global_store_dwordx2 v201, v[202:203], s[8:9]
	v_cvt_pk_bf16_f32 v59, v58, s0
	v_mul_f32_e32 v58, v58, v98
	v_lshl_or_b32 v221, v59, 16, v221
	s_nop 1
	v_mov_b32_dpp v196, v220 quad_perm:[1,0,3,2] row_mask:0xf bank_mask:0xf
	v_mov_b32_dpp v199, v221 quad_perm:[1,0,3,2] row_mask:0xf bank_mask:0xf
	v_alignbit_b32 v196, v196, v196, 16
	v_alignbit_b32 v199, v199, v199, 16
	v_bfi_b32 v197, v195, v220, v196
	v_bfi_b32 v198, v195, v221, v199
	s_nop 1
	v_mov_b32_dpp v199, v197 quad_perm:[2,3,0,1] row_mask:0xf bank_mask:0xf
	v_mov_b32_dpp v200, v198 quad_perm:[2,3,0,1] row_mask:0xf bank_mask:0xf
	v_cndmask_b32_e64 v202, v197, v200, s[34:35]
	v_cndmask_b32_e64 v203, v199, v198, s[34:35]
	v_add_u32_e32 v201, 0x2400, v194
	global_store_dwordx2 v201, v[202:203], s[10:11]
	v_cvt_pk_bf16_f32 v58, v58, s0
	v_mul_f32_e32 v59, 0xbfb8aa3b, v128
	ds_write_b16 v114, v58 offset:1920
	v_mul_f32_e32 v58, 0x3fb8aa3b, v128
	v_exp_f32_e32 v59, v59
	v_exp_f32_e32 v58, v58
	v_lshlrev_b32_e32 v115, 16, v133
	v_lshlrev_b32_e32 v116, 16, v134
	v_mul_f32_e32 v147, v59, v115
	v_mul_f32_e32 v59, 0x3e000000, v116
	v_mul_f32_e32 v58, v58, v59
	v_cvt_pk_bf16_f32 v148, v58, s0
	v_add_co_u32_e32 v58, vcc, s74, v54
	s_waitcnt vmcnt(36)
	v_lshlrev_b32_e32 v130, 16, v130
	v_addc_co_u32_e32 v59, vcc, 0, v55, vcc
	v_add_co_u32_e32 v116, vcc, s4, v52
	s_mov_b32 s4, 0x5c000
	s_nop 0
	v_addc_co_u32_e32 v117, vcc, 0, v53, vcc
	global_load_ushort v149, v[116:117], off offset:3328
	global_load_ushort v150, v[116:117], off offset:2560
	v_add_co_u32_e32 v116, vcc, s4, v52
	s_mov_b32 s4, 0x5f000
	s_nop 0
	v_addc_co_u32_e32 v117, vcc, 0, v53, vcc
	v_add_co_u32_e32 v118, vcc, s4, v52
	s_mov_b32 s4, 0x62000
	s_nop 0
	v_addc_co_u32_e32 v119, vcc, 0, v53, vcc
	v_add_co_u32_e32 v120, vcc, s4, v52
	s_mov_b32 s4, 0x61000
	s_nop 0
	v_addc_co_u32_e32 v121, vcc, 0, v53, vcc
	global_load_ushort v115, v[116:117], off offset:2304
	s_nop 0
	global_load_ushort v116, v[116:117], off offset:1536
	s_nop 0
	global_load_ushort v117, v[118:119], off offset:1280
	s_nop 0
	global_load_ushort v118, v[118:119], off offset:512
	s_nop 0
	global_load_ushort v119, v[120:121], off offset:256
	v_add_co_u32_e32 v120, vcc, s4, v52
	s_mov_b32 s4, 0x64000
	s_nop 0
	v_addc_co_u32_e32 v121, vcc, 0, v53, vcc
	v_add_co_u32_e32 v122, vcc, s4, v52
	s_mov_b32 s4, 0x67000
	s_nop 0
	v_addc_co_u32_e32 v123, vcc, 0, v53, vcc
	v_add_co_u32_e32 v124, vcc, s4, v52
	s_mov_b32 s4, 0x6a000
	s_nop 0
	v_addc_co_u32_e32 v125, vcc, 0, v53, vcc
	v_add_co_u32_e32 v132, vcc, s4, v52
	s_mov_b32 s4, 0x6d000
	s_nop 0
	v_addc_co_u32_e32 v133, vcc, 0, v53, vcc
	global_load_ushort v120, v[120:121], off offset:3584
	s_nop 0
	global_load_ushort v121, v[122:123], off offset:3328
	s_nop 0
	global_load_ushort v122, v[122:123], off offset:2560
	s_nop 0
	global_load_ushort v123, v[124:125], off offset:2304
	s_nop 0
	global_load_ushort v124, v[124:125], off offset:1536
	s_nop 0
	global_load_ushort v126, v[132:133], off offset:1280
	global_load_ushort v127, v[132:133], off offset:512
	v_add_co_u32_e32 v132, vcc, s4, v52
	s_mov_b32 s4, 0x6c000
	s_nop 0
	v_addc_co_u32_e32 v133, vcc, 0, v53, vcc
	global_load_ushort v125, v[132:133], off offset:256
	v_add_co_u32_e32 v132, vcc, s4, v52
	s_mov_b32 s4, 0x6f000
	s_nop 0
	v_addc_co_u32_e32 v133, vcc, 0, v53, vcc
	global_load_ushort v135, v[132:133], off offset:3584
	v_add_co_u32_e32 v132, vcc, s4, v52
	s_mov_b32 s4, 0x72000
	s_nop 0
	v_addc_co_u32_e32 v133, vcc, 0, v53, vcc
	v_add_co_u32_e32 v136, vcc, s4, v52
	s_mov_b32 s4, 0x75000
	s_nop 0
	v_addc_co_u32_e32 v137, vcc, 0, v53, vcc
	v_add_co_u32_e32 v138, vcc, s4, v52
	global_load_ushort v131, v[132:133], off offset:3328
	s_nop 0
	global_load_ushort v132, v[132:133], off offset:2560
	v_addc_co_u32_e32 v139, vcc, 0, v53, vcc
	global_load_ushort v133, v[136:137], off offset:2304
	global_load_ushort v134, v[136:137], off offset:1536
	s_nop 0
	global_load_ushort v136, v[138:139], off offset:1280
	global_load_ushort v137, v[138:139], off offset:512
	v_add_co_u32_e32 v138, vcc, s84, v52
	s_mov_b32 s4, 0x77000
	s_nop 0
	v_addc_co_u32_e32 v139, vcc, 0, v53, vcc
	global_load_ushort v128, v[138:139], off offset:256
	v_add_co_u32_e32 v138, vcc, s4, v52
	s_mov_b32 s4, 0x7a000
	s_nop 0
	v_addc_co_u32_e32 v139, vcc, 0, v53, vcc
	v_add_co_u32_e32 v140, vcc, s4, v52
	s_mov_b32 s4, 0x7d000
	s_nop 0
	v_addc_co_u32_e32 v141, vcc, 0, v53, vcc
	v_add_co_u32_e32 v142, vcc, s4, v52
	s_mov_b32 s4, 0x80000
	s_nop 0
	v_addc_co_u32_e32 v143, vcc, 0, v53, vcc
	v_add_co_u32_e32 v152, vcc, s4, v52
	global_load_ushort v144, v[138:139], off offset:3584
	s_nop 0
	v_addc_co_u32_e32 v153, vcc, 0, v53, vcc
	global_load_ushort v138, v[140:141], off offset:3328
	global_load_ushort v139, v[140:141], off offset:2560
	s_nop 0
	global_load_ushort v140, v[142:143], off offset:2304
	global_load_ushort v141, v[142:143], off offset:1536
	s_nop 0
	global_load_ushort v142, v[152:153], off offset:1280
	global_load_ushort v143, v[152:153], off offset:512
	s_mov_b32 s4, 0x83000
	v_and_b32_e32 v222, s31, v148
	v_cvt_pk_bf16_f32 v148, v147, s0
	v_mul_f32_e32 v147, v147, v98
	v_cvt_pk_bf16_f32 v147, v147, s0
	ds_write_b16 v162, v147 offset:2048
	v_mul_f32_e32 v147, 0x3fb8aa3b, v91
	v_mul_f32_e32 v91, 0xbfb8aa3b, v91
	v_exp_f32_e32 v91, v91
	v_exp_f32_e32 v147, v147
	v_add_co_u32_e32 v152, vcc, s4, v52
	v_mul_f32_e32 v91, v91, v129
	v_mul_f32_e32 v129, 0x3e000000, v130
	v_mul_f32_e32 v129, v147, v129
	v_cvt_pk_bf16_f32 v129, v129, s0
	v_lshl_or_b32 v222, v129, 16, v222
	v_cvt_pk_bf16_f32 v129, v91, s0
	v_mul_f32_e32 v91, v91, v98
	v_addc_co_u32_e32 v153, vcc, 0, v53, vcc
	s_mov_b32 s4, 0x82000
	v_cvt_pk_bf16_f32 v91, v91, s0
	global_load_ushort v145, v[152:153], off offset:256
	v_add_co_u32_e32 v152, vcc, s4, v52
	ds_write_b16 v162, v91 offset:2176
	v_mul_f32_e32 v91, 0x3fb8aa3b, v93
	v_mul_f32_e32 v93, 0xbfb8aa3b, v93
	v_addc_co_u32_e32 v153, vcc, 0, v53, vcc
	v_exp_f32_e32 v93, v93
	global_load_ushort v146, v[152:153], off offset:3584
	v_add_co_u32_e32 v152, vcc, s74, v56
	v_exp_f32_e32 v91, v91
	s_nop 0
	v_addc_co_u32_e32 v153, vcc, 0, v57, vcc
	v_lshlrev_b32_e32 v224, 16, v129
	s_waitcnt vmcnt(40)
	v_lshlrev_b32_e32 v129, 16, v164
	v_lshlrev_b32_e32 v130, 16, v165
	v_mul_f32_e32 v93, v93, v129
	v_mul_f32_e32 v129, 0x3e000000, v130
	v_mul_f32_e32 v91, v91, v129
	v_cvt_pk_bf16_f32 v91, v91, s0
	v_and_b32_e32 v223, s31, v91
	v_cvt_pk_bf16_f32 v91, v93, s0
	v_and_b32_e32 v225, s31, v91
	v_mul_f32_e32 v91, v93, v98
	v_cvt_pk_bf16_f32 v91, v91, s0
	v_mul_f32_e32 v93, 0xbfb8aa3b, v95
	ds_write_b16 v113, v91 offset:2304
	v_mul_f32_e32 v91, 0x3fb8aa3b, v95
	v_exp_f32_e32 v93, v93
	v_exp_f32_e32 v91, v91
	v_lshlrev_b32_e32 v95, 16, v166
	v_lshlrev_b32_e32 v129, 16, v174
	v_mul_f32_e32 v93, v93, v95
	v_mul_f32_e32 v95, 0x3e000000, v129
	v_mul_f32_e32 v91, v91, v95
	v_cvt_pk_bf16_f32 v91, v91, s0
	v_lshl_or_b32 v223, v91, 16, v223
	s_nop 1
	v_mov_b32_dpp v196, v222 quad_perm:[1,0,3,2] row_mask:0xf bank_mask:0xf
	v_mov_b32_dpp v199, v223 quad_perm:[1,0,3,2] row_mask:0xf bank_mask:0xf
	v_alignbit_b32 v196, v196, v196, 16
	v_alignbit_b32 v199, v199, v199, 16
	v_bfi_b32 v197, v195, v222, v196
	v_bfi_b32 v198, v195, v223, v199
	s_nop 1
	v_mov_b32_dpp v199, v197 quad_perm:[2,3,0,1] row_mask:0xf bank_mask:0xf
	v_mov_b32_dpp v200, v198 quad_perm:[2,3,0,1] row_mask:0xf bank_mask:0xf
	v_cndmask_b32_e64 v202, v197, v200, s[34:35]
	v_cndmask_b32_e64 v203, v199, v198, s[34:35]
	v_add_u32_e32 v201, 0x3000, v194
	global_store_dwordx2 v201, v[202:203], s[8:9]
	v_cvt_pk_bf16_f32 v91, v93, s0
	v_lshl_or_b32 v225, v91, 16, v225
	v_mul_f32_e32 v91, v93, v98
	v_cvt_pk_bf16_f32 v91, v91, s0
	v_mul_f32_e32 v93, 0xbfb8aa3b, v97
	ds_write_b16 v113, v91 offset:2432
	v_mul_f32_e32 v91, 0x3fb8aa3b, v97
	v_exp_f32_e32 v93, v93
	v_exp_f32_e32 v91, v91
	v_lshlrev_b32_e32 v95, 16, v172
	v_lshlrev_b32_e32 v97, 16, v173
	v_mul_f32_e32 v93, v93, v95
	v_mul_f32_e32 v95, 0x3e000000, v97
	v_mul_f32_e32 v91, v91, v95
	v_cvt_pk_bf16_f32 v91, v91, s0
	v_and_b32_e32 v226, s31, v91
	v_cvt_pk_bf16_f32 v91, v93, s0
	v_and_b32_e32 v228, s31, v91
	v_mul_f32_e32 v91, v98, v93
	v_cvt_pk_bf16_f32 v91, v91, s0
	v_mul_f32_e32 v93, 0xbfb8aa3b, v100
	ds_write_b16 v162, v91 offset:2560
	v_mul_f32_e32 v91, 0x3fb8aa3b, v100
	v_exp_f32_e32 v93, v93
	v_exp_f32_e32 v91, v91
	v_lshlrev_b32_e32 v95, 16, v168
	v_lshlrev_b32_e32 v97, 16, v169
	v_mul_f32_e32 v93, v93, v95
	v_mul_f32_e32 v95, 0x3e000000, v97
	v_mul_f32_e32 v91, v91, v95
	v_cvt_pk_bf16_f32 v91, v91, s0
	v_lshl_or_b32 v226, v91, 16, v226
	v_cvt_pk_bf16_f32 v58, v93, s0
	v_lshl_or_b32 v228, v58, 16, v228
	v_mul_f32_e32 v58, v98, v93
	v_cvt_pk_bf16_f32 v58, v58, s0
	v_mul_f32_e32 v59, 0xbfb8aa3b, v101
	ds_write_b16 v162, v58 offset:2688
	v_mul_f32_e32 v58, 0x3fb8aa3b, v101
	v_exp_f32_e32 v59, v59
	v_exp_f32_e32 v58, v58
	v_lshlrev_b32_e32 v91, 16, v170
	v_lshlrev_b32_e32 v93, 16, v171
	v_mul_f32_e32 v91, v59, v91
	v_mul_f32_e32 v59, 0x3e000000, v93
	v_mul_f32_e32 v58, v58, v59
	v_cvt_pk_bf16_f32 v93, v58, s0
	v_add_co_u32_e32 v58, vcc, s79, v54
	v_lshlrev_b32_e32 v95, 16, v167
	s_nop 0
	v_addc_co_u32_e32 v59, vcc, 0, v55, vcc
	v_add_co_u32_e32 v100, vcc, s79, v56
	v_and_b32_e32 v227, s31, v93
	v_cvt_pk_bf16_f32 v93, v91, s0
	v_addc_co_u32_e32 v101, vcc, 0, v57, vcc
	v_mul_f32_e32 v91, v98, v91
	v_and_b32_e32 v229, s31, v93
	v_cvt_pk_bf16_f32 v91, v91, s0
	v_mul_f32_e32 v93, 0xbfb8aa3b, v102
	ds_write_b16 v113, v91 offset:2816
	v_mul_f32_e32 v91, 0x3fb8aa3b, v102
	v_exp_f32_e32 v93, v93
	v_exp_f32_e32 v91, v91
	v_lshlrev_b32_e32 v97, 16, v182
	s_mov_b32 s4, 0x85000
	v_mul_f32_e32 v93, v93, v95
	v_mul_f32_e32 v95, 0x3e000000, v97
	v_mul_f32_e32 v91, v91, v95
	v_cvt_pk_bf16_f32 v91, v91, s0
	v_lshl_or_b32 v227, v91, 16, v227
	s_nop 1
	v_mov_b32_dpp v196, v226 quad_perm:[1,0,3,2] row_mask:0xf bank_mask:0xf
	v_mov_b32_dpp v199, v227 quad_perm:[1,0,3,2] row_mask:0xf bank_mask:0xf
	v_alignbit_b32 v196, v196, v196, 16
	v_alignbit_b32 v199, v199, v199, 16
	v_bfi_b32 v197, v195, v226, v196
	v_bfi_b32 v198, v195, v227, v199
	s_nop 1
	v_mov_b32_dpp v199, v197 quad_perm:[2,3,0,1] row_mask:0xf bank_mask:0xf
	v_mov_b32_dpp v200, v198 quad_perm:[2,3,0,1] row_mask:0xf bank_mask:0xf
	v_cndmask_b32_e64 v202, v197, v200, s[34:35]
	v_cndmask_b32_e64 v203, v199, v198, s[34:35]
	v_add_u32_e32 v201, 0x3c00, v194
	global_store_dwordx2 v201, v[202:203], s[8:9]
	v_cvt_pk_bf16_f32 v91, v93, s0
	v_lshl_or_b32 v229, v91, 16, v229
	s_nop 1
	v_mov_b32_dpp v196, v228 quad_perm:[1,0,3,2] row_mask:0xf bank_mask:0xf
	v_mov_b32_dpp v199, v229 quad_perm:[1,0,3,2] row_mask:0xf bank_mask:0xf
	v_alignbit_b32 v196, v196, v196, 16
	v_alignbit_b32 v199, v199, v199, 16
	v_bfi_b32 v197, v195, v228, v196
	v_bfi_b32 v198, v195, v229, v199
	s_nop 1
	v_mov_b32_dpp v199, v197 quad_perm:[2,3,0,1] row_mask:0xf bank_mask:0xf
	v_mov_b32_dpp v200, v198 quad_perm:[2,3,0,1] row_mask:0xf bank_mask:0xf
	v_cndmask_b32_e64 v202, v197, v200, s[34:35]
	v_cndmask_b32_e64 v203, v199, v198, s[34:35]
	v_add_u32_e32 v201, 0x3c00, v194
	global_store_dwordx2 v201, v[202:203], s[10:11]
	v_mul_f32_e32 v91, v98, v93
	v_cvt_pk_bf16_f32 v91, v91, s0
	v_mul_f32_e32 v93, 0xbfb8aa3b, v103
	ds_write_b16 v113, v91 offset:2944
	v_mul_f32_e32 v91, 0x3fb8aa3b, v103
	v_exp_f32_e32 v93, v93
	v_exp_f32_e32 v91, v91
	v_lshlrev_b32_e32 v95, 16, v179
	v_lshlrev_b32_e32 v97, 16, v180
	v_mul_f32_e32 v93, v93, v95
	v_mul_f32_e32 v95, 0x3e000000, v97
	v_mul_f32_e32 v91, v91, v95
	v_cvt_pk_bf16_f32 v91, v91, s0
	v_and_b32_e32 v230, s31, v91
	v_cvt_pk_bf16_f32 v91, v93, s0
	v_and_b32_e32 v236, s31, v91
	v_mul_f32_e32 v91, v98, v93
	v_cvt_pk_bf16_f32 v91, v91, s0
	v_mul_f32_e32 v93, 0xbfb8aa3b, v104
	ds_write_b16 v4, v91 offset:3072
	v_mul_f32_e32 v91, 0x3fb8aa3b, v104
	v_exp_f32_e32 v93, v93
	v_exp_f32_e32 v91, v91
	v_lshlrev_b32_e32 v95, 16, v175
	v_lshlrev_b32_e32 v97, 16, v176
	v_mul_f32_e32 v93, v93, v95
	v_mul_f32_e32 v95, 0x3e000000, v97
	v_mul_f32_e32 v91, v91, v95
	v_cvt_pk_bf16_f32 v91, v91, s0
	v_lshl_or_b32 v230, v91, 16, v230
	v_cvt_pk_bf16_f32 v91, v93, s0
	v_lshl_or_b32 v236, v91, 16, v236
	v_mul_f32_e32 v91, v98, v93
	v_cvt_pk_bf16_f32 v91, v91, s0
	v_mul_f32_e32 v93, 0xbfb8aa3b, v105
	ds_write_b16 v4, v91 offset:3200
	v_mul_f32_e32 v91, 0x3fb8aa3b, v105
	v_exp_f32_e32 v93, v93
	v_exp_f32_e32 v91, v91
	v_lshlrev_b32_e32 v95, 16, v177
	v_lshlrev_b32_e32 v97, 16, v178
	v_mul_f32_e32 v93, v93, v95
	v_mul_f32_e32 v95, 0x3e000000, v97
	v_mul_f32_e32 v91, v91, v95
	v_cvt_pk_bf16_f32 v91, v91, s0
	v_and_b32_e32 v231, s31, v91
	v_cvt_pk_bf16_f32 v58, v93, s0
	v_and_b32_e32 v237, s31, v58
	v_mul_f32_e32 v58, v98, v93
	v_cvt_pk_bf16_f32 v58, v58, s0
	v_mul_f32_e32 v59, 0xbfb8aa3b, v106
	ds_write_b16 v114, v58 offset:3328
	v_mul_f32_e32 v58, 0x3fb8aa3b, v106
	v_exp_f32_e32 v59, v59
	v_exp_f32_e32 v58, v58
	v_lshlrev_b32_e32 v91, 16, v181
	v_lshlrev_b32_e32 v93, 16, v190
	v_mul_f32_e32 v91, v59, v91
	v_mul_f32_e32 v59, 0x3e000000, v93
	v_mul_f32_e32 v58, v58, v59
	v_cvt_pk_bf16_f32 v93, v58, s0
	v_add_co_u32_e32 v58, vcc, s40, v54
	v_lshlrev_b32_e32 v95, 16, v187
	s_nop 0
	v_addc_co_u32_e32 v59, vcc, 0, v55, vcc
	v_add_co_u32_e32 v100, vcc, s40, v56
	v_lshl_or_b32 v231, v93, 16, v231
	s_nop 1
	v_mov_b32_dpp v196, v230 quad_perm:[1,0,3,2] row_mask:0xf bank_mask:0xf
	v_mov_b32_dpp v199, v231 quad_perm:[1,0,3,2] row_mask:0xf bank_mask:0xf
	v_alignbit_b32 v196, v196, v196, 16
	v_alignbit_b32 v199, v199, v199, 16
	v_bfi_b32 v197, v195, v230, v196
	v_bfi_b32 v198, v195, v231, v199
	s_nop 1
	v_mov_b32_dpp v199, v197 quad_perm:[2,3,0,1] row_mask:0xf bank_mask:0xf
	v_mov_b32_dpp v200, v198 quad_perm:[2,3,0,1] row_mask:0xf bank_mask:0xf
	v_cndmask_b32_e64 v202, v197, v200, s[34:35]
	v_cndmask_b32_e64 v203, v199, v198, s[34:35]
	v_add_u32_e32 v201, 0x4800, v194
	global_store_dwordx2 v201, v[202:203], s[8:9]
	v_cvt_pk_bf16_f32 v93, v91, s0
	v_addc_co_u32_e32 v101, vcc, 0, v57, vcc
	v_mul_f32_e32 v91, v98, v91
	v_lshl_or_b32 v237, v93, 16, v237
	s_nop 1
	v_mov_b32_dpp v196, v236 quad_perm:[1,0,3,2] row_mask:0xf bank_mask:0xf
	v_mov_b32_dpp v199, v237 quad_perm:[1,0,3,2] row_mask:0xf bank_mask:0xf
	v_alignbit_b32 v196, v196, v196, 16
	v_alignbit_b32 v199, v199, v199, 16
	v_bfi_b32 v197, v195, v236, v196
	v_bfi_b32 v198, v195, v237, v199
	s_nop 1
	v_mov_b32_dpp v199, v197 quad_perm:[2,3,0,1] row_mask:0xf bank_mask:0xf
	v_mov_b32_dpp v200, v198 quad_perm:[2,3,0,1] row_mask:0xf bank_mask:0xf
	v_cndmask_b32_e64 v202, v197, v200, s[34:35]
	v_cndmask_b32_e64 v203, v199, v198, s[34:35]
	v_add_u32_e32 v201, 0x4800, v194
	global_store_dwordx2 v201, v[202:203], s[10:11]
	v_cvt_pk_bf16_f32 v91, v91, s0
	v_mul_f32_e32 v93, 0xbfb8aa3b, v107
	ds_write_b16 v114, v91 offset:3456
	v_mul_f32_e32 v91, 0x3fb8aa3b, v107
	v_exp_f32_e32 v93, v93
	v_exp_f32_e32 v91, v91
	v_lshlrev_b32_e32 v97, 16, v188
	v_and_or_b32 v224, v148, s31, v224
	s_nop 1
	v_mov_b32_dpp v196, v224 quad_perm:[1,0,3,2] row_mask:0xf bank_mask:0xf
	v_mov_b32_dpp v199, v225 quad_perm:[1,0,3,2] row_mask:0xf bank_mask:0xf
	v_alignbit_b32 v196, v196, v196, 16
	v_alignbit_b32 v199, v199, v199, 16
	v_bfi_b32 v197, v195, v224, v196
	v_bfi_b32 v198, v195, v225, v199
	s_nop 1
	v_mov_b32_dpp v199, v197 quad_perm:[2,3,0,1] row_mask:0xf bank_mask:0xf
	v_mov_b32_dpp v200, v198 quad_perm:[2,3,0,1] row_mask:0xf bank_mask:0xf
	v_cndmask_b32_e64 v202, v197, v200, s[34:35]
	v_cndmask_b32_e64 v203, v199, v198, s[34:35]
	v_add_u32_e32 v201, 0x3000, v194
	global_store_dwordx2 v201, v[202:203], s[10:11]
	v_mul_f32_e32 v93, v93, v95
	v_mul_f32_e32 v95, 0x3e000000, v97
	v_mul_f32_e32 v91, v91, v95
	v_cvt_pk_bf16_f32 v91, v91, s0
	v_and_b32_e32 v238, s31, v91
	v_cvt_pk_bf16_f32 v91, v93, s0
	v_and_b32_e32 v248, s31, v91
	v_mul_f32_e32 v91, v98, v93
	v_cvt_pk_bf16_f32 v91, v91, s0
	v_mul_f32_e32 v93, 0xbfb8aa3b, v109
	ds_write_b16 v4, v91 offset:3584
	v_mul_f32_e32 v91, 0x3fb8aa3b, v109
	v_exp_f32_e32 v93, v93
	v_exp_f32_e32 v91, v91
	v_lshlrev_b32_e32 v95, 16, v183
	v_lshlrev_b32_e32 v97, 16, v184
	v_mul_f32_e32 v93, v93, v95
	v_mul_f32_e32 v95, 0x3e000000, v97
	v_mul_f32_e32 v91, v91, v95
	v_cvt_pk_bf16_f32 v91, v91, s0
	v_lshl_or_b32 v238, v91, 16, v238
	v_cvt_pk_bf16_f32 v91, v93, s0
	v_lshl_or_b32 v248, v91, 16, v248
	v_mul_f32_e32 v91, v98, v93
	v_cvt_pk_bf16_f32 v91, v91, s0
	v_mul_f32_e32 v93, 0xbfb8aa3b, v110
	ds_write_b16 v4, v91 offset:3712
	v_mul_f32_e32 v91, 0x3fb8aa3b, v110
	v_exp_f32_e32 v93, v93
	v_exp_f32_e32 v91, v91
	v_lshlrev_b32_e32 v95, 16, v185
	v_lshlrev_b32_e32 v97, 16, v186
	v_mul_f32_e32 v93, v93, v95
	v_mul_f32_e32 v95, 0x3e000000, v97
	v_mul_f32_e32 v91, v91, v95
	v_cvt_pk_bf16_f32 v91, v91, s0
	v_and_b32_e32 v239, s31, v91
	v_cvt_pk_bf16_f32 v91, v93, s0
	v_and_b32_e32 v249, s31, v91
	v_mul_f32_e32 v91, v98, v93
	v_cvt_pk_bf16_f32 v91, v91, s0
	v_mul_f32_e32 v93, 0xbfb8aa3b, v111
	ds_write_b16 v114, v91 offset:3840
	v_mul_f32_e32 v91, 0x3fb8aa3b, v111
	v_exp_f32_e32 v93, v93
	v_exp_f32_e32 v91, v91
	v_lshlrev_b32_e32 v95, 16, v189
	v_lshlrev_b32_e32 v97, 16, v191
	v_mul_f32_e32 v93, v93, v95
	v_mul_f32_e32 v95, 0x3e000000, v97
	v_mul_f32_e32 v91, v91, v95
	v_cvt_pk_bf16_f32 v91, v91, s0
	v_lshl_or_b32 v239, v91, 16, v239
	s_nop 1
	v_mov_b32_dpp v196, v238 quad_perm:[1,0,3,2] row_mask:0xf bank_mask:0xf
	v_mov_b32_dpp v199, v239 quad_perm:[1,0,3,2] row_mask:0xf bank_mask:0xf
	v_alignbit_b32 v196, v196, v196, 16
	v_alignbit_b32 v199, v199, v199, 16
	v_bfi_b32 v197, v195, v238, v196
	v_bfi_b32 v198, v195, v239, v199
	s_nop 1
	v_mov_b32_dpp v199, v197 quad_perm:[2,3,0,1] row_mask:0xf bank_mask:0xf
	v_mov_b32_dpp v200, v198 quad_perm:[2,3,0,1] row_mask:0xf bank_mask:0xf
	v_cndmask_b32_e64 v202, v197, v200, s[34:35]
	v_cndmask_b32_e64 v203, v199, v198, s[34:35]
	v_add_u32_e32 v201, 0x5400, v194
	global_store_dwordx2 v201, v[202:203], s[8:9]
	v_cvt_pk_bf16_f32 v58, v93, s0
	v_lshl_or_b32 v249, v58, 16, v249
	s_nop 1
	v_mov_b32_dpp v196, v248 quad_perm:[1,0,3,2] row_mask:0xf bank_mask:0xf
	v_mov_b32_dpp v199, v249 quad_perm:[1,0,3,2] row_mask:0xf bank_mask:0xf
	v_alignbit_b32 v196, v196, v196, 16
	v_alignbit_b32 v199, v199, v199, 16
	v_bfi_b32 v197, v195, v248, v196
	v_bfi_b32 v198, v195, v249, v199
	s_nop 1
	v_mov_b32_dpp v199, v197 quad_perm:[2,3,0,1] row_mask:0xf bank_mask:0xf
	v_mov_b32_dpp v200, v198 quad_perm:[2,3,0,1] row_mask:0xf bank_mask:0xf
	v_cndmask_b32_e64 v202, v197, v200, s[34:35]
	v_cndmask_b32_e64 v203, v199, v198, s[34:35]
	v_add_u32_e32 v201, 0x5400, v194
	global_store_dwordx2 v201, v[202:203], s[10:11]
	v_mul_f32_e32 v58, v98, v93
	v_cvt_pk_bf16_f32 v58, v58, s0
	v_mul_f32_e32 v59, 0xbfb8aa3b, v112
	ds_write_b16 v114, v58 offset:3968
	v_mul_f32_e32 v58, 0x3fb8aa3b, v112
	v_exp_f32_e32 v59, v59
	v_exp_f32_e32 v58, v58
	s_waitcnt vmcnt(38)
	v_lshlrev_b32_e32 v91, 16, v149
	v_lshlrev_b32_e32 v93, 16, v150
	v_mul_f32_e32 v91, v59, v91
	v_mul_f32_e32 v59, 0x3e000000, v93
	v_mul_f32_e32 v58, v58, v59
	v_cvt_pk_bf16_f32 v93, v58, s0
	v_add_co_u32_e32 v58, vcc, s62, v54
	s_nop 1
	v_addc_co_u32_e32 v59, vcc, 0, v55, vcc
	v_add_co_u32_e32 v100, vcc, s4, v52
	s_mov_b32 s4, 0x88000
	s_nop 0
	v_addc_co_u32_e32 v101, vcc, 0, v53, vcc
	v_add_co_u32_e32 v102, vcc, s4, v52
	s_mov_b32 s4, 0x8b000
	s_nop 0
	v_addc_co_u32_e32 v103, vcc, 0, v53, vcc
	v_add_co_u32_e32 v104, vcc, s4, v52
	s_mov_b32 s4, 0x8e000
	s_nop 0
	v_addc_co_u32_e32 v105, vcc, 0, v53, vcc
	global_load_ushort v95, v[100:101], off offset:3328
	global_load_ushort v97, v[100:101], off offset:2560
	s_nop 0
	global_load_ushort v100, v[102:103], off offset:2304
	global_load_ushort v101, v[102:103], off offset:1536
	s_nop 0
	global_load_ushort v102, v[104:105], off offset:1280
	global_load_ushort v103, v[104:105], off offset:512
	v_add_co_u32_e32 v104, vcc, s4, v52
	s_mov_b32 s4, 0x8d000
	s_nop 0
	v_addc_co_u32_e32 v105, vcc, 0, v53, vcc
	v_add_co_u32_e32 v106, vcc, s4, v52
	global_load_ushort v104, v[104:105], off offset:256
	s_nop 0
	v_addc_co_u32_e32 v107, vcc, 0, v53, vcc
	global_load_ushort v129, v[106:107], off offset:3584
	v_add_co_u32_e32 v106, vcc, s85, v52
	s_mov_b32 s4, 0x93000
	s_nop 0
	v_addc_co_u32_e32 v107, vcc, 0, v53, vcc
	v_add_co_u32_e32 v110, vcc, s4, v52
	s_mov_b32 s4, 0x96000
	s_nop 0
	v_addc_co_u32_e32 v111, vcc, 0, v53, vcc
	v_add_co_u32_e32 v148, vcc, s4, v52
	s_mov_b32 s4, 0x99000
	s_nop 0
	v_addc_co_u32_e32 v149, vcc, 0, v53, vcc
	global_load_ushort v105, v[106:107], off offset:3328
	s_nop 0
	global_load_ushort v106, v[106:107], off offset:2560
	s_nop 0
	global_load_ushort v107, v[110:111], off offset:2304
	global_load_ushort v109, v[110:111], off offset:1536
	s_nop 0
	global_load_ushort v111, v[148:149], off offset:1280
	global_load_ushort v112, v[148:149], off offset:512
	v_add_co_u32_e32 v148, vcc, s4, v52
	s_mov_b32 s4, 0x98000
	s_nop 0
	v_addc_co_u32_e32 v149, vcc, 0, v53, vcc
	global_load_ushort v110, v[148:149], off offset:256
	v_add_co_u32_e32 v148, vcc, s4, v52
	s_mov_b32 s4, 0x9b000
	s_nop 0
	v_addc_co_u32_e32 v149, vcc, 0, v53, vcc
	global_load_ushort v150, v[148:149], off offset:3584
	v_add_co_u32_e32 v148, vcc, s4, v52
	s_mov_b32 s4, 0x9e000
	s_nop 0
	v_addc_co_u32_e32 v149, vcc, 0, v53, vcc
	v_add_co_u32_e32 v152, vcc, s4, v52
	s_mov_b32 s4, 0xa1000
	s_nop 0
	v_addc_co_u32_e32 v153, vcc, 0, v53, vcc
	global_load_ushort v130, v[148:149], off offset:3328
	global_load_ushort v147, v[148:149], off offset:2560
	s_nop 0
	global_load_ushort v148, v[152:153], off offset:2304
	global_load_ushort v149, v[152:153], off offset:1536
	v_add_co_u32_e32 v152, vcc, s4, v52
	s_mov_b32 s4, 0xa4000
	s_nop 0
	v_addc_co_u32_e32 v153, vcc, 0, v53, vcc
	v_add_co_u32_e32 v154, vcc, s4, v52
	s_mov_b32 s4, 0xa3000
	s_nop 0
	v_addc_co_u32_e32 v155, vcc, 0, v53, vcc
	global_load_ushort v151, v[152:153], off offset:1280
	s_nop 0
	global_load_ushort v152, v[152:153], off offset:512
	s_nop 0
	global_load_ushort v153, v[154:155], off offset:256
	v_add_co_u32_e32 v154, vcc, s4, v52
	s_mov_b32 s4, 0xa6000
	s_nop 0
	v_addc_co_u32_e32 v155, vcc, 0, v53, vcc
	v_add_co_u32_e32 v156, vcc, s4, v52
	s_mov_b32 s4, 0xa9000
	s_nop 0
	v_addc_co_u32_e32 v157, vcc, 0, v53, vcc
	v_add_co_u32_e32 v158, vcc, s4, v52
	s_mov_b32 s4, 0xac000
	s_nop 0
	v_addc_co_u32_e32 v159, vcc, 0, v53, vcc
	v_add_co_u32_e32 v164, vcc, s4, v52
	s_mov_b32 s4, 0xaf000
	s_nop 0
	v_addc_co_u32_e32 v165, vcc, 0, v53, vcc
	global_load_ushort v160, v[154:155], off offset:3584
	s_nop 0
	global_load_ushort v154, v[156:157], off offset:3328
	global_load_ushort v155, v[156:157], off offset:2560
	s_nop 0
	global_load_ushort v156, v[158:159], off offset:2304
	global_load_ushort v157, v[158:159], off offset:1536
	s_nop 0
	global_load_ushort v158, v[164:165], off offset:1280
	global_load_ushort v159, v[164:165], off offset:512
	v_add_co_u32_e32 v164, vcc, s4, v52
	s_mov_b32 s4, 0xae000
	s_nop 0
	v_addc_co_u32_e32 v165, vcc, 0, v53, vcc
	v_add_co_u32_e32 v52, vcc, s4, v52
	global_load_ushort v161, v[164:165], off offset:256
	s_nop 0
	v_addc_co_u32_e32 v53, vcc, 0, v53, vcc
	global_load_ushort v52, v[52:53], off offset:3584
	v_add_co_u32_e32 v164, vcc, s62, v56
	v_cvt_pk_bf16_f32 v53, v91, s0
	s_nop 0
	v_addc_co_u32_e32 v165, vcc, 0, v57, vcc
	v_and_b32_e32 v250, s31, v53
	v_mul_f32_e32 v53, v98, v91
	v_cvt_pk_bf16_f32 v53, v53, s0
	ds_write_b16 v162, v53 offset:4096
	v_mul_f32_e32 v53, 0x3fb8aa3b, v62
	v_mul_f32_e32 v62, 0xbfb8aa3b, v62
	v_exp_f32_e32 v62, v62
	v_exp_f32_e32 v53, v53
	v_and_b32_e32 v204, s31, v93
	s_waitcnt vmcnt(40)
	v_lshlrev_b32_e32 v91, 16, v115
	v_lshlrev_b32_e32 v93, 16, v116
	v_mul_f32_e32 v62, v62, v91
	v_mul_f32_e32 v91, 0x3e000000, v93
	v_mul_f32_e32 v53, v53, v91
	v_cvt_pk_bf16_f32 v53, v53, s0
	v_lshl_or_b32 v204, v53, 16, v204
	v_cvt_pk_bf16_f32 v53, v62, s0
	v_lshl_or_b32 v250, v53, 16, v250
	v_mul_f32_e32 v53, v98, v62
	v_cvt_pk_bf16_f32 v53, v53, s0
	v_mul_f32_e32 v62, 0xbfb8aa3b, v63
	ds_write_b16 v162, v53 offset:4224
	v_mul_f32_e32 v53, 0x3fb8aa3b, v63
	v_exp_f32_e32 v62, v62
	v_exp_f32_e32 v53, v53
	v_lshlrev_b32_e32 v63, 16, v117
	v_lshlrev_b32_e32 v91, 16, v118
	v_mul_f32_e32 v62, v62, v63
	v_mul_f32_e32 v63, 0x3e000000, v91
	v_mul_f32_e32 v53, v53, v63
	v_cvt_pk_bf16_f32 v53, v53, s0
	v_and_b32_e32 v205, s31, v53
	v_cvt_pk_bf16_f32 v53, v62, s0
	v_and_b32_e32 v251, s31, v53
	v_mul_f32_e32 v53, v98, v62
	v_cvt_pk_bf16_f32 v53, v53, s0
	v_mul_f32_e32 v62, 0xbfb8aa3b, v64
	ds_write_b16 v113, v53 offset:4352
	v_mul_f32_e32 v53, 0x3fb8aa3b, v64
	v_exp_f32_e32 v62, v62
	v_exp_f32_e32 v53, v53
	v_lshlrev_b32_e32 v63, 16, v119
	v_lshlrev_b32_e32 v64, 16, v120
	v_mul_f32_e32 v62, v62, v63
	v_mul_f32_e32 v63, 0x3e000000, v64
	v_mul_f32_e32 v53, v53, v63
	v_cvt_pk_bf16_f32 v53, v53, s0
	v_lshl_or_b32 v205, v53, 16, v205
	s_nop 1
	v_mov_b32_dpp v196, v204 quad_perm:[1,0,3,2] row_mask:0xf bank_mask:0xf
	v_mov_b32_dpp v199, v205 quad_perm:[1,0,3,2] row_mask:0xf bank_mask:0xf
	v_alignbit_b32 v196, v196, v196, 16
	v_alignbit_b32 v199, v199, v199, 16
	v_bfi_b32 v197, v195, v204, v196
	v_bfi_b32 v198, v195, v205, v199
	s_nop 1
	v_mov_b32_dpp v199, v197 quad_perm:[2,3,0,1] row_mask:0xf bank_mask:0xf
	v_mov_b32_dpp v200, v198 quad_perm:[2,3,0,1] row_mask:0xf bank_mask:0xf
	v_cndmask_b32_e64 v202, v197, v200, s[34:35]
	v_cndmask_b32_e64 v203, v199, v198, s[34:35]
	v_add_u32_e32 v201, 0x6000, v194
	global_store_dwordx2 v201, v[202:203], s[8:9]
	v_cvt_pk_bf16_f32 v53, v62, s0
	v_lshl_or_b32 v251, v53, 16, v251
	s_nop 1
	v_mov_b32_dpp v196, v250 quad_perm:[1,0,3,2] row_mask:0xf bank_mask:0xf
	v_mov_b32_dpp v199, v251 quad_perm:[1,0,3,2] row_mask:0xf bank_mask:0xf
	v_alignbit_b32 v196, v196, v196, 16
	v_alignbit_b32 v199, v199, v199, 16
	v_bfi_b32 v197, v195, v250, v196
	v_bfi_b32 v198, v195, v251, v199
	s_nop 1
	v_mov_b32_dpp v199, v197 quad_perm:[2,3,0,1] row_mask:0xf bank_mask:0xf
	v_mov_b32_dpp v200, v198 quad_perm:[2,3,0,1] row_mask:0xf bank_mask:0xf
	v_cndmask_b32_e64 v202, v197, v200, s[34:35]
	v_cndmask_b32_e64 v203, v199, v198, s[34:35]
	v_add_u32_e32 v201, 0x6000, v194
	global_store_dwordx2 v201, v[202:203], s[10:11]
	v_mul_f32_e32 v53, v98, v62
	v_cvt_pk_bf16_f32 v53, v53, s0
	v_mul_f32_e32 v62, 0xbfb8aa3b, v65
	ds_write_b16 v113, v53 offset:4480
	v_mul_f32_e32 v53, 0x3fb8aa3b, v65
	v_exp_f32_e32 v62, v62
	v_exp_f32_e32 v53, v53
	v_lshlrev_b32_e32 v63, 16, v121
	v_lshlrev_b32_e32 v64, 16, v122
	v_mul_f32_e32 v62, v62, v63
	v_mul_f32_e32 v63, 0x3e000000, v64
	v_mul_f32_e32 v53, v53, v63
	v_cvt_pk_bf16_f32 v53, v53, s0
	v_and_b32_e32 v206, s31, v53
	v_cvt_pk_bf16_f32 v53, v62, s0
	v_and_b32_e32 v208, s31, v53
	v_mul_f32_e32 v53, v98, v62
	v_cvt_pk_bf16_f32 v53, v53, s0
	v_mul_f32_e32 v62, 0xbfb8aa3b, v66
	ds_write_b16 v162, v53 offset:4608
	v_mul_f32_e32 v53, 0x3fb8aa3b, v66
	v_exp_f32_e32 v62, v62
	v_exp_f32_e32 v53, v53
	v_lshlrev_b32_e32 v63, 16, v123
	v_lshlrev_b32_e32 v64, 16, v124
	v_mul_f32_e32 v62, v62, v63
	v_mul_f32_e32 v63, 0x3e000000, v64
	v_mul_f32_e32 v53, v53, v63
	v_cvt_pk_bf16_f32 v53, v53, s0
	v_lshl_or_b32 v206, v53, 16, v206
	v_cvt_pk_bf16_f32 v53, v62, s0
	v_lshl_or_b32 v208, v53, 16, v208
	v_mul_f32_e32 v53, v98, v62
	v_cvt_pk_bf16_f32 v53, v53, s0
	v_mul_f32_e32 v58, 0xbfb8aa3b, v67
	ds_write_b16 v162, v53 offset:4736
	v_mul_f32_e32 v53, 0x3fb8aa3b, v67
	v_exp_f32_e32 v58, v58
	v_exp_f32_e32 v53, v53
	v_lshlrev_b32_e32 v59, 16, v126
	v_lshlrev_b32_e32 v62, 16, v127
	v_mul_f32_e32 v64, v58, v59
	v_mul_f32_e32 v58, 0x3e000000, v62
	v_mul_f32_e32 v53, v53, v58
	v_add_co_u32_e32 v58, vcc, s41, v54
	v_cvt_pk_bf16_f32 v53, v53, s0
	s_nop 0
	v_addc_co_u32_e32 v59, vcc, 0, v55, vcc
	v_add_co_u32_e32 v62, vcc, s41, v56
	v_and_b32_e32 v207, s31, v53
	v_cvt_pk_bf16_f32 v53, v64, s0
	v_addc_co_u32_e32 v63, vcc, 0, v57, vcc
	v_and_b32_e32 v209, s31, v53
	v_mul_f32_e32 v53, v98, v64
	v_cvt_pk_bf16_f32 v53, v53, s0
	ds_write_b16 v113, v53 offset:4864
	v_mul_f32_e32 v53, 0x3fb8aa3b, v61
	v_mul_f32_e32 v61, 0xbfb8aa3b, v61
	v_exp_f32_e32 v61, v61
	v_exp_f32_e32 v53, v53
	v_lshlrev_b32_e32 v64, 16, v125
	v_lshlrev_b32_e32 v65, 16, v135
	v_mul_f32_e32 v61, v61, v64
	v_mul_f32_e32 v64, 0x3e000000, v65
	v_mul_f32_e32 v53, v53, v64
	v_cvt_pk_bf16_f32 v53, v53, s0
	v_lshl_or_b32 v207, v53, 16, v207
	s_nop 1
	v_mov_b32_dpp v196, v206 quad_perm:[1,0,3,2] row_mask:0xf bank_mask:0xf
	v_mov_b32_dpp v199, v207 quad_perm:[1,0,3,2] row_mask:0xf bank_mask:0xf
	v_alignbit_b32 v196, v196, v196, 16
	v_alignbit_b32 v199, v199, v199, 16
	v_bfi_b32 v197, v195, v206, v196
	v_bfi_b32 v198, v195, v207, v199
	s_nop 1
	v_mov_b32_dpp v199, v197 quad_perm:[2,3,0,1] row_mask:0xf bank_mask:0xf
	v_mov_b32_dpp v200, v198 quad_perm:[2,3,0,1] row_mask:0xf bank_mask:0xf
	v_cndmask_b32_e64 v202, v197, v200, s[34:35]
	v_cndmask_b32_e64 v203, v199, v198, s[34:35]
	v_add_u32_e32 v201, 0x6c00, v194
	global_store_dwordx2 v201, v[202:203], s[8:9]
	v_cvt_pk_bf16_f32 v53, v61, s0
	v_lshl_or_b32 v209, v53, 16, v209
	s_nop 1
	v_mov_b32_dpp v196, v208 quad_perm:[1,0,3,2] row_mask:0xf bank_mask:0xf
	v_mov_b32_dpp v199, v209 quad_perm:[1,0,3,2] row_mask:0xf bank_mask:0xf
	v_alignbit_b32 v196, v196, v196, 16
	v_alignbit_b32 v199, v199, v199, 16
	v_bfi_b32 v197, v195, v208, v196
	v_bfi_b32 v198, v195, v209, v199
	s_nop 1
	v_mov_b32_dpp v199, v197 quad_perm:[2,3,0,1] row_mask:0xf bank_mask:0xf
	v_mov_b32_dpp v200, v198 quad_perm:[2,3,0,1] row_mask:0xf bank_mask:0xf
	v_cndmask_b32_e64 v202, v197, v200, s[34:35]
	v_cndmask_b32_e64 v203, v199, v198, s[34:35]
	v_add_u32_e32 v201, 0x6c00, v194
	global_store_dwordx2 v201, v[202:203], s[10:11]
	v_mul_f32_e32 v53, v98, v61
	v_cvt_pk_bf16_f32 v53, v53, s0
	v_mul_f32_e32 v61, 0xbfb8aa3b, v68
	ds_write_b16 v113, v53 offset:4992
	v_mul_f32_e32 v53, 0x3fb8aa3b, v68
	v_exp_f32_e32 v61, v61
	v_exp_f32_e32 v53, v53
	v_lshlrev_b32_e32 v64, 16, v131
	v_lshlrev_b32_e32 v65, 16, v132
	v_mul_f32_e32 v61, v61, v64
	v_mul_f32_e32 v64, 0x3e000000, v65
	v_mul_f32_e32 v53, v53, v64
	v_cvt_pk_bf16_f32 v53, v53, s0
	v_and_b32_e32 v212, s31, v53
	v_cvt_pk_bf16_f32 v53, v61, s0
	v_and_b32_e32 v214, s31, v53
	v_mul_f32_e32 v53, v98, v61
	v_cvt_pk_bf16_f32 v53, v53, s0
	v_mul_f32_e32 v61, 0xbfb8aa3b, v69
	ds_write_b16 v4, v53 offset:5120
	v_mul_f32_e32 v53, 0x3fb8aa3b, v69
	v_exp_f32_e32 v61, v61
	v_exp_f32_e32 v53, v53
	v_lshlrev_b32_e32 v64, 16, v133
	v_lshlrev_b32_e32 v65, 16, v134
	v_mul_f32_e32 v61, v61, v64
	v_mul_f32_e32 v64, 0x3e000000, v65
	v_mul_f32_e32 v53, v53, v64
	v_cvt_pk_bf16_f32 v53, v53, s0
	v_lshl_or_b32 v212, v53, 16, v212
	v_cvt_pk_bf16_f32 v53, v61, s0
	v_lshl_or_b32 v214, v53, 16, v214
	v_mul_f32_e32 v53, v98, v61
	v_cvt_pk_bf16_f32 v53, v53, s0
	v_mul_f32_e32 v61, 0xbfb8aa3b, v73
	ds_write_b16 v4, v53 offset:5248
	v_mul_f32_e32 v53, 0x3fb8aa3b, v73
	v_exp_f32_e32 v61, v61
	v_exp_f32_e32 v53, v53
	v_lshlrev_b32_e32 v64, 16, v136
	v_lshlrev_b32_e32 v65, 16, v137
	v_mul_f32_e32 v61, v61, v64
	v_mul_f32_e32 v64, 0x3e000000, v65
	v_mul_f32_e32 v53, v53, v64
	v_cvt_pk_bf16_f32 v53, v53, s0
	v_and_b32_e32 v213, s31, v53
	v_cvt_pk_bf16_f32 v53, v61, s0
	v_and_b32_e32 v215, s31, v53
	v_mul_f32_e32 v53, v98, v61
	v_cvt_pk_bf16_f32 v53, v53, s0
	v_mul_f32_e32 v58, 0xbfb8aa3b, v74
	ds_write_b16 v114, v53 offset:5376
	v_mul_f32_e32 v53, 0x3fb8aa3b, v74
	v_exp_f32_e32 v58, v58
	v_exp_f32_e32 v53, v53
	v_lshlrev_b32_e32 v59, 16, v128
	v_lshlrev_b32_e32 v61, 16, v144
	v_mul_f32_e32 v64, v58, v59
	v_mul_f32_e32 v58, 0x3e000000, v61
	v_mul_f32_e32 v53, v53, v58
	v_add_co_u32_e32 v58, vcc, s49, v54
	v_cvt_pk_bf16_f32 v53, v53, s0
	s_nop 0
	v_addc_co_u32_e32 v59, vcc, 0, v55, vcc
	v_add_co_u32_e32 v62, vcc, s49, v56
	v_lshl_or_b32 v213, v53, 16, v213
	s_nop 1
	v_mov_b32_dpp v196, v212 quad_perm:[1,0,3,2] row_mask:0xf bank_mask:0xf
	v_mov_b32_dpp v199, v213 quad_perm:[1,0,3,2] row_mask:0xf bank_mask:0xf
	v_alignbit_b32 v196, v196, v196, 16
	v_alignbit_b32 v199, v199, v199, 16
	v_bfi_b32 v197, v195, v212, v196
	v_bfi_b32 v198, v195, v213, v199
	s_nop 1
	v_mov_b32_dpp v199, v197 quad_perm:[2,3,0,1] row_mask:0xf bank_mask:0xf
	v_mov_b32_dpp v200, v198 quad_perm:[2,3,0,1] row_mask:0xf bank_mask:0xf
	v_cndmask_b32_e64 v202, v197, v200, s[34:35]
	v_cndmask_b32_e64 v203, v199, v198, s[34:35]
	v_add_u32_e32 v201, 0x7800, v194
	global_store_dwordx2 v201, v[202:203], s[8:9]
	v_cvt_pk_bf16_f32 v53, v64, s0
	v_addc_co_u32_e32 v63, vcc, 0, v57, vcc
	v_lshl_or_b32 v215, v53, 16, v215
	s_nop 1
	v_mov_b32_dpp v196, v214 quad_perm:[1,0,3,2] row_mask:0xf bank_mask:0xf
	v_mov_b32_dpp v199, v215 quad_perm:[1,0,3,2] row_mask:0xf bank_mask:0xf
	v_alignbit_b32 v196, v196, v196, 16
	v_alignbit_b32 v199, v199, v199, 16
	v_bfi_b32 v197, v195, v214, v196
	v_bfi_b32 v198, v195, v215, v199
	s_nop 1
	v_mov_b32_dpp v199, v197 quad_perm:[2,3,0,1] row_mask:0xf bank_mask:0xf
	v_mov_b32_dpp v200, v198 quad_perm:[2,3,0,1] row_mask:0xf bank_mask:0xf
	v_cndmask_b32_e64 v202, v197, v200, s[34:35]
	v_cndmask_b32_e64 v203, v199, v198, s[34:35]
	v_add_u32_e32 v201, 0x7800, v194
	global_store_dwordx2 v201, v[202:203], s[10:11]
	v_mul_f32_e32 v53, v98, v64
	v_cvt_pk_bf16_f32 v53, v53, s0
	v_mul_f32_e32 v61, 0xbfb8aa3b, v75
	ds_write_b16 v114, v53 offset:5504
	v_mul_f32_e32 v53, 0x3fb8aa3b, v75
	v_exp_f32_e32 v61, v61
	v_exp_f32_e32 v53, v53
	v_lshlrev_b32_e32 v64, 16, v138
	v_lshlrev_b32_e32 v65, 16, v139
	v_mul_f32_e32 v61, v61, v64
	v_mul_f32_e32 v64, 0x3e000000, v65
	v_mul_f32_e32 v53, v53, v64
	v_cvt_pk_bf16_f32 v53, v53, s0
	v_and_b32_e32 v216, s31, v53
	v_cvt_pk_bf16_f32 v53, v61, s0
	v_and_b32_e32 v218, s31, v53
	v_mul_f32_e32 v53, v98, v61
	v_cvt_pk_bf16_f32 v53, v53, s0
	v_mul_f32_e32 v61, 0xbfb8aa3b, v76
	ds_write_b16 v4, v53 offset:5632
	v_mul_f32_e32 v53, 0x3fb8aa3b, v76
	v_exp_f32_e32 v61, v61
	v_exp_f32_e32 v53, v53
	v_lshlrev_b32_e32 v64, 16, v140
	v_lshlrev_b32_e32 v65, 16, v141
	v_mul_f32_e32 v61, v61, v64
	v_mul_f32_e32 v64, 0x3e000000, v65
	v_mul_f32_e32 v53, v53, v64
	v_cvt_pk_bf16_f32 v53, v53, s0
	v_lshl_or_b32 v216, v53, 16, v216
	v_cvt_pk_bf16_f32 v53, v61, s0
	v_lshl_or_b32 v218, v53, 16, v218
	v_mul_f32_e32 v53, v98, v61
	v_cvt_pk_bf16_f32 v53, v53, s0
	v_mul_f32_e32 v61, 0xbfb8aa3b, v77
	ds_write_b16 v4, v53 offset:5760
	v_mul_f32_e32 v53, 0x3fb8aa3b, v77
	v_exp_f32_e32 v61, v61
	v_exp_f32_e32 v53, v53
	v_lshlrev_b32_e32 v64, 16, v142
	v_lshlrev_b32_e32 v65, 16, v143
	v_mul_f32_e32 v61, v61, v64
	v_mul_f32_e32 v64, 0x3e000000, v65
	v_mul_f32_e32 v53, v53, v64
	v_cvt_pk_bf16_f32 v53, v53, s0
	v_and_b32_e32 v217, s31, v53
	v_cvt_pk_bf16_f32 v53, v61, s0
	v_and_b32_e32 v219, s31, v53
	v_mul_f32_e32 v53, v98, v61
	v_cvt_pk_bf16_f32 v53, v53, s0
	v_mul_f32_e32 v61, 0xbfb8aa3b, v78
	ds_write_b16 v114, v53 offset:5888
	v_mul_f32_e32 v53, 0x3fb8aa3b, v78
	v_exp_f32_e32 v61, v61
	v_exp_f32_e32 v53, v53
	v_lshlrev_b32_e32 v64, 16, v145
	v_lshlrev_b32_e32 v65, 16, v146
	v_mul_f32_e32 v61, v61, v64
	v_mul_f32_e32 v64, 0x3e000000, v65
	v_mul_f32_e32 v53, v53, v64
	v_cvt_pk_bf16_f32 v53, v53, s0
	v_lshl_or_b32 v217, v53, 16, v217
	s_nop 1
	v_mov_b32_dpp v196, v216 quad_perm:[1,0,3,2] row_mask:0xf bank_mask:0xf
	v_mov_b32_dpp v199, v217 quad_perm:[1,0,3,2] row_mask:0xf bank_mask:0xf
	v_alignbit_b32 v196, v196, v196, 16
	v_alignbit_b32 v199, v199, v199, 16
	v_bfi_b32 v197, v195, v216, v196
	v_bfi_b32 v198, v195, v217, v199
	s_nop 1
	v_mov_b32_dpp v199, v197 quad_perm:[2,3,0,1] row_mask:0xf bank_mask:0xf
	v_mov_b32_dpp v200, v198 quad_perm:[2,3,0,1] row_mask:0xf bank_mask:0xf
	v_cndmask_b32_e64 v202, v197, v200, s[34:35]
	v_cndmask_b32_e64 v203, v199, v198, s[34:35]
	v_add_u32_e32 v201, 0x8400, v194
	global_store_dwordx2 v201, v[202:203], s[8:9]
	v_cvt_pk_bf16_f32 v53, v61, s0
	v_lshl_or_b32 v219, v53, 16, v219
	s_nop 1
	v_mov_b32_dpp v196, v218 quad_perm:[1,0,3,2] row_mask:0xf bank_mask:0xf
	v_mov_b32_dpp v199, v219 quad_perm:[1,0,3,2] row_mask:0xf bank_mask:0xf
	v_alignbit_b32 v196, v196, v196, 16
	v_alignbit_b32 v199, v199, v199, 16
	v_bfi_b32 v197, v195, v218, v196
	v_bfi_b32 v198, v195, v219, v199
	s_nop 1
	v_mov_b32_dpp v199, v197 quad_perm:[2,3,0,1] row_mask:0xf bank_mask:0xf
	v_mov_b32_dpp v200, v198 quad_perm:[2,3,0,1] row_mask:0xf bank_mask:0xf
	v_cndmask_b32_e64 v202, v197, v200, s[34:35]
	v_cndmask_b32_e64 v203, v199, v198, s[34:35]
	v_add_u32_e32 v201, 0x8400, v194
	global_store_dwordx2 v201, v[202:203], s[10:11]
	v_mul_f32_e32 v53, v98, v61
	v_cvt_pk_bf16_f32 v53, v53, s0
	v_mul_f32_e32 v58, 0xbfb8aa3b, v79
	ds_write_b16 v114, v53 offset:6016
	v_mul_f32_e32 v53, 0x3fb8aa3b, v79
	v_exp_f32_e32 v58, v58
	v_exp_f32_e32 v53, v53
	s_waitcnt vmcnt(38)
	v_lshlrev_b32_e32 v59, 16, v95
	v_lshlrev_b32_e32 v61, 16, v97
	v_mul_f32_e32 v64, v58, v59
	v_mul_f32_e32 v58, 0x3e000000, v61
	v_mul_f32_e32 v53, v53, v58
	v_add_co_u32_e32 v58, vcc, s93, v54
	v_cvt_pk_bf16_f32 v53, v53, s0
	s_nop 0
	v_addc_co_u32_e32 v59, vcc, 0, v55, vcc
	v_add_co_u32_e32 v62, vcc, s93, v56
	v_and_b32_e32 v220, s31, v53
	v_cvt_pk_bf16_f32 v53, v64, s0
	v_addc_co_u32_e32 v63, vcc, 0, v57, vcc
	v_and_b32_e32 v222, s31, v53
	v_mul_f32_e32 v53, v98, v64
	v_cvt_pk_bf16_f32 v53, v53, s0
	v_mul_f32_e32 v61, 0xbfb8aa3b, v80
	ds_write_b16 v162, v53 offset:6144
	v_mul_f32_e32 v53, 0x3fb8aa3b, v80
	v_exp_f32_e32 v61, v61
	v_exp_f32_e32 v53, v53
	s_waitcnt vmcnt(36)
	v_lshlrev_b32_e32 v64, 16, v100
	v_lshlrev_b32_e32 v65, 16, v101
	v_mul_f32_e32 v61, v61, v64
	v_mul_f32_e32 v64, 0x3e000000, v65
	v_mul_f32_e32 v53, v53, v64
	v_cvt_pk_bf16_f32 v53, v53, s0
	v_lshl_or_b32 v220, v53, 16, v220
	v_cvt_pk_bf16_f32 v53, v61, s0
	v_lshl_or_b32 v222, v53, 16, v222
	v_mul_f32_e32 v53, v98, v61
	v_cvt_pk_bf16_f32 v53, v53, s0
	v_mul_f32_e32 v61, 0xbfb8aa3b, v81
	ds_write_b16 v162, v53 offset:6272
	v_mul_f32_e32 v53, 0x3fb8aa3b, v81
	v_exp_f32_e32 v61, v61
	v_exp_f32_e32 v53, v53
	s_waitcnt vmcnt(34)
	v_lshlrev_b32_e32 v64, 16, v102
	v_lshlrev_b32_e32 v65, 16, v103
	v_mul_f32_e32 v61, v61, v64
	v_mul_f32_e32 v64, 0x3e000000, v65
	v_mul_f32_e32 v53, v53, v64
	v_cvt_pk_bf16_f32 v53, v53, s0
	v_and_b32_e32 v221, s31, v53
	v_cvt_pk_bf16_f32 v53, v61, s0
	v_and_b32_e32 v223, s31, v53
	v_mul_f32_e32 v53, v98, v61
	v_cvt_pk_bf16_f32 v53, v53, s0
	v_mul_f32_e32 v61, 0xbfb8aa3b, v82
	ds_write_b16 v113, v53 offset:6400
	v_mul_f32_e32 v53, 0x3fb8aa3b, v82
	v_exp_f32_e32 v61, v61
	v_exp_f32_e32 v53, v53
	s_waitcnt vmcnt(32)
	v_lshlrev_b32_e32 v64, 16, v104
	v_lshlrev_b32_e32 v65, 16, v129
	v_mul_f32_e32 v61, v61, v64
	v_mul_f32_e32 v64, 0x3e000000, v65
	v_mul_f32_e32 v53, v53, v64
	v_cvt_pk_bf16_f32 v53, v53, s0
	v_lshl_or_b32 v221, v53, 16, v221
	s_nop 1
	v_mov_b32_dpp v196, v220 quad_perm:[1,0,3,2] row_mask:0xf bank_mask:0xf
	v_mov_b32_dpp v199, v221 quad_perm:[1,0,3,2] row_mask:0xf bank_mask:0xf
	v_alignbit_b32 v196, v196, v196, 16
	v_alignbit_b32 v199, v199, v199, 16
	v_bfi_b32 v197, v195, v220, v196
	v_bfi_b32 v198, v195, v221, v199
	s_nop 1
	v_mov_b32_dpp v199, v197 quad_perm:[2,3,0,1] row_mask:0xf bank_mask:0xf
	v_mov_b32_dpp v200, v198 quad_perm:[2,3,0,1] row_mask:0xf bank_mask:0xf
	v_cndmask_b32_e64 v202, v197, v200, s[34:35]
	v_cndmask_b32_e64 v203, v199, v198, s[34:35]
	v_add_u32_e32 v201, 0x9000, v194
	global_store_dwordx2 v201, v[202:203], s[8:9]
	v_cvt_pk_bf16_f32 v53, v61, s0
	v_lshl_or_b32 v223, v53, 16, v223
	s_nop 1
	v_mov_b32_dpp v196, v222 quad_perm:[1,0,3,2] row_mask:0xf bank_mask:0xf
	v_mov_b32_dpp v199, v223 quad_perm:[1,0,3,2] row_mask:0xf bank_mask:0xf
	v_alignbit_b32 v196, v196, v196, 16
	v_alignbit_b32 v199, v199, v199, 16
	v_bfi_b32 v197, v195, v222, v196
	v_bfi_b32 v198, v195, v223, v199
	s_nop 1
	v_mov_b32_dpp v199, v197 quad_perm:[2,3,0,1] row_mask:0xf bank_mask:0xf
	v_mov_b32_dpp v200, v198 quad_perm:[2,3,0,1] row_mask:0xf bank_mask:0xf
	v_cndmask_b32_e64 v202, v197, v200, s[34:35]
	v_cndmask_b32_e64 v203, v199, v198, s[34:35]
	v_add_u32_e32 v201, 0x9000, v194
	global_store_dwordx2 v201, v[202:203], s[10:11]
	v_mul_f32_e32 v53, v98, v61
	v_cvt_pk_bf16_f32 v53, v53, s0
	v_mul_f32_e32 v61, 0xbfb8aa3b, v83
	ds_write_b16 v113, v53 offset:6528
	v_mul_f32_e32 v53, 0x3fb8aa3b, v83
	v_exp_f32_e32 v61, v61
	v_exp_f32_e32 v53, v53
	s_waitcnt vmcnt(32)
	v_lshlrev_b32_e32 v64, 16, v105
	v_lshlrev_b32_e32 v65, 16, v106
	v_mul_f32_e32 v61, v61, v64
	v_mul_f32_e32 v64, 0x3e000000, v65
	v_mul_f32_e32 v53, v53, v64
	v_cvt_pk_bf16_f32 v53, v53, s0
	v_and_b32_e32 v226, s31, v53
	v_cvt_pk_bf16_f32 v53, v61, s0
	v_and_b32_e32 v228, s31, v53
	v_mul_f32_e32 v53, v98, v61
	v_cvt_pk_bf16_f32 v53, v53, s0
	v_mul_f32_e32 v61, 0xbfb8aa3b, v84
	ds_write_b16 v162, v53 offset:6656
	v_mul_f32_e32 v53, 0x3fb8aa3b, v84
	v_exp_f32_e32 v61, v61
	v_exp_f32_e32 v53, v53
	s_waitcnt vmcnt(30)
	v_lshlrev_b32_e32 v64, 16, v107
	v_lshlrev_b32_e32 v65, 16, v109
	v_mul_f32_e32 v61, v61, v64
	v_mul_f32_e32 v64, 0x3e000000, v65
	v_mul_f32_e32 v53, v53, v64
	v_cvt_pk_bf16_f32 v53, v53, s0
	v_lshl_or_b32 v226, v53, 16, v226
	v_cvt_pk_bf16_f32 v53, v61, s0
	v_lshl_or_b32 v228, v53, 16, v228
	v_mul_f32_e32 v53, v98, v61
	v_cvt_pk_bf16_f32 v53, v53, s0
	v_mul_f32_e32 v58, 0xbfb8aa3b, v85
	ds_write_b16 v162, v53 offset:6784
	v_mul_f32_e32 v53, 0x3fb8aa3b, v85
	v_exp_f32_e32 v58, v58
	v_exp_f32_e32 v53, v53
	s_waitcnt vmcnt(28)
	v_lshlrev_b32_e32 v59, 16, v111
	v_lshlrev_b32_e32 v61, 16, v112
	v_mul_f32_e32 v64, v58, v59
	v_mul_f32_e32 v58, 0x3e000000, v61
	v_mul_f32_e32 v53, v53, v58
	v_add_co_u32_e32 v58, vcc, s50, v54
	v_cvt_pk_bf16_f32 v53, v53, s0
	s_nop 0
	v_addc_co_u32_e32 v59, vcc, 0, v55, vcc
	v_add_co_u32_e32 v62, vcc, s50, v56
	v_and_b32_e32 v227, s31, v53
	v_cvt_pk_bf16_f32 v53, v64, s0
	v_addc_co_u32_e32 v63, vcc, 0, v57, vcc
	v_and_b32_e32 v229, s31, v53
	v_mul_f32_e32 v53, v98, v64
	v_cvt_pk_bf16_f32 v53, v53, s0
	v_mul_f32_e32 v61, 0xbfb8aa3b, v86
	ds_write_b16 v113, v53 offset:6912
	v_mul_f32_e32 v53, 0x3fb8aa3b, v86
	v_exp_f32_e32 v61, v61
	v_exp_f32_e32 v53, v53
	s_waitcnt vmcnt(26)
	v_lshlrev_b32_e32 v64, 16, v110
	v_lshlrev_b32_e32 v65, 16, v150
	v_mul_f32_e32 v61, v61, v64
	v_mul_f32_e32 v64, 0x3e000000, v65
	v_mul_f32_e32 v53, v53, v64
	v_cvt_pk_bf16_f32 v53, v53, s0
	v_lshl_or_b32 v227, v53, 16, v227
	s_nop 1
	v_mov_b32_dpp v196, v226 quad_perm:[1,0,3,2] row_mask:0xf bank_mask:0xf
	v_mov_b32_dpp v199, v227 quad_perm:[1,0,3,2] row_mask:0xf bank_mask:0xf
	v_alignbit_b32 v196, v196, v196, 16
	v_alignbit_b32 v199, v199, v199, 16
	v_bfi_b32 v197, v195, v226, v196
	v_bfi_b32 v198, v195, v227, v199
	s_nop 1
	v_mov_b32_dpp v199, v197 quad_perm:[2,3,0,1] row_mask:0xf bank_mask:0xf
	v_mov_b32_dpp v200, v198 quad_perm:[2,3,0,1] row_mask:0xf bank_mask:0xf
	v_cndmask_b32_e64 v202, v197, v200, s[34:35]
	v_cndmask_b32_e64 v203, v199, v198, s[34:35]
	v_add_u32_e32 v201, 0x9c00, v194
	global_store_dwordx2 v201, v[202:203], s[8:9]
	v_cvt_pk_bf16_f32 v53, v61, s0
	v_lshl_or_b32 v229, v53, 16, v229
	s_nop 1
	v_mov_b32_dpp v196, v228 quad_perm:[1,0,3,2] row_mask:0xf bank_mask:0xf
	v_mov_b32_dpp v199, v229 quad_perm:[1,0,3,2] row_mask:0xf bank_mask:0xf
	v_alignbit_b32 v196, v196, v196, 16
	v_alignbit_b32 v199, v199, v199, 16
	v_bfi_b32 v197, v195, v228, v196
	v_bfi_b32 v198, v195, v229, v199
	s_nop 1
	v_mov_b32_dpp v199, v197 quad_perm:[2,3,0,1] row_mask:0xf bank_mask:0xf
	v_mov_b32_dpp v200, v198 quad_perm:[2,3,0,1] row_mask:0xf bank_mask:0xf
	v_cndmask_b32_e64 v202, v197, v200, s[34:35]
	v_cndmask_b32_e64 v203, v199, v198, s[34:35]
	v_add_u32_e32 v201, 0x9c00, v194
	global_store_dwordx2 v201, v[202:203], s[10:11]
	v_mul_f32_e32 v53, v98, v61
	v_cvt_pk_bf16_f32 v53, v53, s0
	v_mul_f32_e32 v61, 0xbfb8aa3b, v87
	ds_write_b16 v113, v53 offset:7040
	v_mul_f32_e32 v53, 0x3fb8aa3b, v87
	v_exp_f32_e32 v61, v61
	v_exp_f32_e32 v53, v53
	s_waitcnt vmcnt(26)
	v_lshlrev_b32_e32 v64, 16, v130
	v_lshlrev_b32_e32 v65, 16, v147
	v_mul_f32_e32 v61, v61, v64
	v_mul_f32_e32 v64, 0x3e000000, v65
	v_mul_f32_e32 v53, v53, v64
	v_cvt_pk_bf16_f32 v53, v53, s0
	v_and_b32_e32 v230, s31, v53
	v_cvt_pk_bf16_f32 v53, v61, s0
	v_and_b32_e32 v236, s31, v53
	v_mul_f32_e32 v53, v98, v61
	v_cvt_pk_bf16_f32 v53, v53, s0
	v_mul_f32_e32 v61, 0xbfb8aa3b, v88
	ds_write_b16 v4, v53 offset:7168
	v_mul_f32_e32 v53, 0x3fb8aa3b, v88
	v_exp_f32_e32 v61, v61
	v_exp_f32_e32 v53, v53
	s_waitcnt vmcnt(24)
	v_lshlrev_b32_e32 v64, 16, v148
	v_lshlrev_b32_e32 v65, 16, v149
	v_mul_f32_e32 v61, v61, v64
	v_mul_f32_e32 v64, 0x3e000000, v65
	v_mul_f32_e32 v53, v53, v64
	v_cvt_pk_bf16_f32 v53, v53, s0
	v_lshl_or_b32 v230, v53, 16, v230
	v_cvt_pk_bf16_f32 v53, v61, s0
	v_lshl_or_b32 v236, v53, 16, v236
	v_mul_f32_e32 v53, v98, v61
	v_cvt_pk_bf16_f32 v53, v53, s0
	v_mul_f32_e32 v61, 0xbfb8aa3b, v89
	ds_write_b16 v4, v53 offset:7296
	v_mul_f32_e32 v53, 0x3fb8aa3b, v89
	v_exp_f32_e32 v61, v61
	v_exp_f32_e32 v53, v53
	s_waitcnt vmcnt(22)
	v_lshlrev_b32_e32 v64, 16, v151
	v_lshlrev_b32_e32 v65, 16, v152
	v_mul_f32_e32 v61, v61, v64
	v_mul_f32_e32 v64, 0x3e000000, v65
	v_mul_f32_e32 v53, v53, v64
	v_cvt_pk_bf16_f32 v53, v53, s0
	v_and_b32_e32 v231, s31, v53
	v_cvt_pk_bf16_f32 v53, v61, s0
	v_and_b32_e32 v237, s31, v53
	v_mul_f32_e32 v53, v98, v61
	v_cvt_pk_bf16_f32 v53, v53, s0
	v_mul_f32_e32 v58, 0xbfb8aa3b, v90
	ds_write_b16 v114, v53 offset:7424
	v_mul_f32_e32 v53, 0x3fb8aa3b, v90
	v_exp_f32_e32 v58, v58
	v_exp_f32_e32 v53, v53
	s_waitcnt vmcnt(20)
	v_lshlrev_b32_e32 v59, 16, v153
	v_lshlrev_b32_e32 v61, 16, v160
	v_mul_f32_e32 v58, v58, v59
	v_mul_f32_e32 v59, 0x3e000000, v61
	v_add_co_u32_e32 v54, vcc, s53, v54
	v_mul_f32_e32 v53, v53, v59
	s_nop 0
	v_addc_co_u32_e32 v55, vcc, 0, v55, vcc
	v_cvt_pk_bf16_f32 v53, v53, s0
	v_add_co_u32_e32 v56, vcc, s53, v56
	v_lshl_or_b32 v231, v53, 16, v231
	s_nop 1
	v_mov_b32_dpp v196, v230 quad_perm:[1,0,3,2] row_mask:0xf bank_mask:0xf
	v_mov_b32_dpp v199, v231 quad_perm:[1,0,3,2] row_mask:0xf bank_mask:0xf
	v_alignbit_b32 v196, v196, v196, 16
	v_alignbit_b32 v199, v199, v199, 16
	v_bfi_b32 v197, v195, v230, v196
	v_bfi_b32 v198, v195, v231, v199
	s_nop 1
	v_mov_b32_dpp v199, v197 quad_perm:[2,3,0,1] row_mask:0xf bank_mask:0xf
	v_mov_b32_dpp v200, v198 quad_perm:[2,3,0,1] row_mask:0xf bank_mask:0xf
	v_cndmask_b32_e64 v202, v197, v200, s[34:35]
	v_cndmask_b32_e64 v203, v199, v198, s[34:35]
	v_add_u32_e32 v201, 0xa800, v194
	global_store_dwordx2 v201, v[202:203], s[8:9]
	v_cvt_pk_bf16_f32 v53, v58, s0
	v_addc_co_u32_e32 v57, vcc, 0, v57, vcc
	v_lshl_or_b32 v237, v53, 16, v237
	s_nop 1
	v_mov_b32_dpp v196, v236 quad_perm:[1,0,3,2] row_mask:0xf bank_mask:0xf
	v_mov_b32_dpp v199, v237 quad_perm:[1,0,3,2] row_mask:0xf bank_mask:0xf
	v_alignbit_b32 v196, v196, v196, 16
	v_alignbit_b32 v199, v199, v199, 16
	v_bfi_b32 v197, v195, v236, v196
	v_bfi_b32 v198, v195, v237, v199
	s_nop 1
	v_mov_b32_dpp v199, v197 quad_perm:[2,3,0,1] row_mask:0xf bank_mask:0xf
	v_mov_b32_dpp v200, v198 quad_perm:[2,3,0,1] row_mask:0xf bank_mask:0xf
	v_cndmask_b32_e64 v202, v197, v200, s[34:35]
	v_cndmask_b32_e64 v203, v199, v198, s[34:35]
	v_add_u32_e32 v201, 0xa800, v194
	global_store_dwordx2 v201, v[202:203], s[10:11]
	v_mul_f32_e32 v53, v98, v58
	v_cvt_pk_bf16_f32 v53, v53, s0
	v_mul_f32_e32 v58, 0xbfb8aa3b, v92
	ds_write_b16 v114, v53 offset:7552
	v_mul_f32_e32 v53, 0x3fb8aa3b, v92
	v_exp_f32_e32 v58, v58
	v_exp_f32_e32 v53, v53
	s_waitcnt vmcnt(20)
	v_lshlrev_b32_e32 v59, 16, v154
	v_lshlrev_b32_e32 v61, 16, v155
	v_mul_f32_e32 v58, v58, v59
	v_mul_f32_e32 v59, 0x3e000000, v61
	v_mul_f32_e32 v53, v53, v59
	v_cvt_pk_bf16_f32 v53, v53, s0
	v_and_b32_e32 v224, s31, v53
	v_cvt_pk_bf16_f32 v53, v58, s0
	v_and_b32_e32 v238, s31, v53
	v_mul_f32_e32 v53, v98, v58
	v_cvt_pk_bf16_f32 v53, v53, s0
	v_mul_f32_e32 v58, 0xbfb8aa3b, v94
	ds_write_b16 v4, v53 offset:7680
	v_mul_f32_e32 v53, 0x3fb8aa3b, v94
	v_exp_f32_e32 v58, v58
	v_exp_f32_e32 v53, v53
	s_waitcnt vmcnt(18)
	v_lshlrev_b32_e32 v59, 16, v156
	v_lshlrev_b32_e32 v61, 16, v157
	v_mul_f32_e32 v58, v58, v59
	v_mul_f32_e32 v59, 0x3e000000, v61
	v_mul_f32_e32 v53, v53, v59
	v_cvt_pk_bf16_f32 v53, v53, s0
	v_lshl_or_b32 v224, v53, 16, v224
	v_cvt_pk_bf16_f32 v53, v58, s0
	v_lshl_or_b32 v238, v53, 16, v238
	v_mul_f32_e32 v53, v98, v58
	v_cvt_pk_bf16_f32 v53, v53, s0
	ds_write_b16 v4, v53 offset:7808
	v_mul_f32_e32 v53, 0xbfb8aa3b, v96
	v_mul_f32_e32 v4, 0x3fb8aa3b, v96
	v_exp_f32_e32 v53, v53
	v_exp_f32_e32 v4, v4
	s_waitcnt vmcnt(16)
	v_lshlrev_b32_e32 v58, 16, v158
	v_lshlrev_b32_e32 v59, 16, v159
	v_mul_f32_e32 v53, v53, v58
	v_mul_f32_e32 v58, 0x3e000000, v59
	v_mul_f32_e32 v4, v4, v58
	v_cvt_pk_bf16_f32 v4, v4, s0
	v_and_b32_e32 v225, s31, v4
	v_cvt_pk_bf16_f32 v4, v53, s0
	v_and_b32_e32 v239, s31, v4
	v_mul_f32_e32 v4, v98, v53
	v_cvt_pk_bf16_f32 v4, v4, s0
	ds_write_b16 v114, v4 offset:7936
	v_mul_f32_e32 v4, 0xbfb8aa3b, v99
	v_exp_f32_e32 v4, v4
	s_waitcnt vmcnt(14)
	v_lshlrev_b32_e32 v52, 16, v52
	v_mul_f32_e32 v52, 0x3e000000, v52
	v_lshlrev_b32_e32 v53, 16, v161
	v_mul_f32_e32 v52, v98, v52
	v_mul_f32_e32 v4, v4, v53
	v_cvt_pk_bf16_f32 v52, v52, s0
	v_lshl_or_b32 v225, v52, 16, v225
	s_nop 1
	v_mov_b32_dpp v196, v224 quad_perm:[1,0,3,2] row_mask:0xf bank_mask:0xf
	v_mov_b32_dpp v199, v225 quad_perm:[1,0,3,2] row_mask:0xf bank_mask:0xf
	v_alignbit_b32 v196, v196, v196, 16
	v_alignbit_b32 v199, v199, v199, 16
	v_bfi_b32 v197, v195, v224, v196
	v_bfi_b32 v198, v195, v225, v199
	s_nop 1
	v_mov_b32_dpp v199, v197 quad_perm:[2,3,0,1] row_mask:0xf bank_mask:0xf
	v_mov_b32_dpp v200, v198 quad_perm:[2,3,0,1] row_mask:0xf bank_mask:0xf
	v_cndmask_b32_e64 v202, v197, v200, s[34:35]
	v_cndmask_b32_e64 v203, v199, v198, s[34:35]
	v_add_u32_e32 v201, 0xb400, v194
	global_store_dwordx2 v201, v[202:203], s[8:9]
	v_cvt_pk_bf16_f32 v52, v4, s0
	v_mul_f32_e32 v4, v98, v4
	s_lshl_b64 s[4:5], s[6:7], 15
	v_cvt_pk_bf16_f32 v4, v4, s0
	s_add_u32 s4, s19, s4
	ds_write_b16 v114, v4 offset:8064
	s_addc_u32 s5, s20, s5
	v_lshlrev_b32_e32 v4, 8, v71
	v_lshl_or_b32 v239, v52, 16, v239
	s_nop 1
	v_mov_b32_dpp v196, v238 quad_perm:[1,0,3,2] row_mask:0xf bank_mask:0xf
	v_mov_b32_dpp v199, v239 quad_perm:[1,0,3,2] row_mask:0xf bank_mask:0xf
	v_alignbit_b32 v196, v196, v196, 16
	v_alignbit_b32 v199, v199, v199, 16
	v_bfi_b32 v197, v195, v238, v196
	v_bfi_b32 v198, v195, v239, v199
	s_nop 1
	v_mov_b32_dpp v199, v197 quad_perm:[2,3,0,1] row_mask:0xf bank_mask:0xf
	v_mov_b32_dpp v200, v198 quad_perm:[2,3,0,1] row_mask:0xf bank_mask:0xf
	v_cndmask_b32_e64 v202, v197, v200, s[34:35]
	v_cndmask_b32_e64 v203, v199, v198, s[34:35]
	v_add_u32_e32 v201, 0xb400, v194
	global_store_dwordx2 v201, v[202:203], s[10:11]
	v_lshl_add_u64 v[52:53], s[4:5], 0, v[4:5]
	v_and_b32_e32 v4, 48, v108
	v_lshl_add_u64 v[106:107], v[52:53], 0, v[4:5]
	v_lshlrev_b32_e32 v4, 4, v108
	v_lshlrev_b32_e32 v55, 5, v108
	v_lshlrev_b32_e32 v56, 3, v108
	v_bfe_u32 v53, v108, 1, 2
	v_and_b32_e32 v54, 16, v4
	v_lshlrev_b32_e32 v4, 10, v60
	v_and_b32_e32 v55, 0x180, v55
	v_and_b32_e32 v56, 24, v56
	v_or3_b32 v58, v55, v4, v56
	v_bitop3_b32 v4, v60, v53, 1 bitop3:0x6c
	v_lshlrev_b32_e32 v52, 7, v72
	v_lshl_add_u32 v4, v4, 5, s13
	v_add3_u32 v4, v4, v52, v54
	ds_write_b128 v4, v[34:37] offset:8192
	v_bitop3_b32 v34, v60, v53, 2 bitop3:0x36
	v_lshl_add_u32 v34, v34, 5, s13
	v_add3_u32 v109, v34, v52, v54
	ds_write_b128 v109, v[6:9] offset:9216
	ds_write_b128 v4, v[10:13] offset:10240
	ds_write_b128 v109, v[14:17] offset:11264
	ds_write_b128 v4, v[18:21] offset:12288
	ds_write_b128 v109, v[22:25] offset:13312
	ds_write_b128 v4, v[26:29] offset:14336
	ds_write_b128 v109, v[30:33] offset:15360
	global_load_dwordx4 v[6:9], v[50:51], off offset:128
	global_load_dwordx4 v[10:13], v[48:49], off offset:128
	global_load_dwordx4 v[14:17], v[46:47], off offset:128
	global_load_dwordx4 v[18:21], v[44:45], off offset:128
	global_load_dwordx4 v[22:25], v[42:43], off offset:128
	global_load_dwordx4 v[26:29], v[40:41], off offset:128
	global_load_dwordx4 v[30:33], v[38:39], off offset:128
	global_load_dwordx4 v[34:37], v[2:3], off offset:128
	v_and_b32_e32 v2, 0x60, v70
	v_or_b32_e32 v2, v2, v58
	v_add_u32_e32 v110, s13, v2
	v_bitop3_b32 v2, v70, 32, v245 bitop3:0x6c
	v_or_b32_e32 v2, v2, v58
	v_add_u32_e32 v111, s13, v2
	v_bitop3_b32 v2, v70, 64, v245 bitop3:0x6c
	s_waitcnt lgkmcnt(0)
	v_or_b32_e32 v2, v2, v58
	ds_read_b64_tr_b16 v[38:39], v110 offset:8192
	ds_read_b64_tr_b16 v[40:41], v110 offset:8704
	ds_read_b64_tr_b16 v[42:43], v110
	ds_read_b64_tr_b16 v[44:45], v110 offset:512
	v_add_u32_e32 v112, s13, v2
	v_bitop3_b32 v2, v70, v58, s63 bitop3:0xce
	ds_read_b64_tr_b16 v[50:51], v111 offset:8192
	ds_read_b64_tr_b16 v[52:53], v111 offset:8704
	ds_read_b64_tr_b16 v[46:47], v111
	ds_read_b64_tr_b16 v[48:49], v111 offset:512
	v_add_u32_e32 v113, s13, v2
	ds_read_b64_tr_b16 v[102:103], v112 offset:8192
	ds_read_b64_tr_b16 v[104:105], v112 offset:8704
	ds_read_b64_tr_b16 v[54:55], v112
	ds_read_b64_tr_b16 v[56:57], v112 offset:512
	ds_read_b64_tr_b16 v[114:115], v113 offset:8192
	ds_read_b64_tr_b16 v[116:117], v113 offset:8704
	ds_read_b64_tr_b16 v[118:119], v113
	ds_read_b64_tr_b16 v[120:121], v113 offset:512
	s_waitcnt lgkmcnt(12)
	v_mfma_f32_16x16x32_bf16 v[98:101], v[42:45], v[38:41], 0
	v_add_co_u32_e32 v2, vcc, s1, v106
	s_add_i32 s4, s18, 8
	s_waitcnt lgkmcnt(8)
	v_mfma_f32_16x16x32_bf16 v[94:97], v[46:49], v[38:41], 0
	v_addc_co_u32_e32 v3, vcc, 0, v107, vcc
	s_addk_i32 s28, 0x200
	s_waitcnt lgkmcnt(4)
	v_mfma_f32_16x16x32_bf16 v[90:93], v[54:57], v[38:41], 0
	s_addk_i32 s29, 0x400
	s_cmp_gt_i32 s18, 3
	s_mov_b32 s18, s4
	s_waitcnt lgkmcnt(0)
	v_mfma_f32_16x16x32_bf16 v[86:89], v[118:121], v[38:41], 0
	v_mfma_f32_16x16x32_bf16 v[74:77], v[42:45], v[50:53], 0
	v_mfma_f32_16x16x32_bf16 v[78:81], v[46:49], v[50:53], 0
	v_mfma_f32_16x16x32_bf16 v[82:85], v[54:57], v[50:53], 0
	v_mfma_f32_16x16x32_bf16 v[70:73], v[118:121], v[50:53], 0
	v_mfma_f32_16x16x32_bf16 v[66:69], v[42:45], v[102:105], 0
	v_mfma_f32_16x16x32_bf16 v[62:65], v[46:49], v[102:105], 0
	v_mfma_f32_16x16x32_bf16 v[58:61], v[54:57], v[102:105], 0
	v_mfma_f32_16x16x32_bf16 v[38:41], v[118:121], v[102:105], 0
	v_mfma_f32_16x16x32_bf16 v[42:45], v[42:45], v[114:117], 0
	v_mfma_f32_16x16x32_bf16 v[46:49], v[46:49], v[114:117], 0
	v_mfma_f32_16x16x32_bf16 v[50:53], v[54:57], v[114:117], 0
	v_mfma_f32_16x16x32_bf16 v[54:57], v[118:121], v[114:117], 0
	ds_read_b64_tr_b16 v[102:103], v110 offset:12288
	ds_read_b64_tr_b16 v[104:105], v110 offset:12800
	ds_read_b64_tr_b16 v[114:115], v110 offset:4096
	ds_read_b64_tr_b16 v[116:117], v110 offset:4608
	ds_read_b64_tr_b16 v[118:119], v111 offset:12288
	ds_read_b64_tr_b16 v[120:121], v111 offset:12800
	ds_read_b64_tr_b16 v[122:123], v111 offset:4096
	ds_read_b64_tr_b16 v[124:125], v111 offset:4608
	ds_read_b64_tr_b16 v[126:127], v112 offset:12288
	ds_read_b64_tr_b16 v[128:129], v112 offset:12800
	ds_read_b64_tr_b16 v[130:131], v112 offset:4096
	ds_read_b64_tr_b16 v[132:133], v112 offset:4608
	ds_read_b64_tr_b16 v[134:135], v113 offset:12288
	ds_read_b64_tr_b16 v[136:137], v113 offset:12800
	ds_read_b64_tr_b16 v[138:139], v113 offset:4096
	ds_read_b64_tr_b16 v[140:141], v113 offset:4608
	s_waitcnt lgkmcnt(12)
	v_mfma_f32_16x16x32_bf16 v[98:101], v[114:117], v[102:105], v[98:101]
	s_waitcnt lgkmcnt(8)
	v_mfma_f32_16x16x32_bf16 v[94:97], v[122:125], v[102:105], v[94:97]
	s_waitcnt lgkmcnt(4)
	v_mfma_f32_16x16x32_bf16 v[90:93], v[130:133], v[102:105], v[90:93]
	v_mfma_f32_16x16x32_bf16 v[74:77], v[114:117], v[118:121], v[74:77]
	s_waitcnt lgkmcnt(0)
	v_mfma_f32_16x16x32_bf16 v[86:89], v[138:141], v[102:105], v[86:89]
	s_nop 0
	global_store_dwordx4 v[106:107], v[98:101], off
	s_nop 0
	global_store_dwordx4 v[106:107], v[94:97], off offset:64
	s_nop 0
	global_store_dwordx4 v[106:107], v[90:93], off offset:128
	s_nop 1
	global_store_dwordx4 v[106:107], v[86:89], off offset:192
	v_mfma_f32_16x16x32_bf16 v[78:81], v[122:125], v[118:121], v[78:81]
	s_nop 0
	v_add_co_u32_e32 v86, vcc, s75, v106
	v_mfma_f32_16x16x32_bf16 v[82:85], v[130:133], v[118:121], v[82:85]
	s_nop 0
	v_addc_co_u32_e32 v87, vcc, 0, v107, vcc
	v_mfma_f32_16x16x32_bf16 v[70:73], v[138:141], v[118:121], v[70:73]
	v_mfma_f32_16x16x32_bf16 v[38:41], v[138:141], v[126:129], v[38:41]
	v_mfma_f32_16x16x32_bf16 v[66:69], v[114:117], v[126:129], v[66:69]
	v_mfma_f32_16x16x32_bf16 v[62:65], v[122:125], v[126:129], v[62:65]
	v_mfma_f32_16x16x32_bf16 v[58:61], v[130:133], v[126:129], v[58:61]
	global_store_dwordx4 v[86:87], v[74:77], off offset:-4096
	global_store_dwordx4 v[2:3], v[78:81], off offset:64
	global_store_dwordx4 v[2:3], v[82:85], off offset:128
	s_nop 0
	global_store_dwordx4 v[2:3], v[70:73], off offset:192
	s_nop 0
	global_store_dwordx4 v[86:87], v[66:69], off
	global_store_dwordx4 v[86:87], v[62:65], off offset:64
	global_store_dwordx4 v[86:87], v[58:61], off offset:128
	global_store_dwordx4 v[86:87], v[38:41], off offset:192
	v_mfma_f32_16x16x32_bf16 v[42:45], v[114:117], v[134:137], v[42:45]
	s_nop 0
	v_add_co_u32_e32 v38, vcc, s74, v106
	v_mfma_f32_16x16x32_bf16 v[46:49], v[122:125], v[134:137], v[46:49]
	s_nop 0
	v_addc_co_u32_e32 v39, vcc, 0, v107, vcc
	v_add_co_u32_e32 v2, vcc, s79, v106
	v_mfma_f32_16x16x32_bf16 v[50:53], v[130:133], v[134:137], v[50:53]
	s_nop 0
	v_addc_co_u32_e32 v3, vcc, 0, v107, vcc
	v_mfma_f32_16x16x32_bf16 v[54:57], v[138:141], v[134:137], v[54:57]
	global_store_dwordx4 v[2:3], v[42:45], off offset:-4096
	global_store_dwordx4 v[38:39], v[46:49], off offset:64
	s_nop 2
	global_store_dwordx4 v[38:39], v[50:53], off offset:128
	s_nop 1
	global_store_dwordx4 v[38:39], v[54:57], off offset:192
	s_waitcnt lgkmcnt(0)
	s_waitcnt vmcnt(16)
	ds_write_b128 v4, v[34:37] offset:8192
	ds_write_b128 v109, v[30:33] offset:9216
	ds_write_b128 v4, v[26:29] offset:10240
	ds_write_b128 v109, v[22:25] offset:11264
	ds_write_b128 v4, v[18:21] offset:12288
	ds_write_b128 v109, v[14:17] offset:13312
	ds_write_b128 v4, v[10:13] offset:14336
	ds_write_b128 v109, v[6:9] offset:15360
	s_waitcnt lgkmcnt(0)
	ds_read_b64_tr_b16 v[6:7], v110 offset:8192
	ds_read_b64_tr_b16 v[8:9], v110 offset:8704
	ds_read_b64_tr_b16 v[22:23], v110
	ds_read_b64_tr_b16 v[24:25], v110 offset:512
	ds_read_b64_tr_b16 v[10:11], v111 offset:8192
	ds_read_b64_tr_b16 v[12:13], v111 offset:8704
	ds_read_b64_tr_b16 v[26:27], v111
	ds_read_b64_tr_b16 v[28:29], v111 offset:512
	ds_read_b64_tr_b16 v[18:19], v112 offset:8192
	ds_read_b64_tr_b16 v[20:21], v112 offset:8704
	ds_read_b64_tr_b16 v[30:31], v112
	ds_read_b64_tr_b16 v[32:33], v112 offset:512
	ds_read_b64_tr_b16 v[34:35], v113 offset:8192
	ds_read_b64_tr_b16 v[36:37], v113 offset:8704
	ds_read_b64_tr_b16 v[70:71], v113
	ds_read_b64_tr_b16 v[72:73], v113 offset:512
	s_waitcnt lgkmcnt(12)
	v_mfma_f32_16x16x32_bf16 v[66:69], v[22:25], v[6:9], 0
	s_waitcnt lgkmcnt(8)
	v_mfma_f32_16x16x32_bf16 v[62:65], v[26:29], v[6:9], 0
	s_waitcnt lgkmcnt(4)
	v_mfma_f32_16x16x32_bf16 v[58:61], v[30:33], v[6:9], 0
	s_waitcnt lgkmcnt(0)
	v_mfma_f32_16x16x32_bf16 v[54:57], v[70:73], v[6:9], 0
	v_mfma_f32_16x16x32_bf16 v[42:45], v[22:25], v[10:13], 0
	v_mfma_f32_16x16x32_bf16 v[46:49], v[26:29], v[10:13], 0
	v_mfma_f32_16x16x32_bf16 v[50:53], v[30:33], v[10:13], 0
	v_mfma_f32_16x16x32_bf16 v[38:41], v[70:73], v[10:13], 0
	v_mfma_f32_16x16x32_bf16 v[6:9], v[22:25], v[18:21], 0
	v_mfma_f32_16x16x32_bf16 v[10:13], v[26:29], v[18:21], 0
	v_mfma_f32_16x16x32_bf16 v[14:17], v[30:33], v[18:21], 0
	v_mfma_f32_16x16x32_bf16 v[18:21], v[70:73], v[18:21], 0
	v_mfma_f32_16x16x32_bf16 v[22:25], v[22:25], v[34:37], 0
	v_mfma_f32_16x16x32_bf16 v[26:29], v[26:29], v[34:37], 0
	v_mfma_f32_16x16x32_bf16 v[30:33], v[30:33], v[34:37], 0
	v_mfma_f32_16x16x32_bf16 v[34:37], v[70:73], v[34:37], 0
	ds_read_b64_tr_b16 v[70:71], v110 offset:12288
	ds_read_b64_tr_b16 v[72:73], v110 offset:12800
	ds_read_b64_tr_b16 v[74:75], v110 offset:4096
	ds_read_b64_tr_b16 v[76:77], v110 offset:4608
	ds_read_b64_tr_b16 v[78:79], v111 offset:12288
	ds_read_b64_tr_b16 v[80:81], v111 offset:12800
	ds_read_b64_tr_b16 v[82:83], v111 offset:4096
	ds_read_b64_tr_b16 v[84:85], v111 offset:4608
	ds_read_b64_tr_b16 v[86:87], v112 offset:12288
	ds_read_b64_tr_b16 v[88:89], v112 offset:12800
	ds_read_b64_tr_b16 v[90:91], v112 offset:4096
	ds_read_b64_tr_b16 v[92:93], v112 offset:4608
	ds_read_b64_tr_b16 v[94:95], v113 offset:12288
	ds_read_b64_tr_b16 v[96:97], v113 offset:12800
	ds_read_b64_tr_b16 v[98:99], v113 offset:4096
	ds_read_b64_tr_b16 v[100:101], v113 offset:4608
	s_waitcnt lgkmcnt(12)
	v_mfma_f32_16x16x32_bf16 v[66:69], v[74:77], v[70:73], v[66:69]
	s_waitcnt lgkmcnt(8)
	v_mfma_f32_16x16x32_bf16 v[62:65], v[82:85], v[70:73], v[62:65]
	s_waitcnt lgkmcnt(4)
	v_mfma_f32_16x16x32_bf16 v[58:61], v[90:93], v[70:73], v[58:61]
	s_waitcnt lgkmcnt(0)
	v_mfma_f32_16x16x32_bf16 v[54:57], v[98:101], v[70:73], v[54:57]
	s_nop 1
	global_store_dwordx4 v[2:3], v[66:69], off
	s_nop 0
	global_store_dwordx4 v[2:3], v[62:65], off offset:64
	s_nop 0
	global_store_dwordx4 v[2:3], v[58:61], off offset:128
	s_nop 0
	global_store_dwordx4 v[2:3], v[54:57], off offset:192
	v_add_co_u32_e32 v2, vcc, s40, v106
	v_mfma_f32_16x16x32_bf16 v[42:45], v[74:77], v[78:81], v[42:45]
	s_nop 0
	v_addc_co_u32_e32 v3, vcc, 0, v107, vcc
	v_add_co_u32_e32 v54, vcc, s62, v106
	v_mfma_f32_16x16x32_bf16 v[46:49], v[82:85], v[78:81], v[46:49]
	s_nop 0
	v_addc_co_u32_e32 v55, vcc, 0, v107, vcc
	v_mfma_f32_16x16x32_bf16 v[50:53], v[90:93], v[78:81], v[50:53]
	v_mfma_f32_16x16x32_bf16 v[22:25], v[74:77], v[94:97], v[22:25]
	v_mfma_f32_16x16x32_bf16 v[38:41], v[98:101], v[78:81], v[38:41]
	v_mfma_f32_16x16x32_bf16 v[26:29], v[82:85], v[94:97], v[26:29]
	v_mfma_f32_16x16x32_bf16 v[6:9], v[74:77], v[86:89], v[6:9]
	v_mfma_f32_16x16x32_bf16 v[10:13], v[82:85], v[86:89], v[10:13]
	v_mfma_f32_16x16x32_bf16 v[14:17], v[90:93], v[86:89], v[14:17]
	v_mfma_f32_16x16x32_bf16 v[18:21], v[98:101], v[86:89], v[18:21]
	global_store_dwordx4 v[54:55], v[42:45], off offset:-4096
	global_store_dwordx4 v[2:3], v[46:49], off offset:64
	global_store_dwordx4 v[2:3], v[50:53], off offset:128
	global_store_dwordx4 v[2:3], v[38:41], off offset:192
	s_nop 0
	global_store_dwordx4 v[54:55], v[6:9], off
	global_store_dwordx4 v[54:55], v[10:13], off offset:64
	global_store_dwordx4 v[54:55], v[14:17], off offset:128
	global_store_dwordx4 v[54:55], v[18:21], off offset:192
	v_add_co_u32_e32 v2, vcc, 0x7000, v106
	v_mfma_f32_16x16x32_bf16 v[30:33], v[90:93], v[94:97], v[30:33]
	s_nop 0
	v_addc_co_u32_e32 v3, vcc, 0, v107, vcc
	v_mfma_f32_16x16x32_bf16 v[34:37], v[98:101], v[94:97], v[34:37]
	global_store_dwordx4 v[2:3], v[22:25], off
	global_store_dwordx4 v[2:3], v[26:29], off offset:64
	s_nop 2
	global_store_dwordx4 v[2:3], v[30:33], off offset:128
	s_nop 1
	global_store_dwordx4 v[2:3], v[34:37], off offset:192
	s_waitcnt lgkmcnt(0)
	s_cbranch_scc0 .LBB0_284
	s_branch .LBB0_281
